# speedup vs baseline: 1.0007x; 1.0007x over previous
.Lglds2_2829:
	ds_read_b128 v[152:155], v112 offset:16384
	ds_read_b128 v[156:159], v112 offset:18432
	ds_read_b128 v[160:163], v110
	ds_read_b128 v[164:167], v110 offset:2048
	ds_read_b128 v[168:171], v112 offset:20480
	ds_read_b128 v[172:175], v113 offset:16384
	ds_read_b128 v[208:211], v110 offset:4096
	ds_read_b128 v[212:215], v111
	ds_read_b128 v[216:219], v116 offset:16384
	ds_read_b128 v[220:223], v116 offset:18432
	ds_read_b128 v[224:227], v114
	ds_read_b128 v[228:231], v114 offset:2048
	ds_read_b128 v[232:235], v116 offset:20480
	ds_read_b128 v[236:239], v117 offset:16384
	ds_read_b128 v[240:243], v114 offset:4096
	ds_read_b128 v[244:247], v115
	s_setprio 1
	s_waitcnt lgkmcnt(13)
	v_mfma_f32_16x16x32_bf16 v[94:97], v[152:155], v[160:163], v[94:97]
	v_mfma_f32_16x16x32_bf16 v[90:93], v[156:159], v[160:163], v[90:93]
	s_waitcnt lgkmcnt(11)
	v_mfma_f32_16x16x32_bf16 v[86:89], v[168:171], v[160:163], v[86:89]
	s_waitcnt lgkmcnt(10)
	v_mfma_f32_16x16x32_bf16 v[82:85], v[172:175], v[160:163], v[82:85]
	v_mfma_f32_16x16x32_bf16 v[78:81], v[152:155], v[164:167], v[78:81]
	v_mfma_f32_16x16x32_bf16 v[62:65], v[156:159], v[164:167], v[62:65]
	v_mfma_f32_16x16x32_bf16 v[46:49], v[168:171], v[164:167], v[46:49]
	v_mfma_f32_16x16x32_bf16 v[26:29], v[172:175], v[164:167], v[26:29]
	s_waitcnt lgkmcnt(9)
	v_mfma_f32_16x16x32_bf16 v[38:41], v[152:155], v[208:211], v[38:41]
	v_mfma_f32_16x16x32_bf16 v[30:33], v[156:159], v[208:211], v[30:33]
	v_mfma_f32_16x16x32_bf16 v[22:25], v[168:171], v[208:211], v[22:25]
	v_mfma_f32_16x16x32_bf16 v[18:21], v[172:175], v[208:211], v[18:21]
	s_waitcnt lgkmcnt(8)
	v_mfma_f32_16x16x32_bf16 v[14:17], v[152:155], v[212:215], v[14:17]
	v_mfma_f32_16x16x32_bf16 v[10:13], v[156:159], v[212:215], v[10:13]
	v_mfma_f32_16x16x32_bf16 v[6:9], v[168:171], v[212:215], v[6:9]
	v_mfma_f32_16x16x32_bf16 v[2:5], v[172:175], v[212:215], v[2:5]
	s_setprio 0
	s_waitcnt lgkmcnt(0)
	s_waitcnt vmcnt(0)
	s_barrier
	s_add_i32 s0, s5, 0x80
	s_min_u32 s0, s0, 0x3c0
	s_lshl_b32 s0, s0, 1
	s_setprio 1
	v_mfma_f32_16x16x32_bf16 v[94:97], v[216:219], v[224:227], v[94:97]
	s_add_u32 m0, s6, 0x0
	v_lshl_add_u64 v[204:205], v[188:189], 0, s[0:1]
	global_load_lds_dwordx4 v[204:205], off
	v_mfma_f32_16x16x32_bf16 v[90:93], v[220:223], v[224:227], v[90:93]
	v_mfma_f32_16x16x32_bf16 v[86:89], v[232:235], v[224:227], v[86:89]
	s_add_u32 m0, s6, 0x1000
	v_lshl_add_u64 v[206:207], v[190:191], 0, s[0:1]
	global_load_lds_dwordx4 v[206:207], off
	v_mfma_f32_16x16x32_bf16 v[82:85], v[236:239], v[224:227], v[82:85]
	v_mfma_f32_16x16x32_bf16 v[78:81], v[216:219], v[228:231], v[78:81]
	s_add_u32 m0, s6, 0x2000
	v_lshl_add_u64 v[204:205], v[192:193], 0, s[0:1]
	global_load_lds_dwordx4 v[204:205], off
	v_mfma_f32_16x16x32_bf16 v[62:65], v[220:223], v[228:231], v[62:65]
	v_mfma_f32_16x16x32_bf16 v[46:49], v[232:235], v[228:231], v[46:49]
	s_add_u32 m0, s6, 0x3000
	v_lshl_add_u64 v[206:207], v[194:195], 0, s[0:1]
	global_load_lds_dwordx4 v[206:207], off
	v_mfma_f32_16x16x32_bf16 v[26:29], v[236:239], v[228:231], v[26:29]
	v_mfma_f32_16x16x32_bf16 v[38:41], v[216:219], v[240:243], v[38:41]
	s_add_u32 m0, s6, 0x4000
	v_lshl_add_u64 v[204:205], v[196:197], 0, s[0:1]
	global_load_lds_dwordx4 v[204:205], off
	v_mfma_f32_16x16x32_bf16 v[30:33], v[220:223], v[240:243], v[30:33]
	v_mfma_f32_16x16x32_bf16 v[22:25], v[232:235], v[240:243], v[22:25]
	s_add_u32 m0, s6, 0x5000
	v_lshl_add_u64 v[206:207], v[198:199], 0, s[0:1]
	global_load_lds_dwordx4 v[206:207], off
	v_mfma_f32_16x16x32_bf16 v[18:21], v[236:239], v[240:243], v[18:21]
	v_mfma_f32_16x16x32_bf16 v[14:17], v[216:219], v[244:247], v[14:17]
	s_add_u32 m0, s6, 0x6000
	v_lshl_add_u64 v[204:205], v[200:201], 0, s[0:1]
	global_load_lds_dwordx4 v[204:205], off
	v_mfma_f32_16x16x32_bf16 v[10:13], v[220:223], v[244:247], v[10:13]
	v_mfma_f32_16x16x32_bf16 v[6:9], v[232:235], v[244:247], v[6:9]
	s_add_u32 m0, s6, 0x7000
	v_lshl_add_u64 v[206:207], v[202:203], 0, s[0:1]
	global_load_lds_dwordx4 v[206:207], off
	v_mfma_f32_16x16x32_bf16 v[2:5], v[236:239], v[244:247], v[2:5]
	s_setprio 0
	ds_read_b128 v[152:155], v112 offset:49152
	ds_read_b128 v[156:159], v112 offset:51200
	ds_read_b128 v[160:163], v110 offset:32768
	ds_read_b128 v[164:167], v110 offset:34816
	ds_read_b128 v[168:171], v112 offset:53248
	ds_read_b128 v[172:175], v113 offset:49152
	ds_read_b128 v[208:211], v110 offset:36864
	ds_read_b128 v[212:215], v111 offset:32768
	ds_read_b128 v[216:219], v116 offset:49152
	ds_read_b128 v[220:223], v116 offset:51200
	ds_read_b128 v[224:227], v114 offset:32768
	ds_read_b128 v[228:231], v114 offset:34816
	ds_read_b128 v[232:235], v116 offset:53248
	ds_read_b128 v[236:239], v117 offset:49152
	ds_read_b128 v[240:243], v114 offset:36864
	ds_read_b128 v[244:247], v115 offset:32768
	s_setprio 1
	s_waitcnt lgkmcnt(13)
	v_mfma_f32_16x16x32_bf16 v[94:97], v[152:155], v[160:163], v[94:97]
	v_mfma_f32_16x16x32_bf16 v[90:93], v[156:159], v[160:163], v[90:93]
	s_waitcnt lgkmcnt(11)
	v_mfma_f32_16x16x32_bf16 v[86:89], v[168:171], v[160:163], v[86:89]
	s_waitcnt lgkmcnt(10)
	v_mfma_f32_16x16x32_bf16 v[82:85], v[172:175], v[160:163], v[82:85]
	v_mfma_f32_16x16x32_bf16 v[78:81], v[152:155], v[164:167], v[78:81]
	v_mfma_f32_16x16x32_bf16 v[62:65], v[156:159], v[164:167], v[62:65]
	v_mfma_f32_16x16x32_bf16 v[46:49], v[168:171], v[164:167], v[46:49]
	v_mfma_f32_16x16x32_bf16 v[26:29], v[172:175], v[164:167], v[26:29]
	s_waitcnt lgkmcnt(9)
	v_mfma_f32_16x16x32_bf16 v[38:41], v[152:155], v[208:211], v[38:41]
	v_mfma_f32_16x16x32_bf16 v[30:33], v[156:159], v[208:211], v[30:33]
	v_mfma_f32_16x16x32_bf16 v[22:25], v[168:171], v[208:211], v[22:25]
	v_mfma_f32_16x16x32_bf16 v[18:21], v[172:175], v[208:211], v[18:21]
	s_waitcnt lgkmcnt(8)
	v_mfma_f32_16x16x32_bf16 v[14:17], v[152:155], v[212:215], v[14:17]
	v_mfma_f32_16x16x32_bf16 v[10:13], v[156:159], v[212:215], v[10:13]
	v_mfma_f32_16x16x32_bf16 v[6:9], v[168:171], v[212:215], v[6:9]
	v_mfma_f32_16x16x32_bf16 v[2:5], v[172:175], v[212:215], v[2:5]
	s_setprio 0
	s_waitcnt lgkmcnt(0)
	s_waitcnt vmcnt(0)
	s_barrier
	s_add_i32 s0, s5, 0xc0
	s_min_u32 s0, s0, 0x3c0
	s_lshl_b32 s0, s0, 1
	s_setprio 1
	v_mfma_f32_16x16x32_bf16 v[94:97], v[216:219], v[224:227], v[94:97]
	s_add_u32 m0, s6, 0x8000
	v_lshl_add_u64 v[204:205], v[188:189], 0, s[0:1]
	global_load_lds_dwordx4 v[204:205], off
	v_mfma_f32_16x16x32_bf16 v[90:93], v[220:223], v[224:227], v[90:93]
	v_mfma_f32_16x16x32_bf16 v[86:89], v[232:235], v[224:227], v[86:89]
	s_add_u32 m0, s6, 0x9000
	v_lshl_add_u64 v[206:207], v[190:191], 0, s[0:1]
	global_load_lds_dwordx4 v[206:207], off
	v_mfma_f32_16x16x32_bf16 v[82:85], v[236:239], v[224:227], v[82:85]
	v_mfma_f32_16x16x32_bf16 v[78:81], v[216:219], v[228:231], v[78:81]
	s_add_u32 m0, s6, 0xa000
	v_lshl_add_u64 v[204:205], v[192:193], 0, s[0:1]
	global_load_lds_dwordx4 v[204:205], off
	v_mfma_f32_16x16x32_bf16 v[62:65], v[220:223], v[228:231], v[62:65]
	v_mfma_f32_16x16x32_bf16 v[46:49], v[232:235], v[228:231], v[46:49]
	s_add_u32 m0, s6, 0xb000
	v_lshl_add_u64 v[206:207], v[194:195], 0, s[0:1]
	global_load_lds_dwordx4 v[206:207], off
	v_mfma_f32_16x16x32_bf16 v[26:29], v[236:239], v[228:231], v[26:29]
	v_mfma_f32_16x16x32_bf16 v[38:41], v[216:219], v[240:243], v[38:41]
	s_add_u32 m0, s6, 0xc000
	v_lshl_add_u64 v[204:205], v[196:197], 0, s[0:1]
	global_load_lds_dwordx4 v[204:205], off
	v_mfma_f32_16x16x32_bf16 v[30:33], v[220:223], v[240:243], v[30:33]
	v_mfma_f32_16x16x32_bf16 v[22:25], v[232:235], v[240:243], v[22:25]
	s_add_u32 m0, s6, 0xd000
	v_lshl_add_u64 v[206:207], v[198:199], 0, s[0:1]
	global_load_lds_dwordx4 v[206:207], off
	v_mfma_f32_16x16x32_bf16 v[18:21], v[236:239], v[240:243], v[18:21]
	v_mfma_f32_16x16x32_bf16 v[14:17], v[216:219], v[244:247], v[14:17]
	s_add_u32 m0, s6, 0xe000
	v_lshl_add_u64 v[204:205], v[200:201], 0, s[0:1]
	global_load_lds_dwordx4 v[204:205], off
	v_mfma_f32_16x16x32_bf16 v[10:13], v[220:223], v[244:247], v[10:13]
	v_mfma_f32_16x16x32_bf16 v[6:9], v[232:235], v[244:247], v[6:9]
	s_add_u32 m0, s6, 0xf000
	v_lshl_add_u64 v[206:207], v[202:203], 0, s[0:1]
	global_load_lds_dwordx4 v[206:207], off
	v_mfma_f32_16x16x32_bf16 v[2:5], v[236:239], v[244:247], v[2:5]
	s_setprio 0
	s_add_i32 s5, s5, 0x80
	s_add_i32 s4, s4, 2
	s_cmp_gt_u32 s4, 13
	s_cbranch_scc0 .Lglds2_2829
	ds_read_b128 v[152:155], v112 offset:16384
	ds_read_b128 v[156:159], v112 offset:18432
	ds_read_b128 v[160:163], v110
	ds_read_b128 v[164:167], v110 offset:2048
	ds_read_b128 v[168:171], v112 offset:20480
	ds_read_b128 v[172:175], v113 offset:16384
	ds_read_b128 v[208:211], v110 offset:4096
	ds_read_b128 v[212:215], v111
	ds_read_b128 v[216:219], v116 offset:16384
	ds_read_b128 v[220:223], v116 offset:18432
	ds_read_b128 v[224:227], v114
	ds_read_b128 v[228:231], v114 offset:2048
	ds_read_b128 v[232:235], v116 offset:20480
	ds_read_b128 v[236:239], v117 offset:16384
	ds_read_b128 v[240:243], v114 offset:4096
	ds_read_b128 v[244:247], v115
	s_setprio 1
	s_waitcnt lgkmcnt(13)
	v_mfma_f32_16x16x32_bf16 v[94:97], v[152:155], v[160:163], v[94:97]
	v_mfma_f32_16x16x32_bf16 v[90:93], v[156:159], v[160:163], v[90:93]
	s_waitcnt lgkmcnt(11)
	v_mfma_f32_16x16x32_bf16 v[86:89], v[168:171], v[160:163], v[86:89]
	s_waitcnt lgkmcnt(10)
	v_mfma_f32_16x16x32_bf16 v[82:85], v[172:175], v[160:163], v[82:85]
	v_mfma_f32_16x16x32_bf16 v[78:81], v[152:155], v[164:167], v[78:81]
	v_mfma_f32_16x16x32_bf16 v[62:65], v[156:159], v[164:167], v[62:65]
	v_mfma_f32_16x16x32_bf16 v[46:49], v[168:171], v[164:167], v[46:49]
	v_mfma_f32_16x16x32_bf16 v[26:29], v[172:175], v[164:167], v[26:29]
	s_waitcnt lgkmcnt(9)
	v_mfma_f32_16x16x32_bf16 v[38:41], v[152:155], v[208:211], v[38:41]
	v_mfma_f32_16x16x32_bf16 v[30:33], v[156:159], v[208:211], v[30:33]
	v_mfma_f32_16x16x32_bf16 v[22:25], v[168:171], v[208:211], v[22:25]
	v_mfma_f32_16x16x32_bf16 v[18:21], v[172:175], v[208:211], v[18:21]
	s_waitcnt lgkmcnt(8)
	v_mfma_f32_16x16x32_bf16 v[14:17], v[152:155], v[212:215], v[14:17]
	v_mfma_f32_16x16x32_bf16 v[10:13], v[156:159], v[212:215], v[10:13]
	v_mfma_f32_16x16x32_bf16 v[6:9], v[168:171], v[212:215], v[6:9]
	v_mfma_f32_16x16x32_bf16 v[2:5], v[172:175], v[212:215], v[2:5]
	s_setprio 0
	s_waitcnt lgkmcnt(0)
	s_waitcnt vmcnt(0)
	s_barrier
	s_setprio 1
	v_mfma_f32_16x16x32_bf16 v[94:97], v[216:219], v[224:227], v[94:97]
	v_mfma_f32_16x16x32_bf16 v[90:93], v[220:223], v[224:227], v[90:93]
	v_mfma_f32_16x16x32_bf16 v[86:89], v[232:235], v[224:227], v[86:89]
	v_mfma_f32_16x16x32_bf16 v[82:85], v[236:239], v[224:227], v[82:85]
	v_mfma_f32_16x16x32_bf16 v[78:81], v[216:219], v[228:231], v[78:81]
	v_mfma_f32_16x16x32_bf16 v[62:65], v[220:223], v[228:231], v[62:65]
	v_mfma_f32_16x16x32_bf16 v[46:49], v[232:235], v[228:231], v[46:49]
	v_mfma_f32_16x16x32_bf16 v[26:29], v[236:239], v[228:231], v[26:29]
	v_mfma_f32_16x16x32_bf16 v[38:41], v[216:219], v[240:243], v[38:41]
	v_mfma_f32_16x16x32_bf16 v[30:33], v[220:223], v[240:243], v[30:33]
	v_mfma_f32_16x16x32_bf16 v[22:25], v[232:235], v[240:243], v[22:25]
	v_mfma_f32_16x16x32_bf16 v[18:21], v[236:239], v[240:243], v[18:21]
	v_mfma_f32_16x16x32_bf16 v[14:17], v[216:219], v[244:247], v[14:17]
	v_mfma_f32_16x16x32_bf16 v[10:13], v[220:223], v[244:247], v[10:13]
	v_mfma_f32_16x16x32_bf16 v[6:9], v[232:235], v[244:247], v[6:9]
	v_mfma_f32_16x16x32_bf16 v[2:5], v[236:239], v[244:247], v[2:5]
	s_setprio 0
	ds_read_b128 v[152:155], v112 offset:49152
	ds_read_b128 v[156:159], v112 offset:51200
	ds_read_b128 v[160:163], v110 offset:32768
	ds_read_b128 v[164:167], v110 offset:34816
	ds_read_b128 v[168:171], v112 offset:53248
	ds_read_b128 v[172:175], v113 offset:49152
	ds_read_b128 v[208:211], v110 offset:36864
	ds_read_b128 v[212:215], v111 offset:32768
	ds_read_b128 v[216:219], v116 offset:49152
	ds_read_b128 v[220:223], v116 offset:51200
	ds_read_b128 v[224:227], v114 offset:32768
	ds_read_b128 v[228:231], v114 offset:34816
	ds_read_b128 v[232:235], v116 offset:53248
	ds_read_b128 v[236:239], v117 offset:49152
	ds_read_b128 v[240:243], v114 offset:36864
	ds_read_b128 v[244:247], v115 offset:32768
	s_setprio 1
	s_waitcnt lgkmcnt(13)
	v_mfma_f32_16x16x32_bf16 v[94:97], v[152:155], v[160:163], v[94:97]
	v_mfma_f32_16x16x32_bf16 v[90:93], v[156:159], v[160:163], v[90:93]
	s_waitcnt lgkmcnt(11)
	v_mfma_f32_16x16x32_bf16 v[86:89], v[168:171], v[160:163], v[86:89]
	s_waitcnt lgkmcnt(10)
	v_mfma_f32_16x16x32_bf16 v[82:85], v[172:175], v[160:163], v[82:85]
	v_mfma_f32_16x16x32_bf16 v[78:81], v[152:155], v[164:167], v[78:81]
	v_mfma_f32_16x16x32_bf16 v[62:65], v[156:159], v[164:167], v[62:65]
	v_mfma_f32_16x16x32_bf16 v[46:49], v[168:171], v[164:167], v[46:49]
	v_mfma_f32_16x16x32_bf16 v[26:29], v[172:175], v[164:167], v[26:29]
	s_waitcnt lgkmcnt(9)
	v_mfma_f32_16x16x32_bf16 v[38:41], v[152:155], v[208:211], v[38:41]
	v_mfma_f32_16x16x32_bf16 v[30:33], v[156:159], v[208:211], v[30:33]
	v_mfma_f32_16x16x32_bf16 v[22:25], v[168:171], v[208:211], v[22:25]
	v_mfma_f32_16x16x32_bf16 v[18:21], v[172:175], v[208:211], v[18:21]
	s_waitcnt lgkmcnt(8)
	v_mfma_f32_16x16x32_bf16 v[14:17], v[152:155], v[212:215], v[14:17]
	v_mfma_f32_16x16x32_bf16 v[10:13], v[156:159], v[212:215], v[10:13]
	v_mfma_f32_16x16x32_bf16 v[6:9], v[168:171], v[212:215], v[6:9]
	v_mfma_f32_16x16x32_bf16 v[2:5], v[172:175], v[212:215], v[2:5]
	s_setprio 0
	s_waitcnt lgkmcnt(0)
	s_barrier
	s_setprio 1
	v_mfma_f32_16x16x32_bf16 v[94:97], v[216:219], v[224:227], v[94:97]
	v_mfma_f32_16x16x32_bf16 v[90:93], v[220:223], v[224:227], v[90:93]
	v_mfma_f32_16x16x32_bf16 v[86:89], v[232:235], v[224:227], v[86:89]
	v_mfma_f32_16x16x32_bf16 v[82:85], v[236:239], v[224:227], v[82:85]
	v_mfma_f32_16x16x32_bf16 v[78:81], v[216:219], v[228:231], v[78:81]
	v_mfma_f32_16x16x32_bf16 v[62:65], v[220:223], v[228:231], v[62:65]
	v_mfma_f32_16x16x32_bf16 v[46:49], v[232:235], v[228:231], v[46:49]
	v_mfma_f32_16x16x32_bf16 v[26:29], v[236:239], v[228:231], v[26:29]
	v_mfma_f32_16x16x32_bf16 v[38:41], v[216:219], v[240:243], v[38:41]
	v_mfma_f32_16x16x32_bf16 v[30:33], v[220:223], v[240:243], v[30:33]
	v_mfma_f32_16x16x32_bf16 v[22:25], v[232:235], v[240:243], v[22:25]
	v_mfma_f32_16x16x32_bf16 v[18:21], v[236:239], v[240:243], v[18:21]
	v_mfma_f32_16x16x32_bf16 v[14:17], v[216:219], v[244:247], v[14:17]
	v_mfma_f32_16x16x32_bf16 v[10:13], v[220:223], v[244:247], v[10:13]
	v_mfma_f32_16x16x32_bf16 v[6:9], v[232:235], v[244:247], v[6:9]
	v_mfma_f32_16x16x32_bf16 v[2:5], v[236:239], v[244:247], v[2:5]
	s_setprio 0
	s_waitcnt vmcnt(0)
	v_readlane_b32 s36, v254, 40
	s_waitcnt vmcnt(7)
	v_or_b32_e32 v35, s2, v118
	v_readlane_b32 s48, v254, 52
	v_readlane_b32 s49, v254, 53
	v_or_b32_e32 v34, s3, v119
	s_waitcnt vmcnt(6)
	v_add_u32_e32 v42, v35, v120
	v_mov_b64_e32 v[36:37], s[48:49]
	v_mad_i64_i32 v[36:37], s[2:3], v42, s18, v[36:37]
	v_cmp_gt_i32_e32 vcc, s19, v34
	v_ashrrev_i32_e32 v35, 31, v34
	v_readlane_b32 s37, v254, 41
	v_readlane_b32 s38, v254, 42
	v_readlane_b32 s39, v254, 43
	v_readlane_b32 s40, v254, 44
	v_readlane_b32 s41, v254, 45
	v_readlane_b32 s42, v254, 46
	v_readlane_b32 s43, v254, 47
	v_readlane_b32 s44, v254, 48
	v_readlane_b32 s45, v254, 49
	v_readlane_b32 s46, v254, 50
	v_readlane_b32 s47, v254, 51
	v_readlane_b32 s50, v254, 54
	v_readlane_b32 s51, v254, 55
	s_and_saveexec_b64 s[2:3], vcc
	s_cbranch_execnz .LBB0_205
	s_or_b64 exec, exec, s[2:3]
	v_cmp_gt_i32_e64 s[4:5], s20, v34
	s_and_saveexec_b64 s[2:3], s[4:5]
	s_cbranch_execnz .LBB0_206

.Lglds2_3547:
	ds_read_b128 v[152:155], v112 offset:16384
	ds_read_b128 v[156:159], v112 offset:18432
	ds_read_b128 v[160:163], v110
	ds_read_b128 v[164:167], v110 offset:2048
	ds_read_b128 v[168:171], v112 offset:20480
	ds_read_b128 v[172:175], v113 offset:16384
	ds_read_b128 v[208:211], v110 offset:4096
	ds_read_b128 v[212:215], v111
	ds_read_b128 v[216:219], v116 offset:16384
	ds_read_b128 v[220:223], v116 offset:18432
	ds_read_b128 v[224:227], v114
	ds_read_b128 v[228:231], v114 offset:2048
	ds_read_b128 v[232:235], v116 offset:20480
	ds_read_b128 v[236:239], v117 offset:16384
	ds_read_b128 v[240:243], v114 offset:4096
	ds_read_b128 v[244:247], v115
	s_setprio 1
	s_waitcnt lgkmcnt(13)
	v_mfma_f32_16x16x32_bf16 v[94:97], v[152:155], v[160:163], v[94:97]
	v_mfma_f32_16x16x32_bf16 v[90:93], v[156:159], v[160:163], v[90:93]
	s_waitcnt lgkmcnt(11)
	v_mfma_f32_16x16x32_bf16 v[86:89], v[168:171], v[160:163], v[86:89]
	s_waitcnt lgkmcnt(10)
	v_mfma_f32_16x16x32_bf16 v[82:85], v[172:175], v[160:163], v[82:85]
	v_mfma_f32_16x16x32_bf16 v[78:81], v[152:155], v[164:167], v[78:81]
	v_mfma_f32_16x16x32_bf16 v[54:57], v[156:159], v[164:167], v[54:57]
	v_mfma_f32_16x16x32_bf16 v[38:41], v[168:171], v[164:167], v[38:41]
	v_mfma_f32_16x16x32_bf16 v[34:37], v[172:175], v[164:167], v[34:37]
	s_waitcnt lgkmcnt(9)
	v_mfma_f32_16x16x32_bf16 v[74:77], v[152:155], v[208:211], v[74:77]
	v_mfma_f32_16x16x32_bf16 v[70:73], v[156:159], v[208:211], v[70:73]
	v_mfma_f32_16x16x32_bf16 v[66:69], v[168:171], v[208:211], v[66:69]
	v_mfma_f32_16x16x32_bf16 v[62:65], v[172:175], v[208:211], v[62:65]
	s_waitcnt lgkmcnt(8)
	v_mfma_f32_16x16x32_bf16 v[58:61], v[152:155], v[212:215], v[58:61]
	v_mfma_f32_16x16x32_bf16 v[50:53], v[156:159], v[212:215], v[50:53]
	v_mfma_f32_16x16x32_bf16 v[46:49], v[168:171], v[212:215], v[46:49]
	v_mfma_f32_16x16x32_bf16 v[42:45], v[172:175], v[212:215], v[42:45]
	s_setprio 0
	s_waitcnt lgkmcnt(0)
	s_waitcnt vmcnt(0)
	s_barrier
	s_add_i32 s0, s19, 0x80
	s_min_u32 s0, s0, 0x3c0
	s_lshl_b32 s0, s0, 1
	s_setprio 1
	v_mfma_f32_16x16x32_bf16 v[94:97], v[216:219], v[224:227], v[94:97]
	s_add_u32 m0, s20, 0x0
	v_lshl_add_u64 v[204:205], v[188:189], 0, s[0:1]
	global_load_lds_dwordx4 v[204:205], off
	v_mfma_f32_16x16x32_bf16 v[90:93], v[220:223], v[224:227], v[90:93]
	v_mfma_f32_16x16x32_bf16 v[86:89], v[232:235], v[224:227], v[86:89]
	s_add_u32 m0, s20, 0x1000
	v_lshl_add_u64 v[206:207], v[190:191], 0, s[0:1]
	global_load_lds_dwordx4 v[206:207], off
	v_mfma_f32_16x16x32_bf16 v[82:85], v[236:239], v[224:227], v[82:85]
	v_mfma_f32_16x16x32_bf16 v[78:81], v[216:219], v[228:231], v[78:81]
	s_add_u32 m0, s20, 0x2000
	v_lshl_add_u64 v[204:205], v[192:193], 0, s[0:1]
	global_load_lds_dwordx4 v[204:205], off
	v_mfma_f32_16x16x32_bf16 v[54:57], v[220:223], v[228:231], v[54:57]
	v_mfma_f32_16x16x32_bf16 v[38:41], v[232:235], v[228:231], v[38:41]
	s_add_u32 m0, s20, 0x3000
	v_lshl_add_u64 v[206:207], v[194:195], 0, s[0:1]
	global_load_lds_dwordx4 v[206:207], off
	v_mfma_f32_16x16x32_bf16 v[34:37], v[236:239], v[228:231], v[34:37]
	v_mfma_f32_16x16x32_bf16 v[74:77], v[216:219], v[240:243], v[74:77]
	s_add_u32 m0, s20, 0x4000
	v_lshl_add_u64 v[204:205], v[196:197], 0, s[0:1]
	global_load_lds_dwordx4 v[204:205], off
	v_mfma_f32_16x16x32_bf16 v[70:73], v[220:223], v[240:243], v[70:73]
	v_mfma_f32_16x16x32_bf16 v[66:69], v[232:235], v[240:243], v[66:69]
	s_add_u32 m0, s20, 0x5000
	v_lshl_add_u64 v[206:207], v[198:199], 0, s[0:1]
	global_load_lds_dwordx4 v[206:207], off
	v_mfma_f32_16x16x32_bf16 v[62:65], v[236:239], v[240:243], v[62:65]
	v_mfma_f32_16x16x32_bf16 v[58:61], v[216:219], v[244:247], v[58:61]
	s_add_u32 m0, s20, 0x6000
	v_lshl_add_u64 v[204:205], v[200:201], 0, s[0:1]
	global_load_lds_dwordx4 v[204:205], off
	v_mfma_f32_16x16x32_bf16 v[50:53], v[220:223], v[244:247], v[50:53]
	v_mfma_f32_16x16x32_bf16 v[46:49], v[232:235], v[244:247], v[46:49]
	s_add_u32 m0, s20, 0x7000
	v_lshl_add_u64 v[206:207], v[202:203], 0, s[0:1]
	global_load_lds_dwordx4 v[206:207], off
	v_mfma_f32_16x16x32_bf16 v[42:45], v[236:239], v[244:247], v[42:45]
	s_setprio 0
	ds_read_b128 v[152:155], v112 offset:49152
	ds_read_b128 v[156:159], v112 offset:51200
	ds_read_b128 v[160:163], v110 offset:32768
	ds_read_b128 v[164:167], v110 offset:34816
	ds_read_b128 v[168:171], v112 offset:53248
	ds_read_b128 v[172:175], v113 offset:49152
	ds_read_b128 v[208:211], v110 offset:36864
	ds_read_b128 v[212:215], v111 offset:32768
	ds_read_b128 v[216:219], v116 offset:49152
	ds_read_b128 v[220:223], v116 offset:51200
	ds_read_b128 v[224:227], v114 offset:32768
	ds_read_b128 v[228:231], v114 offset:34816
	ds_read_b128 v[232:235], v116 offset:53248
	ds_read_b128 v[236:239], v117 offset:49152
	ds_read_b128 v[240:243], v114 offset:36864
	ds_read_b128 v[244:247], v115 offset:32768
	s_setprio 1
	s_waitcnt lgkmcnt(13)
	v_mfma_f32_16x16x32_bf16 v[94:97], v[152:155], v[160:163], v[94:97]
	v_mfma_f32_16x16x32_bf16 v[90:93], v[156:159], v[160:163], v[90:93]
	s_waitcnt lgkmcnt(11)
	v_mfma_f32_16x16x32_bf16 v[86:89], v[168:171], v[160:163], v[86:89]
	s_waitcnt lgkmcnt(10)
	v_mfma_f32_16x16x32_bf16 v[82:85], v[172:175], v[160:163], v[82:85]
	v_mfma_f32_16x16x32_bf16 v[78:81], v[152:155], v[164:167], v[78:81]
	v_mfma_f32_16x16x32_bf16 v[54:57], v[156:159], v[164:167], v[54:57]
	v_mfma_f32_16x16x32_bf16 v[38:41], v[168:171], v[164:167], v[38:41]
	v_mfma_f32_16x16x32_bf16 v[34:37], v[172:175], v[164:167], v[34:37]
	s_waitcnt lgkmcnt(9)
	v_mfma_f32_16x16x32_bf16 v[74:77], v[152:155], v[208:211], v[74:77]
	v_mfma_f32_16x16x32_bf16 v[70:73], v[156:159], v[208:211], v[70:73]
	v_mfma_f32_16x16x32_bf16 v[66:69], v[168:171], v[208:211], v[66:69]
	v_mfma_f32_16x16x32_bf16 v[62:65], v[172:175], v[208:211], v[62:65]
	s_waitcnt lgkmcnt(8)
	v_mfma_f32_16x16x32_bf16 v[58:61], v[152:155], v[212:215], v[58:61]
	v_mfma_f32_16x16x32_bf16 v[50:53], v[156:159], v[212:215], v[50:53]
	v_mfma_f32_16x16x32_bf16 v[46:49], v[168:171], v[212:215], v[46:49]
	v_mfma_f32_16x16x32_bf16 v[42:45], v[172:175], v[212:215], v[42:45]
	s_setprio 0
	s_waitcnt lgkmcnt(0)
	s_waitcnt vmcnt(0)
	s_barrier
	s_add_i32 s0, s19, 0xc0
	s_min_u32 s0, s0, 0x3c0
	s_lshl_b32 s0, s0, 1
	s_setprio 1
	v_mfma_f32_16x16x32_bf16 v[94:97], v[216:219], v[224:227], v[94:97]
	s_add_u32 m0, s20, 0x8000
	v_lshl_add_u64 v[204:205], v[188:189], 0, s[0:1]
	global_load_lds_dwordx4 v[204:205], off
	v_mfma_f32_16x16x32_bf16 v[90:93], v[220:223], v[224:227], v[90:93]
	v_mfma_f32_16x16x32_bf16 v[86:89], v[232:235], v[224:227], v[86:89]
	s_add_u32 m0, s20, 0x9000
	v_lshl_add_u64 v[206:207], v[190:191], 0, s[0:1]
	global_load_lds_dwordx4 v[206:207], off
	v_mfma_f32_16x16x32_bf16 v[82:85], v[236:239], v[224:227], v[82:85]
	v_mfma_f32_16x16x32_bf16 v[78:81], v[216:219], v[228:231], v[78:81]
	s_add_u32 m0, s20, 0xa000
	v_lshl_add_u64 v[204:205], v[192:193], 0, s[0:1]
	global_load_lds_dwordx4 v[204:205], off
	v_mfma_f32_16x16x32_bf16 v[54:57], v[220:223], v[228:231], v[54:57]
	v_mfma_f32_16x16x32_bf16 v[38:41], v[232:235], v[228:231], v[38:41]
	s_add_u32 m0, s20, 0xb000
	v_lshl_add_u64 v[206:207], v[194:195], 0, s[0:1]
	global_load_lds_dwordx4 v[206:207], off
	v_mfma_f32_16x16x32_bf16 v[34:37], v[236:239], v[228:231], v[34:37]
	v_mfma_f32_16x16x32_bf16 v[74:77], v[216:219], v[240:243], v[74:77]
	s_add_u32 m0, s20, 0xc000
	v_lshl_add_u64 v[204:205], v[196:197], 0, s[0:1]
	global_load_lds_dwordx4 v[204:205], off
	v_mfma_f32_16x16x32_bf16 v[70:73], v[220:223], v[240:243], v[70:73]
	v_mfma_f32_16x16x32_bf16 v[66:69], v[232:235], v[240:243], v[66:69]
	s_add_u32 m0, s20, 0xd000
	v_lshl_add_u64 v[206:207], v[198:199], 0, s[0:1]
	global_load_lds_dwordx4 v[206:207], off
	v_mfma_f32_16x16x32_bf16 v[62:65], v[236:239], v[240:243], v[62:65]
	v_mfma_f32_16x16x32_bf16 v[58:61], v[216:219], v[244:247], v[58:61]
	s_add_u32 m0, s20, 0xe000
	v_lshl_add_u64 v[204:205], v[200:201], 0, s[0:1]
	global_load_lds_dwordx4 v[204:205], off
	v_mfma_f32_16x16x32_bf16 v[50:53], v[220:223], v[244:247], v[50:53]
	v_mfma_f32_16x16x32_bf16 v[46:49], v[232:235], v[244:247], v[46:49]
	s_add_u32 m0, s20, 0xf000
	v_lshl_add_u64 v[206:207], v[202:203], 0, s[0:1]
	global_load_lds_dwordx4 v[206:207], off
	v_mfma_f32_16x16x32_bf16 v[42:45], v[236:239], v[244:247], v[42:45]
	s_setprio 0
	s_add_i32 s19, s19, 0x80
	s_add_i32 s18, s18, 2
	s_cmp_lt_u32 s18, 14
	s_cbranch_scc1 .Lglds2_3547
	ds_read_b128 v[152:155], v112 offset:16384
	ds_read_b128 v[156:159], v112 offset:18432
	ds_read_b128 v[160:163], v110
	ds_read_b128 v[164:167], v110 offset:2048
	ds_read_b128 v[168:171], v112 offset:20480
	ds_read_b128 v[172:175], v113 offset:16384
	ds_read_b128 v[208:211], v110 offset:4096
	ds_read_b128 v[212:215], v111
	ds_read_b128 v[216:219], v116 offset:16384
	ds_read_b128 v[220:223], v116 offset:18432
	ds_read_b128 v[224:227], v114
	ds_read_b128 v[228:231], v114 offset:2048
	ds_read_b128 v[232:235], v116 offset:20480
	ds_read_b128 v[236:239], v117 offset:16384
	ds_read_b128 v[240:243], v114 offset:4096
	ds_read_b128 v[244:247], v115
	s_setprio 1
	s_waitcnt lgkmcnt(13)
	v_mfma_f32_16x16x32_bf16 v[94:97], v[152:155], v[160:163], v[94:97]
	v_mfma_f32_16x16x32_bf16 v[90:93], v[156:159], v[160:163], v[90:93]
	s_waitcnt lgkmcnt(11)
	v_mfma_f32_16x16x32_bf16 v[86:89], v[168:171], v[160:163], v[86:89]
	s_waitcnt lgkmcnt(10)
	v_mfma_f32_16x16x32_bf16 v[82:85], v[172:175], v[160:163], v[82:85]
	v_mfma_f32_16x16x32_bf16 v[78:81], v[152:155], v[164:167], v[78:81]
	v_mfma_f32_16x16x32_bf16 v[54:57], v[156:159], v[164:167], v[54:57]
	v_mfma_f32_16x16x32_bf16 v[38:41], v[168:171], v[164:167], v[38:41]
	v_mfma_f32_16x16x32_bf16 v[34:37], v[172:175], v[164:167], v[34:37]
	s_waitcnt lgkmcnt(9)
	v_mfma_f32_16x16x32_bf16 v[74:77], v[152:155], v[208:211], v[74:77]
	v_mfma_f32_16x16x32_bf16 v[70:73], v[156:159], v[208:211], v[70:73]
	v_mfma_f32_16x16x32_bf16 v[66:69], v[168:171], v[208:211], v[66:69]
	v_mfma_f32_16x16x32_bf16 v[62:65], v[172:175], v[208:211], v[62:65]
	s_waitcnt lgkmcnt(8)
	v_mfma_f32_16x16x32_bf16 v[58:61], v[152:155], v[212:215], v[58:61]
	v_mfma_f32_16x16x32_bf16 v[50:53], v[156:159], v[212:215], v[50:53]
	v_mfma_f32_16x16x32_bf16 v[46:49], v[168:171], v[212:215], v[46:49]
	v_mfma_f32_16x16x32_bf16 v[42:45], v[172:175], v[212:215], v[42:45]
	s_setprio 0
	s_waitcnt lgkmcnt(0)
	s_waitcnt vmcnt(0)
	s_barrier
	s_setprio 1
	v_mfma_f32_16x16x32_bf16 v[94:97], v[216:219], v[224:227], v[94:97]
	v_mfma_f32_16x16x32_bf16 v[90:93], v[220:223], v[224:227], v[90:93]
	v_mfma_f32_16x16x32_bf16 v[86:89], v[232:235], v[224:227], v[86:89]
	v_mfma_f32_16x16x32_bf16 v[82:85], v[236:239], v[224:227], v[82:85]
	v_mfma_f32_16x16x32_bf16 v[78:81], v[216:219], v[228:231], v[78:81]
	v_mfma_f32_16x16x32_bf16 v[54:57], v[220:223], v[228:231], v[54:57]
	v_mfma_f32_16x16x32_bf16 v[38:41], v[232:235], v[228:231], v[38:41]
	v_mfma_f32_16x16x32_bf16 v[34:37], v[236:239], v[228:231], v[34:37]
	v_mfma_f32_16x16x32_bf16 v[74:77], v[216:219], v[240:243], v[74:77]
	v_mfma_f32_16x16x32_bf16 v[70:73], v[220:223], v[240:243], v[70:73]
	v_mfma_f32_16x16x32_bf16 v[66:69], v[232:235], v[240:243], v[66:69]
	v_mfma_f32_16x16x32_bf16 v[62:65], v[236:239], v[240:243], v[62:65]
	v_mfma_f32_16x16x32_bf16 v[58:61], v[216:219], v[244:247], v[58:61]
	v_mfma_f32_16x16x32_bf16 v[50:53], v[220:223], v[244:247], v[50:53]
	v_mfma_f32_16x16x32_bf16 v[46:49], v[232:235], v[244:247], v[46:49]
	v_mfma_f32_16x16x32_bf16 v[42:45], v[236:239], v[244:247], v[42:45]
	s_setprio 0
	ds_read_b128 v[152:155], v112 offset:49152
	ds_read_b128 v[156:159], v112 offset:51200
	ds_read_b128 v[160:163], v110 offset:32768
	ds_read_b128 v[164:167], v110 offset:34816
	ds_read_b128 v[168:171], v112 offset:53248
	ds_read_b128 v[172:175], v113 offset:49152
	ds_read_b128 v[208:211], v110 offset:36864
	ds_read_b128 v[212:215], v111 offset:32768
	ds_read_b128 v[216:219], v116 offset:49152
	ds_read_b128 v[220:223], v116 offset:51200
	ds_read_b128 v[224:227], v114 offset:32768
	ds_read_b128 v[228:231], v114 offset:34816
	ds_read_b128 v[232:235], v116 offset:53248
	ds_read_b128 v[236:239], v117 offset:49152
	ds_read_b128 v[240:243], v114 offset:36864
	ds_read_b128 v[244:247], v115 offset:32768
	s_setprio 1
	s_waitcnt lgkmcnt(13)
	v_mfma_f32_16x16x32_bf16 v[94:97], v[152:155], v[160:163], v[94:97]
	v_mfma_f32_16x16x32_bf16 v[90:93], v[156:159], v[160:163], v[90:93]
	s_waitcnt lgkmcnt(11)
	v_mfma_f32_16x16x32_bf16 v[86:89], v[168:171], v[160:163], v[86:89]
	s_waitcnt lgkmcnt(10)
	v_mfma_f32_16x16x32_bf16 v[82:85], v[172:175], v[160:163], v[82:85]
	v_mfma_f32_16x16x32_bf16 v[78:81], v[152:155], v[164:167], v[78:81]
	v_mfma_f32_16x16x32_bf16 v[54:57], v[156:159], v[164:167], v[54:57]
	v_mfma_f32_16x16x32_bf16 v[38:41], v[168:171], v[164:167], v[38:41]
	v_mfma_f32_16x16x32_bf16 v[34:37], v[172:175], v[164:167], v[34:37]
	s_waitcnt lgkmcnt(9)
	v_mfma_f32_16x16x32_bf16 v[74:77], v[152:155], v[208:211], v[74:77]
	v_mfma_f32_16x16x32_bf16 v[70:73], v[156:159], v[208:211], v[70:73]
	v_mfma_f32_16x16x32_bf16 v[66:69], v[168:171], v[208:211], v[66:69]
	v_mfma_f32_16x16x32_bf16 v[62:65], v[172:175], v[208:211], v[62:65]
	s_waitcnt lgkmcnt(8)
	v_mfma_f32_16x16x32_bf16 v[58:61], v[152:155], v[212:215], v[58:61]
	v_mfma_f32_16x16x32_bf16 v[50:53], v[156:159], v[212:215], v[50:53]
	v_mfma_f32_16x16x32_bf16 v[46:49], v[168:171], v[212:215], v[46:49]
	v_mfma_f32_16x16x32_bf16 v[42:45], v[172:175], v[212:215], v[42:45]
	s_setprio 0
	s_waitcnt lgkmcnt(0)
	s_barrier
	s_setprio 1
	v_mfma_f32_16x16x32_bf16 v[94:97], v[216:219], v[224:227], v[94:97]
	v_mfma_f32_16x16x32_bf16 v[90:93], v[220:223], v[224:227], v[90:93]
	v_mfma_f32_16x16x32_bf16 v[86:89], v[232:235], v[224:227], v[86:89]
	v_mfma_f32_16x16x32_bf16 v[82:85], v[236:239], v[224:227], v[82:85]
	v_mfma_f32_16x16x32_bf16 v[78:81], v[216:219], v[228:231], v[78:81]
	v_mfma_f32_16x16x32_bf16 v[54:57], v[220:223], v[228:231], v[54:57]
	v_mfma_f32_16x16x32_bf16 v[38:41], v[232:235], v[228:231], v[38:41]
	v_mfma_f32_16x16x32_bf16 v[34:37], v[236:239], v[228:231], v[34:37]
	v_mfma_f32_16x16x32_bf16 v[74:77], v[216:219], v[240:243], v[74:77]
	v_mfma_f32_16x16x32_bf16 v[70:73], v[220:223], v[240:243], v[70:73]
	v_mfma_f32_16x16x32_bf16 v[66:69], v[232:235], v[240:243], v[66:69]
	v_mfma_f32_16x16x32_bf16 v[62:65], v[236:239], v[240:243], v[62:65]
	v_mfma_f32_16x16x32_bf16 v[58:61], v[216:219], v[244:247], v[58:61]
	v_mfma_f32_16x16x32_bf16 v[50:53], v[220:223], v[244:247], v[50:53]
	v_mfma_f32_16x16x32_bf16 v[46:49], v[232:235], v[244:247], v[46:49]
	v_mfma_f32_16x16x32_bf16 v[42:45], v[236:239], v[244:247], v[42:45]
	s_setprio 0
	s_waitcnt vmcnt(0)
	v_readlane_b32 s36, v254, 40
	s_lshl_b64 s[12:13], s[12:13], 21
	v_readlane_b32 s50, v254, 54
	v_readlane_b32 s51, v254, 55
	s_add_u32 s12, s50, s12
	s_addc_u32 s13, s51, s13
	s_waitcnt vmcnt(7)
	v_or_b32_e32 v4, s17, v119
	v_add_lshl_u32 v98, v118, s16, 10
	v_lshl_add_u64 v[2:3], s[12:13], 0, v[98:99]
	v_lshlrev_b32_e32 v98, 1, v4
	v_lshl_add_u64 v[4:5], v[2:3], 0, v[98:99]
	s_waitcnt vmcnt(6)
	v_cvt_pk_bf16_f32 v6, v94, v95
	v_cvt_pk_bf16_f32 v7, v96, v97
	global_store_dwordx2 v[4:5], v[6:7], off
	v_cvt_pk_bf16_f32 v6, v90, v91
	v_cvt_pk_bf16_f32 v7, v92, v93
	global_store_dwordx2 v[4:5], v[6:7], off offset:32
	v_cvt_pk_bf16_f32 v6, v86, v87
	v_cvt_pk_bf16_f32 v7, v88, v89
	global_store_dwordx2 v[4:5], v[6:7], off offset:64
	v_cvt_pk_bf16_f32 v6, v82, v83
	v_cvt_pk_bf16_f32 v7, v84, v85
	global_store_dwordx2 v[4:5], v[6:7], off offset:96
	v_lshl_add_u64 v[4:5], v[2:3], 0, s[4:5]
	v_lshl_add_u64 v[6:7], v[4:5], 0, v[98:99]
	v_cvt_pk_bf16_f32 v8, v78, v79
	v_cvt_pk_bf16_f32 v9, v80, v81
	global_store_dwordx2 v[6:7], v[8:9], off
	v_or_b32_e32 v6, 32, v98
	v_mov_b32_e32 v7, v99
	v_lshl_add_u64 v[8:9], v[4:5], 0, v[6:7]
	s_waitcnt vmcnt(10)
	v_cvt_pk_bf16_f32 v10, v54, v55
	v_cvt_pk_bf16_f32 v11, v56, v57
	global_store_dwordx2 v[8:9], v[10:11], off
	v_or_b32_e32 v8, 64, v98
	v_mov_b32_e32 v9, v99
	v_lshl_add_u64 v[10:11], v[4:5], 0, v[8:9]
	v_cvt_pk_bf16_f32 v12, v38, v39
	v_cvt_pk_bf16_f32 v13, v40, v41
	global_store_dwordx2 v[10:11], v[12:13], off
	v_or_b32_e32 v10, 0x60, v98
	v_mov_b32_e32 v11, v99
	v_lshl_add_u64 v[4:5], v[4:5], 0, v[10:11]
	v_cvt_pk_bf16_f32 v12, v34, v35
	v_cvt_pk_bf16_f32 v13, v36, v37
	global_store_dwordx2 v[4:5], v[12:13], off
	v_lshl_add_u64 v[4:5], v[2:3], 0, s[6:7]
	v_lshl_add_u64 v[12:13], v[4:5], 0, v[98:99]
	s_waitcnt vmcnt(11)
	v_cvt_pk_bf16_f32 v14, v74, v75
	v_cvt_pk_bf16_f32 v15, v76, v77
	global_store_dwordx2 v[12:13], v[14:15], off
	v_lshl_add_u64 v[12:13], v[4:5], 0, v[6:7]
	v_cvt_pk_bf16_f32 v14, v70, v71
	v_cvt_pk_bf16_f32 v15, v72, v73
	global_store_dwordx2 v[12:13], v[14:15], off
	v_lshl_add_u64 v[12:13], v[4:5], 0, v[8:9]
	v_cvt_pk_bf16_f32 v14, v66, v67
	v_cvt_pk_bf16_f32 v15, v68, v69
	global_store_dwordx2 v[12:13], v[14:15], off
	v_lshl_add_u64 v[4:5], v[4:5], 0, v[10:11]
	v_cvt_pk_bf16_f32 v12, v62, v63
	v_cvt_pk_bf16_f32 v13, v64, v65
	v_lshl_add_u64 v[2:3], v[2:3], 0, s[8:9]
	global_store_dwordx2 v[4:5], v[12:13], off
	v_lshl_add_u64 v[4:5], v[2:3], 0, v[98:99]
	v_cvt_pk_bf16_f32 v12, v58, v59
	v_cvt_pk_bf16_f32 v13, v60, v61
	global_store_dwordx2 v[4:5], v[12:13], off
	v_lshl_add_u64 v[4:5], v[2:3], 0, v[6:7]
	v_cvt_pk_bf16_f32 v6, v50, v51
	v_cvt_pk_bf16_f32 v7, v52, v53
	v_readlane_b32 s12, v254, 0
	global_store_dwordx2 v[4:5], v[6:7], off
	v_lshl_add_u64 v[4:5], v[2:3], 0, v[8:9]
	v_cvt_pk_bf16_f32 v6, v46, v47
	v_cvt_pk_bf16_f32 v7, v48, v49
	s_add_i32 s2, s2, s12
	v_readlane_b32 s37, v254, 41
	global_store_dwordx2 v[4:5], v[6:7], off
	v_lshl_add_u64 v[2:3], v[2:3], 0, v[10:11]
	v_cvt_pk_bf16_f32 v4, v42, v43
	v_cvt_pk_bf16_f32 v5, v44, v45
	s_cmpk_lt_i32 s2, 0x80
	v_readlane_b32 s38, v254, 42
	v_readlane_b32 s39, v254, 43
	v_readlane_b32 s40, v254, 44
	v_readlane_b32 s41, v254, 45
	v_readlane_b32 s42, v254, 46
	v_readlane_b32 s43, v254, 47
	v_readlane_b32 s44, v254, 48
	v_readlane_b32 s45, v254, 49
	v_readlane_b32 s46, v254, 50
	v_readlane_b32 s47, v254, 51
	v_readlane_b32 s48, v254, 52
	v_readlane_b32 s49, v254, 53
	v_readlane_b32 s13, v254, 1
	global_store_dwordx2 v[2:3], v[4:5], off
	s_cbranch_scc1 .LBB0_220

.Lglds2_12468:
	ds_read_b128 v[152:155], v112 offset:16384
	ds_read_b128 v[156:159], v112 offset:18432
	ds_read_b128 v[160:163], v110
	ds_read_b128 v[164:167], v110 offset:2048
	ds_read_b128 v[168:171], v112 offset:20480
	ds_read_b128 v[172:175], v113 offset:16384
	ds_read_b128 v[204:207], v110 offset:4096
	ds_read_b128 v[208:211], v111
	ds_read_b128 v[212:215], v116 offset:16384
	ds_read_b128 v[216:219], v116 offset:18432
	ds_read_b128 v[220:223], v114
	ds_read_b128 v[224:227], v114 offset:2048
	ds_read_b128 v[228:231], v116 offset:20480
	ds_read_b128 v[232:235], v117 offset:16384
	ds_read_b128 v[236:239], v114 offset:4096
	ds_read_b128 v[240:243], v115
	s_setprio 1
	s_waitcnt lgkmcnt(13)
	v_mfma_f32_16x16x32_bf16 v[94:97], v[152:155], v[160:163], v[94:97]
	v_mfma_f32_16x16x32_bf16 v[90:93], v[156:159], v[160:163], v[90:93]
	s_waitcnt lgkmcnt(11)
	v_mfma_f32_16x16x32_bf16 v[86:89], v[168:171], v[160:163], v[86:89]
	s_waitcnt lgkmcnt(10)
	v_mfma_f32_16x16x32_bf16 v[82:85], v[172:175], v[160:163], v[82:85]
	v_mfma_f32_16x16x32_bf16 v[78:81], v[152:155], v[164:167], v[78:81]
	v_mfma_f32_16x16x32_bf16 v[74:77], v[156:159], v[164:167], v[74:77]
	v_mfma_f32_16x16x32_bf16 v[62:65], v[168:171], v[164:167], v[62:65]
	v_mfma_f32_16x16x32_bf16 v[30:33], v[172:175], v[164:167], v[30:33]
	s_waitcnt lgkmcnt(9)
	v_mfma_f32_16x16x32_bf16 v[66:69], v[152:155], v[204:207], v[66:69]
	v_mfma_f32_16x16x32_bf16 v[38:41], v[156:159], v[204:207], v[38:41]
	v_mfma_f32_16x16x32_bf16 v[34:37], v[168:171], v[204:207], v[34:37]
	v_mfma_f32_16x16x32_bf16 v[18:21], v[172:175], v[204:207], v[18:21]
	s_waitcnt lgkmcnt(8)
	v_mfma_f32_16x16x32_bf16 v[14:17], v[152:155], v[208:211], v[14:17]
	v_mfma_f32_16x16x32_bf16 v[10:13], v[156:159], v[208:211], v[10:13]
	v_mfma_f32_16x16x32_bf16 v[6:9], v[168:171], v[208:211], v[6:9]
	v_mfma_f32_16x16x32_bf16 v[2:5], v[172:175], v[208:211], v[2:5]
	s_setprio 0
	s_waitcnt lgkmcnt(0)
	s_waitcnt vmcnt(0)
	s_barrier
	s_add_i32 s4, s14, 0x80
	s_min_u32 s4, s4, 0x3c0
	s_lshl_b32 s4, s4, 1
	s_setprio 1
	v_mfma_f32_16x16x32_bf16 v[94:97], v[212:215], v[220:223], v[94:97]
	s_add_u32 m0, s15, 0x0
	v_lshl_add_u64 v[200:201], v[184:185], 0, s[4:5]
	global_load_lds_dwordx4 v[200:201], off
	v_mfma_f32_16x16x32_bf16 v[90:93], v[216:219], v[220:223], v[90:93]
	v_mfma_f32_16x16x32_bf16 v[86:89], v[228:231], v[220:223], v[86:89]
	s_add_u32 m0, s15, 0x1000
	v_lshl_add_u64 v[202:203], v[186:187], 0, s[4:5]
	global_load_lds_dwordx4 v[202:203], off
	v_mfma_f32_16x16x32_bf16 v[82:85], v[232:235], v[220:223], v[82:85]
	v_mfma_f32_16x16x32_bf16 v[78:81], v[212:215], v[224:227], v[78:81]
	s_add_u32 m0, s15, 0x2000
	v_lshl_add_u64 v[200:201], v[188:189], 0, s[4:5]
	global_load_lds_dwordx4 v[200:201], off
	v_mfma_f32_16x16x32_bf16 v[74:77], v[216:219], v[224:227], v[74:77]
	v_mfma_f32_16x16x32_bf16 v[62:65], v[228:231], v[224:227], v[62:65]
	s_add_u32 m0, s15, 0x3000
	v_lshl_add_u64 v[202:203], v[190:191], 0, s[4:5]
	global_load_lds_dwordx4 v[202:203], off
	v_mfma_f32_16x16x32_bf16 v[30:33], v[232:235], v[224:227], v[30:33]
	v_mfma_f32_16x16x32_bf16 v[66:69], v[212:215], v[236:239], v[66:69]
	s_add_u32 m0, s15, 0x4000
	v_lshl_add_u64 v[200:201], v[192:193], 0, s[4:5]
	global_load_lds_dwordx4 v[200:201], off
	v_mfma_f32_16x16x32_bf16 v[38:41], v[216:219], v[236:239], v[38:41]
	v_mfma_f32_16x16x32_bf16 v[34:37], v[228:231], v[236:239], v[34:37]
	s_add_u32 m0, s15, 0x5000
	v_lshl_add_u64 v[202:203], v[194:195], 0, s[4:5]
	global_load_lds_dwordx4 v[202:203], off
	v_mfma_f32_16x16x32_bf16 v[18:21], v[232:235], v[236:239], v[18:21]
	v_mfma_f32_16x16x32_bf16 v[14:17], v[212:215], v[240:243], v[14:17]
	s_add_u32 m0, s15, 0x6000
	v_lshl_add_u64 v[200:201], v[196:197], 0, s[4:5]
	global_load_lds_dwordx4 v[200:201], off
	v_mfma_f32_16x16x32_bf16 v[10:13], v[216:219], v[240:243], v[10:13]
	v_mfma_f32_16x16x32_bf16 v[6:9], v[228:231], v[240:243], v[6:9]
	s_add_u32 m0, s15, 0x7000
	v_lshl_add_u64 v[202:203], v[198:199], 0, s[4:5]
	global_load_lds_dwordx4 v[202:203], off
	v_mfma_f32_16x16x32_bf16 v[2:5], v[232:235], v[240:243], v[2:5]
	s_setprio 0
	ds_read_b128 v[152:155], v112 offset:49152
	ds_read_b128 v[156:159], v112 offset:51200
	ds_read_b128 v[160:163], v110 offset:32768
	ds_read_b128 v[164:167], v110 offset:34816
	ds_read_b128 v[168:171], v112 offset:53248
	ds_read_b128 v[172:175], v113 offset:49152
	ds_read_b128 v[204:207], v110 offset:36864
	ds_read_b128 v[208:211], v111 offset:32768
	ds_read_b128 v[212:215], v116 offset:49152
	ds_read_b128 v[216:219], v116 offset:51200
	ds_read_b128 v[220:223], v114 offset:32768
	ds_read_b128 v[224:227], v114 offset:34816
	ds_read_b128 v[228:231], v116 offset:53248
	ds_read_b128 v[232:235], v117 offset:49152
	ds_read_b128 v[236:239], v114 offset:36864
	ds_read_b128 v[240:243], v115 offset:32768
	s_setprio 1
	s_waitcnt lgkmcnt(13)
	v_mfma_f32_16x16x32_bf16 v[94:97], v[152:155], v[160:163], v[94:97]
	v_mfma_f32_16x16x32_bf16 v[90:93], v[156:159], v[160:163], v[90:93]
	s_waitcnt lgkmcnt(11)
	v_mfma_f32_16x16x32_bf16 v[86:89], v[168:171], v[160:163], v[86:89]
	s_waitcnt lgkmcnt(10)
	v_mfma_f32_16x16x32_bf16 v[82:85], v[172:175], v[160:163], v[82:85]
	v_mfma_f32_16x16x32_bf16 v[78:81], v[152:155], v[164:167], v[78:81]
	v_mfma_f32_16x16x32_bf16 v[74:77], v[156:159], v[164:167], v[74:77]
	v_mfma_f32_16x16x32_bf16 v[62:65], v[168:171], v[164:167], v[62:65]
	v_mfma_f32_16x16x32_bf16 v[30:33], v[172:175], v[164:167], v[30:33]
	s_waitcnt lgkmcnt(9)
	v_mfma_f32_16x16x32_bf16 v[66:69], v[152:155], v[204:207], v[66:69]
	v_mfma_f32_16x16x32_bf16 v[38:41], v[156:159], v[204:207], v[38:41]
	v_mfma_f32_16x16x32_bf16 v[34:37], v[168:171], v[204:207], v[34:37]
	v_mfma_f32_16x16x32_bf16 v[18:21], v[172:175], v[204:207], v[18:21]
	s_waitcnt lgkmcnt(8)
	v_mfma_f32_16x16x32_bf16 v[14:17], v[152:155], v[208:211], v[14:17]
	v_mfma_f32_16x16x32_bf16 v[10:13], v[156:159], v[208:211], v[10:13]
	v_mfma_f32_16x16x32_bf16 v[6:9], v[168:171], v[208:211], v[6:9]
	v_mfma_f32_16x16x32_bf16 v[2:5], v[172:175], v[208:211], v[2:5]
	s_setprio 0
	s_waitcnt lgkmcnt(0)
	s_waitcnt vmcnt(0)
	s_barrier
	s_add_i32 s4, s14, 0xc0
	s_min_u32 s4, s4, 0x3c0
	s_lshl_b32 s4, s4, 1
	s_setprio 1
	v_mfma_f32_16x16x32_bf16 v[94:97], v[212:215], v[220:223], v[94:97]
	s_add_u32 m0, s15, 0x8000
	v_lshl_add_u64 v[200:201], v[184:185], 0, s[4:5]
	global_load_lds_dwordx4 v[200:201], off
	v_mfma_f32_16x16x32_bf16 v[90:93], v[216:219], v[220:223], v[90:93]
	v_mfma_f32_16x16x32_bf16 v[86:89], v[228:231], v[220:223], v[86:89]
	s_add_u32 m0, s15, 0x9000
	v_lshl_add_u64 v[202:203], v[186:187], 0, s[4:5]
	global_load_lds_dwordx4 v[202:203], off
	v_mfma_f32_16x16x32_bf16 v[82:85], v[232:235], v[220:223], v[82:85]
	v_mfma_f32_16x16x32_bf16 v[78:81], v[212:215], v[224:227], v[78:81]
	s_add_u32 m0, s15, 0xa000
	v_lshl_add_u64 v[200:201], v[188:189], 0, s[4:5]
	global_load_lds_dwordx4 v[200:201], off
	v_mfma_f32_16x16x32_bf16 v[74:77], v[216:219], v[224:227], v[74:77]
	v_mfma_f32_16x16x32_bf16 v[62:65], v[228:231], v[224:227], v[62:65]
	s_add_u32 m0, s15, 0xb000
	v_lshl_add_u64 v[202:203], v[190:191], 0, s[4:5]
	global_load_lds_dwordx4 v[202:203], off
	v_mfma_f32_16x16x32_bf16 v[30:33], v[232:235], v[224:227], v[30:33]
	v_mfma_f32_16x16x32_bf16 v[66:69], v[212:215], v[236:239], v[66:69]
	s_add_u32 m0, s15, 0xc000
	v_lshl_add_u64 v[200:201], v[192:193], 0, s[4:5]
	global_load_lds_dwordx4 v[200:201], off
	v_mfma_f32_16x16x32_bf16 v[38:41], v[216:219], v[236:239], v[38:41]
	v_mfma_f32_16x16x32_bf16 v[34:37], v[228:231], v[236:239], v[34:37]
	s_add_u32 m0, s15, 0xd000
	v_lshl_add_u64 v[202:203], v[194:195], 0, s[4:5]
	global_load_lds_dwordx4 v[202:203], off
	v_mfma_f32_16x16x32_bf16 v[18:21], v[232:235], v[236:239], v[18:21]
	v_mfma_f32_16x16x32_bf16 v[14:17], v[212:215], v[240:243], v[14:17]
	s_add_u32 m0, s15, 0xe000
	v_lshl_add_u64 v[200:201], v[196:197], 0, s[4:5]
	global_load_lds_dwordx4 v[200:201], off
	v_mfma_f32_16x16x32_bf16 v[10:13], v[216:219], v[240:243], v[10:13]
	v_mfma_f32_16x16x32_bf16 v[6:9], v[228:231], v[240:243], v[6:9]
	s_add_u32 m0, s15, 0xf000
	v_lshl_add_u64 v[202:203], v[198:199], 0, s[4:5]
	global_load_lds_dwordx4 v[202:203], off
	v_mfma_f32_16x16x32_bf16 v[2:5], v[232:235], v[240:243], v[2:5]
	s_setprio 0
	s_add_i32 s14, s14, 0x80
	s_add_i32 s13, s13, 2
	s_cmp_lt_u32 s13, 14
	s_cbranch_scc1 .Lglds2_12468
	ds_read_b128 v[152:155], v112 offset:16384
	ds_read_b128 v[156:159], v112 offset:18432
	ds_read_b128 v[160:163], v110
	ds_read_b128 v[164:167], v110 offset:2048
	ds_read_b128 v[168:171], v112 offset:20480
	ds_read_b128 v[172:175], v113 offset:16384
	ds_read_b128 v[204:207], v110 offset:4096
	ds_read_b128 v[208:211], v111
	ds_read_b128 v[212:215], v116 offset:16384
	ds_read_b128 v[216:219], v116 offset:18432
	ds_read_b128 v[220:223], v114
	ds_read_b128 v[224:227], v114 offset:2048
	ds_read_b128 v[228:231], v116 offset:20480
	ds_read_b128 v[232:235], v117 offset:16384
	ds_read_b128 v[236:239], v114 offset:4096
	ds_read_b128 v[240:243], v115
	s_setprio 1
	s_waitcnt lgkmcnt(13)
	v_mfma_f32_16x16x32_bf16 v[94:97], v[152:155], v[160:163], v[94:97]
	v_mfma_f32_16x16x32_bf16 v[90:93], v[156:159], v[160:163], v[90:93]
	s_waitcnt lgkmcnt(11)
	v_mfma_f32_16x16x32_bf16 v[86:89], v[168:171], v[160:163], v[86:89]
	s_waitcnt lgkmcnt(10)
	v_mfma_f32_16x16x32_bf16 v[82:85], v[172:175], v[160:163], v[82:85]
	v_mfma_f32_16x16x32_bf16 v[78:81], v[152:155], v[164:167], v[78:81]
	v_mfma_f32_16x16x32_bf16 v[74:77], v[156:159], v[164:167], v[74:77]
	v_mfma_f32_16x16x32_bf16 v[62:65], v[168:171], v[164:167], v[62:65]
	v_mfma_f32_16x16x32_bf16 v[30:33], v[172:175], v[164:167], v[30:33]
	s_waitcnt lgkmcnt(9)
	v_mfma_f32_16x16x32_bf16 v[66:69], v[152:155], v[204:207], v[66:69]
	v_mfma_f32_16x16x32_bf16 v[38:41], v[156:159], v[204:207], v[38:41]
	v_mfma_f32_16x16x32_bf16 v[34:37], v[168:171], v[204:207], v[34:37]
	v_mfma_f32_16x16x32_bf16 v[18:21], v[172:175], v[204:207], v[18:21]
	s_waitcnt lgkmcnt(8)
	v_mfma_f32_16x16x32_bf16 v[14:17], v[152:155], v[208:211], v[14:17]
	v_mfma_f32_16x16x32_bf16 v[10:13], v[156:159], v[208:211], v[10:13]
	v_mfma_f32_16x16x32_bf16 v[6:9], v[168:171], v[208:211], v[6:9]
	v_mfma_f32_16x16x32_bf16 v[2:5], v[172:175], v[208:211], v[2:5]
	s_setprio 0
	s_waitcnt lgkmcnt(0)
	s_waitcnt vmcnt(0)
	s_barrier
	s_setprio 1
	v_mfma_f32_16x16x32_bf16 v[94:97], v[212:215], v[220:223], v[94:97]
	v_mfma_f32_16x16x32_bf16 v[90:93], v[216:219], v[220:223], v[90:93]
	v_mfma_f32_16x16x32_bf16 v[86:89], v[228:231], v[220:223], v[86:89]
	v_mfma_f32_16x16x32_bf16 v[82:85], v[232:235], v[220:223], v[82:85]
	v_mfma_f32_16x16x32_bf16 v[78:81], v[212:215], v[224:227], v[78:81]
	v_mfma_f32_16x16x32_bf16 v[74:77], v[216:219], v[224:227], v[74:77]
	v_mfma_f32_16x16x32_bf16 v[62:65], v[228:231], v[224:227], v[62:65]
	v_mfma_f32_16x16x32_bf16 v[30:33], v[232:235], v[224:227], v[30:33]
	v_mfma_f32_16x16x32_bf16 v[66:69], v[212:215], v[236:239], v[66:69]
	v_mfma_f32_16x16x32_bf16 v[38:41], v[216:219], v[236:239], v[38:41]
	v_mfma_f32_16x16x32_bf16 v[34:37], v[228:231], v[236:239], v[34:37]
	v_mfma_f32_16x16x32_bf16 v[18:21], v[232:235], v[236:239], v[18:21]
	v_mfma_f32_16x16x32_bf16 v[14:17], v[212:215], v[240:243], v[14:17]
	v_mfma_f32_16x16x32_bf16 v[10:13], v[216:219], v[240:243], v[10:13]
	v_mfma_f32_16x16x32_bf16 v[6:9], v[228:231], v[240:243], v[6:9]
	v_mfma_f32_16x16x32_bf16 v[2:5], v[232:235], v[240:243], v[2:5]
	s_setprio 0
	ds_read_b128 v[152:155], v112 offset:49152
	ds_read_b128 v[156:159], v112 offset:51200
	ds_read_b128 v[160:163], v110 offset:32768
	ds_read_b128 v[164:167], v110 offset:34816
	ds_read_b128 v[168:171], v112 offset:53248
	ds_read_b128 v[172:175], v113 offset:49152
	ds_read_b128 v[204:207], v110 offset:36864
	ds_read_b128 v[208:211], v111 offset:32768
	ds_read_b128 v[212:215], v116 offset:49152
	ds_read_b128 v[216:219], v116 offset:51200
	ds_read_b128 v[220:223], v114 offset:32768
	ds_read_b128 v[224:227], v114 offset:34816
	ds_read_b128 v[228:231], v116 offset:53248
	ds_read_b128 v[232:235], v117 offset:49152
	ds_read_b128 v[236:239], v114 offset:36864
	ds_read_b128 v[240:243], v115 offset:32768
	s_setprio 1
	s_waitcnt lgkmcnt(13)
	v_mfma_f32_16x16x32_bf16 v[94:97], v[152:155], v[160:163], v[94:97]
	v_mfma_f32_16x16x32_bf16 v[90:93], v[156:159], v[160:163], v[90:93]
	s_waitcnt lgkmcnt(11)
	v_mfma_f32_16x16x32_bf16 v[86:89], v[168:171], v[160:163], v[86:89]
	s_waitcnt lgkmcnt(10)
	v_mfma_f32_16x16x32_bf16 v[82:85], v[172:175], v[160:163], v[82:85]
	v_mfma_f32_16x16x32_bf16 v[78:81], v[152:155], v[164:167], v[78:81]
	v_mfma_f32_16x16x32_bf16 v[74:77], v[156:159], v[164:167], v[74:77]
	v_mfma_f32_16x16x32_bf16 v[62:65], v[168:171], v[164:167], v[62:65]
	v_mfma_f32_16x16x32_bf16 v[30:33], v[172:175], v[164:167], v[30:33]
	s_waitcnt lgkmcnt(9)
	v_mfma_f32_16x16x32_bf16 v[66:69], v[152:155], v[204:207], v[66:69]
	v_mfma_f32_16x16x32_bf16 v[38:41], v[156:159], v[204:207], v[38:41]
	v_mfma_f32_16x16x32_bf16 v[34:37], v[168:171], v[204:207], v[34:37]
	v_mfma_f32_16x16x32_bf16 v[18:21], v[172:175], v[204:207], v[18:21]
	s_waitcnt lgkmcnt(8)
	v_mfma_f32_16x16x32_bf16 v[14:17], v[152:155], v[208:211], v[14:17]
	v_mfma_f32_16x16x32_bf16 v[10:13], v[156:159], v[208:211], v[10:13]
	v_mfma_f32_16x16x32_bf16 v[6:9], v[168:171], v[208:211], v[6:9]
	v_mfma_f32_16x16x32_bf16 v[2:5], v[172:175], v[208:211], v[2:5]
	s_setprio 0
	s_waitcnt lgkmcnt(0)
	s_barrier
	s_setprio 1
	v_mfma_f32_16x16x32_bf16 v[94:97], v[212:215], v[220:223], v[94:97]
	v_mfma_f32_16x16x32_bf16 v[90:93], v[216:219], v[220:223], v[90:93]
	v_mfma_f32_16x16x32_bf16 v[86:89], v[228:231], v[220:223], v[86:89]
	v_mfma_f32_16x16x32_bf16 v[82:85], v[232:235], v[220:223], v[82:85]
	v_mfma_f32_16x16x32_bf16 v[78:81], v[212:215], v[224:227], v[78:81]
	v_mfma_f32_16x16x32_bf16 v[74:77], v[216:219], v[224:227], v[74:77]
	v_mfma_f32_16x16x32_bf16 v[62:65], v[228:231], v[224:227], v[62:65]
	v_mfma_f32_16x16x32_bf16 v[30:33], v[232:235], v[224:227], v[30:33]
	v_mfma_f32_16x16x32_bf16 v[66:69], v[212:215], v[236:239], v[66:69]
	v_mfma_f32_16x16x32_bf16 v[38:41], v[216:219], v[236:239], v[38:41]
	v_mfma_f32_16x16x32_bf16 v[34:37], v[228:231], v[236:239], v[34:37]
	v_mfma_f32_16x16x32_bf16 v[18:21], v[232:235], v[236:239], v[18:21]
	v_mfma_f32_16x16x32_bf16 v[14:17], v[212:215], v[240:243], v[14:17]
	v_mfma_f32_16x16x32_bf16 v[10:13], v[216:219], v[240:243], v[10:13]
	v_mfma_f32_16x16x32_bf16 v[6:9], v[228:231], v[240:243], v[6:9]
	v_mfma_f32_16x16x32_bf16 v[2:5], v[232:235], v[240:243], v[2:5]
	s_setprio 0
	s_waitcnt vmcnt(0)
	s_waitcnt vmcnt(0)
	v_or_b32_e32 v170, s12, v119
	v_add_lshl_u32 v98, v118, s11, 10
	v_readlane_b32 s12, v254, 8
	v_readlane_b32 s13, v254, 9
	v_readlane_b32 s14, v254, 10
	v_readlane_b32 s15, v254, 11
	v_readlane_b32 s16, v254, 12
	v_readlane_b32 s17, v254, 13
	v_readlane_b32 s18, v254, 14
	v_readlane_b32 s19, v254, 15
	v_readlane_b32 s20, v254, 16
	v_readlane_b32 s21, v254, 17
	v_readlane_b32 s22, v254, 18
	v_readlane_b32 s23, v254, 19
	v_readlane_b32 s24, v254, 20
	v_readlane_b32 s25, v254, 21
	v_readlane_b32 s26, v254, 22
	v_readlane_b32 s27, v254, 23
	v_lshlrev_b32_e32 v168, 2, v170
	v_mov_b32_e32 v169, v99
	v_lshlrev_b64 v[174:175], 2, v[98:99]
	v_lshl_add_u64 v[152:153], s[12:13], 0, v[174:175]
	v_lshl_add_u64 v[160:161], s[82:83], 0, v[174:175]
	v_lshl_add_u64 v[152:153], v[152:153], 0, v[168:169]
	v_lshl_add_u64 v[160:161], v[160:161], 0, v[168:169]
	global_load_dwordx4 v[120:123], v[152:153], off
	global_load_dwordx4 v[124:127], v[152:153], off offset:64
	global_load_dwordx4 v[128:131], v[152:153], off offset:128
	global_load_dwordx4 v[132:135], v[152:153], off offset:192
	v_or_b32_e32 v172, 0x4000, v98
	v_mov_b32_e32 v173, v99
	v_lshlrev_b64 v[174:175], 2, v[172:173]
	v_lshl_add_u64 v[154:155], s[12:13], 0, v[174:175]
	v_lshl_add_u64 v[162:163], s[82:83], 0, v[174:175]
	v_lshl_add_u64 v[154:155], v[154:155], 0, v[168:169]
	v_lshl_add_u64 v[162:163], v[162:163], 0, v[168:169]
	global_load_dwordx4 v[136:139], v[154:155], off
	global_load_dwordx4 v[140:143], v[154:155], off offset:64
	global_load_dwordx4 v[144:147], v[154:155], off offset:128
	global_load_dwordx4 v[148:151], v[154:155], off offset:192
	v_or_b32_e32 v172, 0x8000, v98
	v_mov_b32_e32 v173, v99
	v_lshlrev_b64 v[174:175], 2, v[172:173]
	v_lshl_add_u64 v[156:157], s[12:13], 0, v[174:175]
	v_lshl_add_u64 v[164:165], s[82:83], 0, v[174:175]
	v_lshl_add_u64 v[156:157], v[156:157], 0, v[168:169]
	v_lshl_add_u64 v[164:165], v[164:165], 0, v[168:169]
	global_load_dwordx4 v[22:25], v[156:157], off
	global_load_dwordx4 v[26:29], v[156:157], off offset:64
	global_load_dwordx4 v[42:45], v[156:157], off offset:128
	global_load_dwordx4 v[46:49], v[156:157], off offset:192
	v_or_b32_e32 v172, 0xc000, v98
	v_mov_b32_e32 v173, v99
	v_lshlrev_b64 v[174:175], 2, v[172:173]
	v_lshl_add_u64 v[158:159], s[12:13], 0, v[174:175]
	v_lshl_add_u64 v[166:167], s[82:83], 0, v[174:175]
	v_lshl_add_u64 v[158:159], v[158:159], 0, v[168:169]
	v_lshl_add_u64 v[166:167], v[166:167], 0, v[168:169]
	global_load_dwordx4 v[50:53], v[158:159], off
	global_load_dwordx4 v[54:57], v[158:159], off offset:64
	global_load_dwordx4 v[58:61], v[158:159], off offset:128
	global_load_dwordx4 v[70:73], v[158:159], off offset:192
	s_waitcnt vmcnt(15)
	v_pk_fma_f32 v[120:121], v[120:121], s[6:7], v[94:95] op_sel_hi:[1,0,1]
	v_pk_fma_f32 v[122:123], v[122:123], s[6:7], v[96:97] op_sel_hi:[1,0,1]
	s_waitcnt vmcnt(14)
	v_pk_fma_f32 v[124:125], v[124:125], s[6:7], v[90:91] op_sel_hi:[1,0,1]
	v_pk_fma_f32 v[126:127], v[126:127], s[6:7], v[92:93] op_sel_hi:[1,0,1]
	s_waitcnt vmcnt(13)
	v_pk_fma_f32 v[128:129], v[128:129], s[6:7], v[86:87] op_sel_hi:[1,0,1]
	v_pk_fma_f32 v[130:131], v[130:131], s[6:7], v[88:89] op_sel_hi:[1,0,1]
	s_waitcnt vmcnt(12)
	v_pk_fma_f32 v[132:133], v[132:133], s[6:7], v[82:83] op_sel_hi:[1,0,1]
	v_pk_fma_f32 v[134:135], v[134:135], s[6:7], v[84:85] op_sel_hi:[1,0,1]
	s_waitcnt vmcnt(11)
	v_pk_fma_f32 v[136:137], v[136:137], s[6:7], v[78:79] op_sel_hi:[1,0,1]
	v_pk_fma_f32 v[138:139], v[138:139], s[6:7], v[80:81] op_sel_hi:[1,0,1]
	s_waitcnt vmcnt(10)
	v_pk_fma_f32 v[140:141], v[140:141], s[6:7], v[74:75] op_sel_hi:[1,0,1]
	v_pk_fma_f32 v[142:143], v[142:143], s[6:7], v[76:77] op_sel_hi:[1,0,1]
	s_waitcnt vmcnt(9)
	v_pk_fma_f32 v[144:145], v[144:145], s[6:7], v[62:63] op_sel_hi:[1,0,1]
	v_pk_fma_f32 v[146:147], v[146:147], s[6:7], v[64:65] op_sel_hi:[1,0,1]
	s_waitcnt vmcnt(8)
	v_pk_fma_f32 v[148:149], v[148:149], s[6:7], v[30:31] op_sel_hi:[1,0,1]
	v_pk_fma_f32 v[150:151], v[150:151], s[6:7], v[32:33] op_sel_hi:[1,0,1]
	s_waitcnt vmcnt(7)
	v_pk_fma_f32 v[22:23], v[22:23], s[6:7], v[66:67] op_sel_hi:[1,0,1]
	v_pk_fma_f32 v[24:25], v[24:25], s[6:7], v[68:69] op_sel_hi:[1,0,1]
	s_waitcnt vmcnt(6)
	v_pk_fma_f32 v[26:27], v[26:27], s[6:7], v[38:39] op_sel_hi:[1,0,1]
	v_pk_fma_f32 v[28:29], v[28:29], s[6:7], v[40:41] op_sel_hi:[1,0,1]
	s_waitcnt vmcnt(5)
	v_pk_fma_f32 v[42:43], v[42:43], s[6:7], v[34:35] op_sel_hi:[1,0,1]
	v_pk_fma_f32 v[44:45], v[44:45], s[6:7], v[36:37] op_sel_hi:[1,0,1]
	s_waitcnt vmcnt(4)
	v_pk_fma_f32 v[46:47], v[46:47], s[6:7], v[18:19] op_sel_hi:[1,0,1]
	v_pk_fma_f32 v[48:49], v[48:49], s[6:7], v[20:21] op_sel_hi:[1,0,1]
	s_waitcnt vmcnt(3)
	v_pk_fma_f32 v[50:51], v[50:51], s[6:7], v[14:15] op_sel_hi:[1,0,1]
	v_pk_fma_f32 v[52:53], v[52:53], s[6:7], v[16:17] op_sel_hi:[1,0,1]
	s_waitcnt vmcnt(2)
	v_pk_fma_f32 v[54:55], v[54:55], s[6:7], v[10:11] op_sel_hi:[1,0,1]
	v_pk_fma_f32 v[56:57], v[56:57], s[6:7], v[12:13] op_sel_hi:[1,0,1]
	s_waitcnt vmcnt(1)
	v_pk_fma_f32 v[58:59], v[58:59], s[6:7], v[6:7] op_sel_hi:[1,0,1]
	v_pk_fma_f32 v[60:61], v[60:61], s[6:7], v[8:9] op_sel_hi:[1,0,1]
	s_waitcnt vmcnt(0)
	v_pk_fma_f32 v[70:71], v[70:71], s[6:7], v[2:3] op_sel_hi:[1,0,1]
	v_pk_fma_f32 v[72:73], v[72:73], s[6:7], v[4:5] op_sel_hi:[1,0,1]
	global_store_dwordx4 v[160:161], v[120:123], off
	global_store_dwordx4 v[160:161], v[124:127], off offset:64
	global_store_dwordx4 v[160:161], v[128:131], off offset:128
	global_store_dwordx4 v[160:161], v[132:135], off offset:192
	global_store_dwordx4 v[162:163], v[136:139], off
	global_store_dwordx4 v[162:163], v[140:143], off offset:64
	global_store_dwordx4 v[162:163], v[144:147], off offset:128
	global_store_dwordx4 v[162:163], v[148:151], off offset:192
	global_store_dwordx4 v[164:165], v[22:25], off
	global_store_dwordx4 v[164:165], v[26:29], off offset:64
	global_store_dwordx4 v[164:165], v[42:45], off offset:128
	global_store_dwordx4 v[164:165], v[46:49], off offset:192
	global_store_dwordx4 v[166:167], v[50:53], off
	global_store_dwordx4 v[166:167], v[54:57], off offset:64
	global_store_dwordx4 v[166:167], v[58:61], off offset:128
	global_store_dwordx4 v[166:167], v[70:73], off offset:192
	s_add_i32 s7, s7, s3
	s_cmpk_lt_u32 s7, 0x100
	s_cbranch_scc1 .LBB0_422

.Lglds2_14401:
	ds_read_b128 v[152:155], v112 offset:16384
	ds_read_b128 v[156:159], v112 offset:18432
	ds_read_b128 v[160:163], v110
	ds_read_b128 v[164:167], v110 offset:2048
	ds_read_b128 v[168:171], v112 offset:20480
	ds_read_b128 v[172:175], v113 offset:16384
	ds_read_b128 v[204:207], v110 offset:4096
	ds_read_b128 v[208:211], v111
	ds_read_b128 v[212:215], v116 offset:16384
	ds_read_b128 v[216:219], v116 offset:18432
	ds_read_b128 v[220:223], v114
	ds_read_b128 v[224:227], v114 offset:2048
	ds_read_b128 v[228:231], v116 offset:20480
	ds_read_b128 v[232:235], v117 offset:16384
	ds_read_b128 v[236:239], v114 offset:4096
	ds_read_b128 v[240:243], v115
	s_setprio 1
	s_waitcnt lgkmcnt(13)
	v_mfma_i32_16x16x64_i8 v[94:97], v[152:155], v[160:163], v[94:97]
	v_mfma_i32_16x16x64_i8 v[90:93], v[156:159], v[160:163], v[90:93]
	s_waitcnt lgkmcnt(11)
	v_mfma_i32_16x16x64_i8 v[86:89], v[168:171], v[160:163], v[86:89]
	s_waitcnt lgkmcnt(10)
	v_mfma_i32_16x16x64_i8 v[82:85], v[172:175], v[160:163], v[82:85]
	v_mfma_i32_16x16x64_i8 v[74:77], v[152:155], v[164:167], v[74:77]
	v_mfma_i32_16x16x64_i8 v[50:53], v[156:159], v[164:167], v[50:53]
	v_mfma_i32_16x16x64_i8 v[38:41], v[168:171], v[164:167], v[38:41]
	v_mfma_i32_16x16x64_i8 v[30:33], v[172:175], v[164:167], v[30:33]
	s_waitcnt lgkmcnt(9)
	v_mfma_i32_16x16x64_i8 v[34:37], v[152:155], v[204:207], v[34:37]
	v_mfma_i32_16x16x64_i8 v[26:29], v[156:159], v[204:207], v[26:29]
	v_mfma_i32_16x16x64_i8 v[22:25], v[168:171], v[204:207], v[22:25]
	v_mfma_i32_16x16x64_i8 v[18:21], v[172:175], v[204:207], v[18:21]
	s_waitcnt lgkmcnt(8)
	v_mfma_i32_16x16x64_i8 v[14:17], v[152:155], v[208:211], v[14:17]
	v_mfma_i32_16x16x64_i8 v[10:13], v[156:159], v[208:211], v[10:13]
	v_mfma_i32_16x16x64_i8 v[6:9], v[168:171], v[208:211], v[6:9]
	v_mfma_i32_16x16x64_i8 v[2:5], v[172:175], v[208:211], v[2:5]
	s_setprio 0
	s_waitcnt lgkmcnt(0)
	s_waitcnt vmcnt(0)
	s_barrier
	s_add_i32 s4, s13, 0x80
	s_min_u32 s4, s4, 0x1c0
	s_lshl_b32 s4, s4, 1
	s_setprio 1
	v_mfma_i32_16x16x64_i8 v[94:97], v[212:215], v[220:223], v[94:97]
	s_add_u32 m0, s14, 0x0
	v_lshl_add_u64 v[200:201], v[184:185], 0, s[4:5]
	global_load_lds_dwordx4 v[200:201], off
	v_mfma_i32_16x16x64_i8 v[90:93], v[216:219], v[220:223], v[90:93]
	v_mfma_i32_16x16x64_i8 v[86:89], v[228:231], v[220:223], v[86:89]
	s_add_u32 m0, s14, 0x1000
	v_lshl_add_u64 v[202:203], v[186:187], 0, s[4:5]
	global_load_lds_dwordx4 v[202:203], off
	v_mfma_i32_16x16x64_i8 v[82:85], v[232:235], v[220:223], v[82:85]
	v_mfma_i32_16x16x64_i8 v[74:77], v[212:215], v[224:227], v[74:77]
	s_add_u32 m0, s14, 0x2000
	v_lshl_add_u64 v[200:201], v[188:189], 0, s[4:5]
	global_load_lds_dwordx4 v[200:201], off
	v_mfma_i32_16x16x64_i8 v[50:53], v[216:219], v[224:227], v[50:53]
	v_mfma_i32_16x16x64_i8 v[38:41], v[228:231], v[224:227], v[38:41]
	s_add_u32 m0, s14, 0x3000
	v_lshl_add_u64 v[202:203], v[190:191], 0, s[4:5]
	global_load_lds_dwordx4 v[202:203], off
	v_mfma_i32_16x16x64_i8 v[30:33], v[232:235], v[224:227], v[30:33]
	v_mfma_i32_16x16x64_i8 v[34:37], v[212:215], v[236:239], v[34:37]
	s_add_u32 m0, s14, 0x4000
	v_lshl_add_u64 v[200:201], v[192:193], 0, s[4:5]
	global_load_lds_dwordx4 v[200:201], off
	v_mfma_i32_16x16x64_i8 v[26:29], v[216:219], v[236:239], v[26:29]
	v_mfma_i32_16x16x64_i8 v[22:25], v[228:231], v[236:239], v[22:25]
	s_add_u32 m0, s14, 0x5000
	v_lshl_add_u64 v[202:203], v[194:195], 0, s[4:5]
	global_load_lds_dwordx4 v[202:203], off
	v_mfma_i32_16x16x64_i8 v[18:21], v[232:235], v[236:239], v[18:21]
	v_mfma_i32_16x16x64_i8 v[14:17], v[212:215], v[240:243], v[14:17]
	s_add_u32 m0, s14, 0x6000
	v_lshl_add_u64 v[200:201], v[196:197], 0, s[4:5]
	global_load_lds_dwordx4 v[200:201], off
	v_mfma_i32_16x16x64_i8 v[10:13], v[216:219], v[240:243], v[10:13]
	v_mfma_i32_16x16x64_i8 v[6:9], v[228:231], v[240:243], v[6:9]
	s_add_u32 m0, s14, 0x7000
	v_lshl_add_u64 v[202:203], v[198:199], 0, s[4:5]
	global_load_lds_dwordx4 v[202:203], off
	v_mfma_i32_16x16x64_i8 v[2:5], v[232:235], v[240:243], v[2:5]
	s_setprio 0
	ds_read_b128 v[152:155], v112 offset:49152
	ds_read_b128 v[156:159], v112 offset:51200
	ds_read_b128 v[160:163], v110 offset:32768
	ds_read_b128 v[164:167], v110 offset:34816
	ds_read_b128 v[168:171], v112 offset:53248
	ds_read_b128 v[172:175], v113 offset:49152
	ds_read_b128 v[204:207], v110 offset:36864
	ds_read_b128 v[208:211], v111 offset:32768
	ds_read_b128 v[212:215], v116 offset:49152
	ds_read_b128 v[216:219], v116 offset:51200
	ds_read_b128 v[220:223], v114 offset:32768
	ds_read_b128 v[224:227], v114 offset:34816
	ds_read_b128 v[228:231], v116 offset:53248
	ds_read_b128 v[232:235], v117 offset:49152
	ds_read_b128 v[236:239], v114 offset:36864
	ds_read_b128 v[240:243], v115 offset:32768
	s_setprio 1
	s_waitcnt lgkmcnt(13)
	v_mfma_i32_16x16x64_i8 v[94:97], v[152:155], v[160:163], v[94:97]
	v_mfma_i32_16x16x64_i8 v[90:93], v[156:159], v[160:163], v[90:93]
	s_waitcnt lgkmcnt(11)
	v_mfma_i32_16x16x64_i8 v[86:89], v[168:171], v[160:163], v[86:89]
	s_waitcnt lgkmcnt(10)
	v_mfma_i32_16x16x64_i8 v[82:85], v[172:175], v[160:163], v[82:85]
	v_mfma_i32_16x16x64_i8 v[74:77], v[152:155], v[164:167], v[74:77]
	v_mfma_i32_16x16x64_i8 v[50:53], v[156:159], v[164:167], v[50:53]
	v_mfma_i32_16x16x64_i8 v[38:41], v[168:171], v[164:167], v[38:41]
	v_mfma_i32_16x16x64_i8 v[30:33], v[172:175], v[164:167], v[30:33]
	s_waitcnt lgkmcnt(9)
	v_mfma_i32_16x16x64_i8 v[34:37], v[152:155], v[204:207], v[34:37]
	v_mfma_i32_16x16x64_i8 v[26:29], v[156:159], v[204:207], v[26:29]
	v_mfma_i32_16x16x64_i8 v[22:25], v[168:171], v[204:207], v[22:25]
	v_mfma_i32_16x16x64_i8 v[18:21], v[172:175], v[204:207], v[18:21]
	s_waitcnt lgkmcnt(8)
	v_mfma_i32_16x16x64_i8 v[14:17], v[152:155], v[208:211], v[14:17]
	v_mfma_i32_16x16x64_i8 v[10:13], v[156:159], v[208:211], v[10:13]
	v_mfma_i32_16x16x64_i8 v[6:9], v[168:171], v[208:211], v[6:9]
	v_mfma_i32_16x16x64_i8 v[2:5], v[172:175], v[208:211], v[2:5]
	s_setprio 0
	s_waitcnt lgkmcnt(0)
	s_waitcnt vmcnt(0)
	s_barrier
	s_add_i32 s4, s13, 0xc0
	s_min_u32 s4, s4, 0x1c0
	s_lshl_b32 s4, s4, 1
	s_setprio 1
	v_mfma_i32_16x16x64_i8 v[94:97], v[212:215], v[220:223], v[94:97]
	s_add_u32 m0, s14, 0x8000
	v_lshl_add_u64 v[200:201], v[184:185], 0, s[4:5]
	global_load_lds_dwordx4 v[200:201], off
	v_mfma_i32_16x16x64_i8 v[90:93], v[216:219], v[220:223], v[90:93]
	v_mfma_i32_16x16x64_i8 v[86:89], v[228:231], v[220:223], v[86:89]
	s_add_u32 m0, s14, 0x9000
	v_lshl_add_u64 v[202:203], v[186:187], 0, s[4:5]
	global_load_lds_dwordx4 v[202:203], off
	v_mfma_i32_16x16x64_i8 v[82:85], v[232:235], v[220:223], v[82:85]
	v_mfma_i32_16x16x64_i8 v[74:77], v[212:215], v[224:227], v[74:77]
	s_add_u32 m0, s14, 0xa000
	v_lshl_add_u64 v[200:201], v[188:189], 0, s[4:5]
	global_load_lds_dwordx4 v[200:201], off
	v_mfma_i32_16x16x64_i8 v[50:53], v[216:219], v[224:227], v[50:53]
	v_mfma_i32_16x16x64_i8 v[38:41], v[228:231], v[224:227], v[38:41]
	s_add_u32 m0, s14, 0xb000
	v_lshl_add_u64 v[202:203], v[190:191], 0, s[4:5]
	global_load_lds_dwordx4 v[202:203], off
	v_mfma_i32_16x16x64_i8 v[30:33], v[232:235], v[224:227], v[30:33]
	v_mfma_i32_16x16x64_i8 v[34:37], v[212:215], v[236:239], v[34:37]
	s_add_u32 m0, s14, 0xc000
	v_lshl_add_u64 v[200:201], v[192:193], 0, s[4:5]
	global_load_lds_dwordx4 v[200:201], off
	v_mfma_i32_16x16x64_i8 v[26:29], v[216:219], v[236:239], v[26:29]
	v_mfma_i32_16x16x64_i8 v[22:25], v[228:231], v[236:239], v[22:25]
	s_add_u32 m0, s14, 0xd000
	v_lshl_add_u64 v[202:203], v[194:195], 0, s[4:5]
	global_load_lds_dwordx4 v[202:203], off
	v_mfma_i32_16x16x64_i8 v[18:21], v[232:235], v[236:239], v[18:21]
	v_mfma_i32_16x16x64_i8 v[14:17], v[212:215], v[240:243], v[14:17]
	s_add_u32 m0, s14, 0xe000
	v_lshl_add_u64 v[200:201], v[196:197], 0, s[4:5]
	global_load_lds_dwordx4 v[200:201], off
	v_mfma_i32_16x16x64_i8 v[10:13], v[216:219], v[240:243], v[10:13]
	v_mfma_i32_16x16x64_i8 v[6:9], v[228:231], v[240:243], v[6:9]
	s_add_u32 m0, s14, 0xf000
	v_lshl_add_u64 v[202:203], v[198:199], 0, s[4:5]
	global_load_lds_dwordx4 v[202:203], off
	v_mfma_i32_16x16x64_i8 v[2:5], v[232:235], v[240:243], v[2:5]
	s_setprio 0
	s_add_i32 s13, s13, 0x80
	s_add_i32 s12, s12, 2
	s_cmp_lt_u32 s12, 6
	s_cbranch_scc1 .Lglds2_14401
	ds_read_b128 v[152:155], v112 offset:16384
	ds_read_b128 v[156:159], v112 offset:18432
	ds_read_b128 v[160:163], v110
	ds_read_b128 v[164:167], v110 offset:2048
	ds_read_b128 v[168:171], v112 offset:20480
	ds_read_b128 v[172:175], v113 offset:16384
	ds_read_b128 v[204:207], v110 offset:4096
	ds_read_b128 v[208:211], v111
	ds_read_b128 v[212:215], v116 offset:16384
	ds_read_b128 v[216:219], v116 offset:18432
	ds_read_b128 v[220:223], v114
	ds_read_b128 v[224:227], v114 offset:2048
	ds_read_b128 v[228:231], v116 offset:20480
	ds_read_b128 v[232:235], v117 offset:16384
	ds_read_b128 v[236:239], v114 offset:4096
	ds_read_b128 v[240:243], v115
	s_setprio 1
	s_waitcnt lgkmcnt(13)
	v_mfma_i32_16x16x64_i8 v[94:97], v[152:155], v[160:163], v[94:97]
	v_mfma_i32_16x16x64_i8 v[90:93], v[156:159], v[160:163], v[90:93]
	s_waitcnt lgkmcnt(11)
	v_mfma_i32_16x16x64_i8 v[86:89], v[168:171], v[160:163], v[86:89]
	s_waitcnt lgkmcnt(10)
	v_mfma_i32_16x16x64_i8 v[82:85], v[172:175], v[160:163], v[82:85]
	v_mfma_i32_16x16x64_i8 v[74:77], v[152:155], v[164:167], v[74:77]
	v_mfma_i32_16x16x64_i8 v[50:53], v[156:159], v[164:167], v[50:53]
	v_mfma_i32_16x16x64_i8 v[38:41], v[168:171], v[164:167], v[38:41]
	v_mfma_i32_16x16x64_i8 v[30:33], v[172:175], v[164:167], v[30:33]
	s_waitcnt lgkmcnt(9)
	v_mfma_i32_16x16x64_i8 v[34:37], v[152:155], v[204:207], v[34:37]
	v_mfma_i32_16x16x64_i8 v[26:29], v[156:159], v[204:207], v[26:29]
	v_mfma_i32_16x16x64_i8 v[22:25], v[168:171], v[204:207], v[22:25]
	v_mfma_i32_16x16x64_i8 v[18:21], v[172:175], v[204:207], v[18:21]
	s_waitcnt lgkmcnt(8)
	v_mfma_i32_16x16x64_i8 v[14:17], v[152:155], v[208:211], v[14:17]
	v_mfma_i32_16x16x64_i8 v[10:13], v[156:159], v[208:211], v[10:13]
	v_mfma_i32_16x16x64_i8 v[6:9], v[168:171], v[208:211], v[6:9]
	v_mfma_i32_16x16x64_i8 v[2:5], v[172:175], v[208:211], v[2:5]
	s_setprio 0
	s_waitcnt lgkmcnt(0)
	s_waitcnt vmcnt(0)
	s_barrier
	s_setprio 1
	v_mfma_i32_16x16x64_i8 v[94:97], v[212:215], v[220:223], v[94:97]
	v_mfma_i32_16x16x64_i8 v[90:93], v[216:219], v[220:223], v[90:93]
	v_mfma_i32_16x16x64_i8 v[86:89], v[228:231], v[220:223], v[86:89]
	v_mfma_i32_16x16x64_i8 v[82:85], v[232:235], v[220:223], v[82:85]
	v_mfma_i32_16x16x64_i8 v[74:77], v[212:215], v[224:227], v[74:77]
	v_mfma_i32_16x16x64_i8 v[50:53], v[216:219], v[224:227], v[50:53]
	v_mfma_i32_16x16x64_i8 v[38:41], v[228:231], v[224:227], v[38:41]
	v_mfma_i32_16x16x64_i8 v[30:33], v[232:235], v[224:227], v[30:33]
	v_mfma_i32_16x16x64_i8 v[34:37], v[212:215], v[236:239], v[34:37]
	v_mfma_i32_16x16x64_i8 v[26:29], v[216:219], v[236:239], v[26:29]
	v_mfma_i32_16x16x64_i8 v[22:25], v[228:231], v[236:239], v[22:25]
	v_mfma_i32_16x16x64_i8 v[18:21], v[232:235], v[236:239], v[18:21]
	v_mfma_i32_16x16x64_i8 v[14:17], v[212:215], v[240:243], v[14:17]
	v_mfma_i32_16x16x64_i8 v[10:13], v[216:219], v[240:243], v[10:13]
	v_mfma_i32_16x16x64_i8 v[6:9], v[228:231], v[240:243], v[6:9]
	v_mfma_i32_16x16x64_i8 v[2:5], v[232:235], v[240:243], v[2:5]
	s_setprio 0
	ds_read_b128 v[152:155], v112 offset:49152
	ds_read_b128 v[156:159], v112 offset:51200
	ds_read_b128 v[160:163], v110 offset:32768
	ds_read_b128 v[164:167], v110 offset:34816
	ds_read_b128 v[168:171], v112 offset:53248
	ds_read_b128 v[172:175], v113 offset:49152
	ds_read_b128 v[204:207], v110 offset:36864
	ds_read_b128 v[208:211], v111 offset:32768
	ds_read_b128 v[212:215], v116 offset:49152
	ds_read_b128 v[216:219], v116 offset:51200
	ds_read_b128 v[220:223], v114 offset:32768
	ds_read_b128 v[224:227], v114 offset:34816
	ds_read_b128 v[228:231], v116 offset:53248
	ds_read_b128 v[232:235], v117 offset:49152
	ds_read_b128 v[236:239], v114 offset:36864
	ds_read_b128 v[240:243], v115 offset:32768
	s_setprio 1
	s_waitcnt lgkmcnt(13)
	v_mfma_i32_16x16x64_i8 v[94:97], v[152:155], v[160:163], v[94:97]
	v_mfma_i32_16x16x64_i8 v[90:93], v[156:159], v[160:163], v[90:93]
	s_waitcnt lgkmcnt(11)
	v_mfma_i32_16x16x64_i8 v[86:89], v[168:171], v[160:163], v[86:89]
	s_waitcnt lgkmcnt(10)
	v_mfma_i32_16x16x64_i8 v[82:85], v[172:175], v[160:163], v[82:85]
	v_mfma_i32_16x16x64_i8 v[74:77], v[152:155], v[164:167], v[74:77]
	v_mfma_i32_16x16x64_i8 v[50:53], v[156:159], v[164:167], v[50:53]
	v_mfma_i32_16x16x64_i8 v[38:41], v[168:171], v[164:167], v[38:41]
	v_mfma_i32_16x16x64_i8 v[30:33], v[172:175], v[164:167], v[30:33]
	s_waitcnt lgkmcnt(9)
	v_mfma_i32_16x16x64_i8 v[34:37], v[152:155], v[204:207], v[34:37]
	v_mfma_i32_16x16x64_i8 v[26:29], v[156:159], v[204:207], v[26:29]
	v_mfma_i32_16x16x64_i8 v[22:25], v[168:171], v[204:207], v[22:25]
	v_mfma_i32_16x16x64_i8 v[18:21], v[172:175], v[204:207], v[18:21]
	s_waitcnt lgkmcnt(8)
	v_mfma_i32_16x16x64_i8 v[14:17], v[152:155], v[208:211], v[14:17]
	v_mfma_i32_16x16x64_i8 v[10:13], v[156:159], v[208:211], v[10:13]
	v_mfma_i32_16x16x64_i8 v[6:9], v[168:171], v[208:211], v[6:9]
	v_mfma_i32_16x16x64_i8 v[2:5], v[172:175], v[208:211], v[2:5]
	s_setprio 0
	s_waitcnt lgkmcnt(0)
	s_barrier
	s_setprio 1
	v_mfma_i32_16x16x64_i8 v[94:97], v[212:215], v[220:223], v[94:97]
	v_mfma_i32_16x16x64_i8 v[90:93], v[216:219], v[220:223], v[90:93]
	v_mfma_i32_16x16x64_i8 v[86:89], v[228:231], v[220:223], v[86:89]
	v_mfma_i32_16x16x64_i8 v[82:85], v[232:235], v[220:223], v[82:85]
	v_mfma_i32_16x16x64_i8 v[74:77], v[212:215], v[224:227], v[74:77]
	v_mfma_i32_16x16x64_i8 v[50:53], v[216:219], v[224:227], v[50:53]
	v_mfma_i32_16x16x64_i8 v[38:41], v[228:231], v[224:227], v[38:41]
	v_mfma_i32_16x16x64_i8 v[30:33], v[232:235], v[224:227], v[30:33]
	v_mfma_i32_16x16x64_i8 v[34:37], v[212:215], v[236:239], v[34:37]
	v_mfma_i32_16x16x64_i8 v[26:29], v[216:219], v[236:239], v[26:29]
	v_mfma_i32_16x16x64_i8 v[22:25], v[228:231], v[236:239], v[22:25]
	v_mfma_i32_16x16x64_i8 v[18:21], v[232:235], v[236:239], v[18:21]
	v_mfma_i32_16x16x64_i8 v[14:17], v[212:215], v[240:243], v[14:17]
	v_mfma_i32_16x16x64_i8 v[10:13], v[216:219], v[240:243], v[10:13]
	v_mfma_i32_16x16x64_i8 v[6:9], v[228:231], v[240:243], v[6:9]
	v_mfma_i32_16x16x64_i8 v[2:5], v[232:235], v[240:243], v[2:5]
	s_setprio 0
	s_waitcnt vmcnt(0)
	v_cvt_f32_i32_e32 v94, v94
	v_cvt_f32_i32_e32 v95, v95
	v_cvt_f32_i32_e32 v96, v96
	v_cvt_f32_i32_e32 v97, v97
	v_cvt_f32_i32_e32 v90, v90
	v_cvt_f32_i32_e32 v91, v91
	v_cvt_f32_i32_e32 v92, v92
	v_cvt_f32_i32_e32 v93, v93
	v_cvt_f32_i32_e32 v86, v86
	v_cvt_f32_i32_e32 v87, v87
	v_cvt_f32_i32_e32 v88, v88
	v_cvt_f32_i32_e32 v89, v89
	v_cvt_f32_i32_e32 v82, v82
	v_cvt_f32_i32_e32 v83, v83
	v_cvt_f32_i32_e32 v84, v84
	v_cvt_f32_i32_e32 v85, v85
	v_cvt_f32_i32_e32 v74, v74
	v_cvt_f32_i32_e32 v75, v75
	v_cvt_f32_i32_e32 v76, v76
	v_cvt_f32_i32_e32 v77, v77
	v_cvt_f32_i32_e32 v50, v50
	v_cvt_f32_i32_e32 v51, v51
	v_cvt_f32_i32_e32 v52, v52
	v_cvt_f32_i32_e32 v53, v53
	v_cvt_f32_i32_e32 v38, v38
	v_cvt_f32_i32_e32 v39, v39
	v_cvt_f32_i32_e32 v40, v40
	v_cvt_f32_i32_e32 v41, v41
	v_cvt_f32_i32_e32 v30, v30
	v_cvt_f32_i32_e32 v31, v31
	v_cvt_f32_i32_e32 v32, v32
	v_cvt_f32_i32_e32 v33, v33
	v_cvt_f32_i32_e32 v34, v34
	v_cvt_f32_i32_e32 v35, v35
	v_cvt_f32_i32_e32 v36, v36
	v_cvt_f32_i32_e32 v37, v37
	v_cvt_f32_i32_e32 v26, v26
	v_cvt_f32_i32_e32 v27, v27
	v_cvt_f32_i32_e32 v28, v28
	v_cvt_f32_i32_e32 v29, v29
	v_cvt_f32_i32_e32 v22, v22
	v_cvt_f32_i32_e32 v23, v23
	v_cvt_f32_i32_e32 v24, v24
	v_cvt_f32_i32_e32 v25, v25
	v_cvt_f32_i32_e32 v18, v18
	v_cvt_f32_i32_e32 v19, v19
	v_cvt_f32_i32_e32 v20, v20
	v_cvt_f32_i32_e32 v21, v21
	v_cvt_f32_i32_e32 v14, v14
	v_cvt_f32_i32_e32 v15, v15
	v_cvt_f32_i32_e32 v16, v16
	v_cvt_f32_i32_e32 v17, v17
	v_cvt_f32_i32_e32 v10, v10
	v_cvt_f32_i32_e32 v11, v11
	v_cvt_f32_i32_e32 v12, v12
	v_cvt_f32_i32_e32 v13, v13
	v_cvt_f32_i32_e32 v6, v6
	v_cvt_f32_i32_e32 v7, v7
	v_cvt_f32_i32_e32 v8, v8
	v_cvt_f32_i32_e32 v9, v9
	v_cvt_f32_i32_e32 v2, v2
	v_cvt_f32_i32_e32 v3, v3
	v_cvt_f32_i32_e32 v4, v4
	v_cvt_f32_i32_e32 v5, v5
	s_waitcnt vmcnt(0)
	v_add_u32_e32 v98, s10, v118
	v_or_b32_e32 v146, s11, v119
	v_lshl_add_u64 v[144:145], v[98:99], 2, s[68:69]
	v_lshlrev_b32_e32 v148, 2, v146
	global_load_dword v136, v[144:145], off
	global_load_dword v138, v[144:145], off offset:64
	global_load_dword v140, v[144:145], off offset:128
	global_load_dword v142, v[144:145], off offset:192
	global_load_dwordx4 v[120:123], v148, s[74:75]
	global_load_dwordx4 v[124:127], v148, s[74:75] offset:64
	global_load_dwordx4 v[128:131], v148, s[74:75] offset:128
	global_load_dwordx4 v[132:135], v148, s[74:75] offset:192
	v_lshlrev_b32_e32 v146, 1, v146
	v_mov_b32_e32 v147, v99
	v_lshlrev_b64 v[42:43], 12, v[98:99]
	v_lshl_add_u64 v[42:43], s[64:65], 0, v[42:43]
	v_lshl_add_u64 v[42:43], v[42:43], 0, v[146:147]
	v_or_b32_e32 v54, 16, v98
	v_mov_b32_e32 v55, v99
	v_lshlrev_b64 v[44:45], 12, v[54:55]
	v_lshl_add_u64 v[44:45], s[64:65], 0, v[44:45]
	v_lshl_add_u64 v[44:45], v[44:45], 0, v[146:147]
	v_or_b32_e32 v54, 32, v98
	v_mov_b32_e32 v55, v99
	v_lshlrev_b64 v[46:47], 12, v[54:55]
	v_lshl_add_u64 v[46:47], s[64:65], 0, v[46:47]
	v_lshl_add_u64 v[46:47], v[46:47], 0, v[146:147]
	v_or_b32_e32 v54, 48, v98
	v_mov_b32_e32 v55, v99
	v_lshlrev_b64 v[48:49], 12, v[54:55]
	v_lshl_add_u64 v[48:49], s[64:65], 0, v[48:49]
	v_lshl_add_u64 v[48:49], v[48:49], 0, v[146:147]
	s_waitcnt vmcnt(0)
	v_pk_mul_f32 v[94:95], v[136:137], v[94:95] op_sel_hi:[0,1]
	v_pk_mul_f32 v[96:97], v[136:137], v[96:97] op_sel_hi:[0,1]
	v_pk_mul_f32 v[94:95], v[120:121], v[94:95]
	v_pk_mul_f32 v[96:97], v[96:97], v[122:123]
	v_cvt_pk_bf16_f32 v94, v94, v95
	v_cvt_pk_bf16_f32 v95, v96, v97
	global_store_dwordx2 v[42:43], v[94:95], off
	v_pk_mul_f32 v[90:91], v[136:137], v[90:91] op_sel_hi:[0,1]
	v_pk_mul_f32 v[92:93], v[136:137], v[92:93] op_sel_hi:[0,1]
	v_pk_mul_f32 v[90:91], v[124:125], v[90:91]
	v_pk_mul_f32 v[92:93], v[92:93], v[126:127]
	v_cvt_pk_bf16_f32 v90, v90, v91
	v_cvt_pk_bf16_f32 v91, v92, v93
	global_store_dwordx2 v[42:43], v[90:91], off offset:32
	v_pk_mul_f32 v[86:87], v[136:137], v[86:87] op_sel_hi:[0,1]
	v_pk_mul_f32 v[88:89], v[136:137], v[88:89] op_sel_hi:[0,1]
	v_pk_mul_f32 v[86:87], v[128:129], v[86:87]
	v_pk_mul_f32 v[88:89], v[88:89], v[130:131]
	v_cvt_pk_bf16_f32 v86, v86, v87
	v_cvt_pk_bf16_f32 v87, v88, v89
	global_store_dwordx2 v[42:43], v[86:87], off offset:64
	v_pk_mul_f32 v[82:83], v[136:137], v[82:83] op_sel_hi:[0,1]
	v_pk_mul_f32 v[84:85], v[136:137], v[84:85] op_sel_hi:[0,1]
	v_pk_mul_f32 v[82:83], v[132:133], v[82:83]
	v_pk_mul_f32 v[84:85], v[84:85], v[134:135]
	v_cvt_pk_bf16_f32 v82, v82, v83
	v_cvt_pk_bf16_f32 v83, v84, v85
	global_store_dwordx2 v[42:43], v[82:83], off offset:96
	v_pk_mul_f32 v[74:75], v[138:139], v[74:75] op_sel_hi:[0,1]
	v_pk_mul_f32 v[76:77], v[138:139], v[76:77] op_sel_hi:[0,1]
	v_pk_mul_f32 v[74:75], v[120:121], v[74:75]
	v_pk_mul_f32 v[76:77], v[76:77], v[122:123]
	v_cvt_pk_bf16_f32 v74, v74, v75
	v_cvt_pk_bf16_f32 v75, v76, v77
	global_store_dwordx2 v[44:45], v[74:75], off
	v_pk_mul_f32 v[50:51], v[138:139], v[50:51] op_sel_hi:[0,1]
	v_pk_mul_f32 v[52:53], v[138:139], v[52:53] op_sel_hi:[0,1]
	v_pk_mul_f32 v[50:51], v[124:125], v[50:51]
	v_pk_mul_f32 v[52:53], v[52:53], v[126:127]
	v_cvt_pk_bf16_f32 v50, v50, v51
	v_cvt_pk_bf16_f32 v51, v52, v53
	global_store_dwordx2 v[44:45], v[50:51], off offset:32
	v_pk_mul_f32 v[38:39], v[138:139], v[38:39] op_sel_hi:[0,1]
	v_pk_mul_f32 v[40:41], v[138:139], v[40:41] op_sel_hi:[0,1]
	v_pk_mul_f32 v[38:39], v[128:129], v[38:39]
	v_pk_mul_f32 v[40:41], v[40:41], v[130:131]
	v_cvt_pk_bf16_f32 v38, v38, v39
	v_cvt_pk_bf16_f32 v39, v40, v41
	global_store_dwordx2 v[44:45], v[38:39], off offset:64
	v_pk_mul_f32 v[30:31], v[138:139], v[30:31] op_sel_hi:[0,1]
	v_pk_mul_f32 v[32:33], v[138:139], v[32:33] op_sel_hi:[0,1]
	v_pk_mul_f32 v[30:31], v[132:133], v[30:31]
	v_pk_mul_f32 v[32:33], v[32:33], v[134:135]
	v_cvt_pk_bf16_f32 v30, v30, v31
	v_cvt_pk_bf16_f32 v31, v32, v33
	global_store_dwordx2 v[44:45], v[30:31], off offset:96
	v_pk_mul_f32 v[34:35], v[140:141], v[34:35] op_sel_hi:[0,1]
	v_pk_mul_f32 v[36:37], v[140:141], v[36:37] op_sel_hi:[0,1]
	v_pk_mul_f32 v[34:35], v[120:121], v[34:35]
	v_pk_mul_f32 v[36:37], v[36:37], v[122:123]
	v_cvt_pk_bf16_f32 v34, v34, v35
	v_cvt_pk_bf16_f32 v35, v36, v37
	global_store_dwordx2 v[46:47], v[34:35], off
	v_pk_mul_f32 v[26:27], v[140:141], v[26:27] op_sel_hi:[0,1]
	v_pk_mul_f32 v[28:29], v[140:141], v[28:29] op_sel_hi:[0,1]
	v_pk_mul_f32 v[26:27], v[124:125], v[26:27]
	v_pk_mul_f32 v[28:29], v[28:29], v[126:127]
	v_cvt_pk_bf16_f32 v26, v26, v27
	v_cvt_pk_bf16_f32 v27, v28, v29
	global_store_dwordx2 v[46:47], v[26:27], off offset:32
	v_pk_mul_f32 v[22:23], v[140:141], v[22:23] op_sel_hi:[0,1]
	v_pk_mul_f32 v[24:25], v[140:141], v[24:25] op_sel_hi:[0,1]
	v_pk_mul_f32 v[22:23], v[128:129], v[22:23]
	v_pk_mul_f32 v[24:25], v[24:25], v[130:131]
	v_cvt_pk_bf16_f32 v22, v22, v23
	v_cvt_pk_bf16_f32 v23, v24, v25
	global_store_dwordx2 v[46:47], v[22:23], off offset:64
	v_pk_mul_f32 v[18:19], v[140:141], v[18:19] op_sel_hi:[0,1]
	v_pk_mul_f32 v[20:21], v[140:141], v[20:21] op_sel_hi:[0,1]
	v_pk_mul_f32 v[18:19], v[132:133], v[18:19]
	v_pk_mul_f32 v[20:21], v[20:21], v[134:135]
	v_cvt_pk_bf16_f32 v18, v18, v19
	v_cvt_pk_bf16_f32 v19, v20, v21
	global_store_dwordx2 v[46:47], v[18:19], off offset:96
	v_pk_mul_f32 v[14:15], v[142:143], v[14:15] op_sel_hi:[0,1]
	v_pk_mul_f32 v[16:17], v[142:143], v[16:17] op_sel_hi:[0,1]
	v_pk_mul_f32 v[14:15], v[120:121], v[14:15]
	v_pk_mul_f32 v[16:17], v[16:17], v[122:123]
	v_cvt_pk_bf16_f32 v14, v14, v15
	v_cvt_pk_bf16_f32 v15, v16, v17
	global_store_dwordx2 v[48:49], v[14:15], off
	v_pk_mul_f32 v[10:11], v[142:143], v[10:11] op_sel_hi:[0,1]
	v_pk_mul_f32 v[12:13], v[142:143], v[12:13] op_sel_hi:[0,1]
	v_pk_mul_f32 v[10:11], v[124:125], v[10:11]
	v_pk_mul_f32 v[12:13], v[12:13], v[126:127]
	v_cvt_pk_bf16_f32 v10, v10, v11
	v_cvt_pk_bf16_f32 v11, v12, v13
	global_store_dwordx2 v[48:49], v[10:11], off offset:32
	v_pk_mul_f32 v[6:7], v[142:143], v[6:7] op_sel_hi:[0,1]
	v_pk_mul_f32 v[8:9], v[142:143], v[8:9] op_sel_hi:[0,1]
	v_pk_mul_f32 v[6:7], v[128:129], v[6:7]
	v_pk_mul_f32 v[8:9], v[8:9], v[130:131]
	v_cvt_pk_bf16_f32 v6, v6, v7
	v_cvt_pk_bf16_f32 v7, v8, v9
	global_store_dwordx2 v[48:49], v[6:7], off offset:64
	v_pk_mul_f32 v[2:3], v[142:143], v[2:3] op_sel_hi:[0,1]
	v_pk_mul_f32 v[4:5], v[142:143], v[4:5] op_sel_hi:[0,1]
	v_pk_mul_f32 v[2:3], v[132:133], v[2:3]
	v_pk_mul_f32 v[4:5], v[4:5], v[134:135]
	v_cvt_pk_bf16_f32 v2, v2, v3
	v_cvt_pk_bf16_f32 v3, v4, v5
	global_store_dwordx2 v[48:49], v[2:3], off offset:96
	s_add_i32 s6, s6, s3
	s_cmpk_lt_u32 s6, 0x200
	s_cbranch_scc1 .LBB0_518

.Lglds2_22142:
	ds_read_b128 v[152:155], v112 offset:16384
	ds_read_b128 v[156:159], v112 offset:18432
	ds_read_b128 v[160:163], v110
	ds_read_b128 v[164:167], v110 offset:2048
	ds_read_b128 v[168:171], v112 offset:20480
	ds_read_b128 v[172:175], v113 offset:16384
	ds_read_b128 v[208:211], v110 offset:4096
	ds_read_b128 v[212:215], v111
	ds_read_b128 v[216:219], v116 offset:16384
	ds_read_b128 v[220:223], v116 offset:18432
	ds_read_b128 v[224:227], v114
	ds_read_b128 v[228:231], v114 offset:2048
	ds_read_b128 v[232:235], v116 offset:20480
	ds_read_b128 v[236:239], v117 offset:16384
	ds_read_b128 v[240:243], v114 offset:4096
	ds_read_b128 v[244:247], v115
	s_setprio 1
	s_waitcnt lgkmcnt(13)
	v_mfma_f32_16x16x32_bf16 v[94:97], v[152:155], v[160:163], v[94:97]
	v_mfma_f32_16x16x32_bf16 v[90:93], v[156:159], v[160:163], v[90:93]
	s_waitcnt lgkmcnt(11)
	v_mfma_f32_16x16x32_bf16 v[86:89], v[168:171], v[160:163], v[86:89]
	s_waitcnt lgkmcnt(10)
	v_mfma_f32_16x16x32_bf16 v[82:85], v[172:175], v[160:163], v[82:85]
	v_mfma_f32_16x16x32_bf16 v[54:57], v[152:155], v[164:167], v[54:57]
	v_mfma_f32_16x16x32_bf16 v[42:45], v[156:159], v[164:167], v[42:45]
	v_mfma_f32_16x16x32_bf16 v[38:41], v[168:171], v[164:167], v[38:41]
	v_mfma_f32_16x16x32_bf16 v[34:37], v[172:175], v[164:167], v[34:37]
	s_waitcnt lgkmcnt(9)
	v_mfma_f32_16x16x32_bf16 v[78:81], v[152:155], v[208:211], v[78:81]
	v_mfma_f32_16x16x32_bf16 v[74:77], v[156:159], v[208:211], v[74:77]
	v_mfma_f32_16x16x32_bf16 v[70:73], v[168:171], v[208:211], v[70:73]
	v_mfma_f32_16x16x32_bf16 v[66:69], v[172:175], v[208:211], v[66:69]
	s_waitcnt lgkmcnt(8)
	v_mfma_f32_16x16x32_bf16 v[62:65], v[152:155], v[212:215], v[62:65]
	v_mfma_f32_16x16x32_bf16 v[58:61], v[156:159], v[212:215], v[58:61]
	v_mfma_f32_16x16x32_bf16 v[50:53], v[168:171], v[212:215], v[50:53]
	v_mfma_f32_16x16x32_bf16 v[46:49], v[172:175], v[212:215], v[46:49]
	s_setprio 0
	s_waitcnt lgkmcnt(0)
	s_waitcnt vmcnt(0)
	s_barrier
	s_add_i32 s4, s16, 0x80
	s_min_u32 s4, s4, 0x3c0
	s_lshl_b32 s4, s4, 1
	s_setprio 1
	v_mfma_f32_16x16x32_bf16 v[94:97], v[216:219], v[224:227], v[94:97]
	s_add_u32 m0, s17, 0x0
	v_lshl_add_u64 v[204:205], v[188:189], 0, s[4:5]
	global_load_lds_dwordx4 v[204:205], off
	v_mfma_f32_16x16x32_bf16 v[90:93], v[220:223], v[224:227], v[90:93]
	v_mfma_f32_16x16x32_bf16 v[86:89], v[232:235], v[224:227], v[86:89]
	s_add_u32 m0, s17, 0x1000
	v_lshl_add_u64 v[206:207], v[190:191], 0, s[4:5]
	global_load_lds_dwordx4 v[206:207], off
	v_mfma_f32_16x16x32_bf16 v[82:85], v[236:239], v[224:227], v[82:85]
	v_mfma_f32_16x16x32_bf16 v[54:57], v[216:219], v[228:231], v[54:57]
	s_add_u32 m0, s17, 0x2000
	v_lshl_add_u64 v[204:205], v[192:193], 0, s[4:5]
	global_load_lds_dwordx4 v[204:205], off
	v_mfma_f32_16x16x32_bf16 v[42:45], v[220:223], v[228:231], v[42:45]
	v_mfma_f32_16x16x32_bf16 v[38:41], v[232:235], v[228:231], v[38:41]
	s_add_u32 m0, s17, 0x3000
	v_lshl_add_u64 v[206:207], v[194:195], 0, s[4:5]
	global_load_lds_dwordx4 v[206:207], off
	v_mfma_f32_16x16x32_bf16 v[34:37], v[236:239], v[228:231], v[34:37]
	v_mfma_f32_16x16x32_bf16 v[78:81], v[216:219], v[240:243], v[78:81]
	s_add_u32 m0, s17, 0x4000
	v_lshl_add_u64 v[204:205], v[196:197], 0, s[4:5]
	global_load_lds_dwordx4 v[204:205], off
	v_mfma_f32_16x16x32_bf16 v[74:77], v[220:223], v[240:243], v[74:77]
	v_mfma_f32_16x16x32_bf16 v[70:73], v[232:235], v[240:243], v[70:73]
	s_add_u32 m0, s17, 0x5000
	v_lshl_add_u64 v[206:207], v[198:199], 0, s[4:5]
	global_load_lds_dwordx4 v[206:207], off
	v_mfma_f32_16x16x32_bf16 v[66:69], v[236:239], v[240:243], v[66:69]
	v_mfma_f32_16x16x32_bf16 v[62:65], v[216:219], v[244:247], v[62:65]
	s_add_u32 m0, s17, 0x6000
	v_lshl_add_u64 v[204:205], v[200:201], 0, s[4:5]
	global_load_lds_dwordx4 v[204:205], off
	v_mfma_f32_16x16x32_bf16 v[58:61], v[220:223], v[244:247], v[58:61]
	v_mfma_f32_16x16x32_bf16 v[50:53], v[232:235], v[244:247], v[50:53]
	s_add_u32 m0, s17, 0x7000
	v_lshl_add_u64 v[206:207], v[202:203], 0, s[4:5]
	global_load_lds_dwordx4 v[206:207], off
	v_mfma_f32_16x16x32_bf16 v[46:49], v[236:239], v[244:247], v[46:49]
	s_setprio 0
	ds_read_b128 v[152:155], v112 offset:49152
	ds_read_b128 v[156:159], v112 offset:51200
	ds_read_b128 v[160:163], v110 offset:32768
	ds_read_b128 v[164:167], v110 offset:34816
	ds_read_b128 v[168:171], v112 offset:53248
	ds_read_b128 v[172:175], v113 offset:49152
	ds_read_b128 v[208:211], v110 offset:36864
	ds_read_b128 v[212:215], v111 offset:32768
	ds_read_b128 v[216:219], v116 offset:49152
	ds_read_b128 v[220:223], v116 offset:51200
	ds_read_b128 v[224:227], v114 offset:32768
	ds_read_b128 v[228:231], v114 offset:34816
	ds_read_b128 v[232:235], v116 offset:53248
	ds_read_b128 v[236:239], v117 offset:49152
	ds_read_b128 v[240:243], v114 offset:36864
	ds_read_b128 v[244:247], v115 offset:32768
	s_setprio 1
	s_waitcnt lgkmcnt(13)
	v_mfma_f32_16x16x32_bf16 v[94:97], v[152:155], v[160:163], v[94:97]
	v_mfma_f32_16x16x32_bf16 v[90:93], v[156:159], v[160:163], v[90:93]
	s_waitcnt lgkmcnt(11)
	v_mfma_f32_16x16x32_bf16 v[86:89], v[168:171], v[160:163], v[86:89]
	s_waitcnt lgkmcnt(10)
	v_mfma_f32_16x16x32_bf16 v[82:85], v[172:175], v[160:163], v[82:85]
	v_mfma_f32_16x16x32_bf16 v[54:57], v[152:155], v[164:167], v[54:57]
	v_mfma_f32_16x16x32_bf16 v[42:45], v[156:159], v[164:167], v[42:45]
	v_mfma_f32_16x16x32_bf16 v[38:41], v[168:171], v[164:167], v[38:41]
	v_mfma_f32_16x16x32_bf16 v[34:37], v[172:175], v[164:167], v[34:37]
	s_waitcnt lgkmcnt(9)
	v_mfma_f32_16x16x32_bf16 v[78:81], v[152:155], v[208:211], v[78:81]
	v_mfma_f32_16x16x32_bf16 v[74:77], v[156:159], v[208:211], v[74:77]
	v_mfma_f32_16x16x32_bf16 v[70:73], v[168:171], v[208:211], v[70:73]
	v_mfma_f32_16x16x32_bf16 v[66:69], v[172:175], v[208:211], v[66:69]
	s_waitcnt lgkmcnt(8)
	v_mfma_f32_16x16x32_bf16 v[62:65], v[152:155], v[212:215], v[62:65]
	v_mfma_f32_16x16x32_bf16 v[58:61], v[156:159], v[212:215], v[58:61]
	v_mfma_f32_16x16x32_bf16 v[50:53], v[168:171], v[212:215], v[50:53]
	v_mfma_f32_16x16x32_bf16 v[46:49], v[172:175], v[212:215], v[46:49]
	s_setprio 0
	s_waitcnt lgkmcnt(0)
	s_waitcnt vmcnt(0)
	s_barrier
	s_add_i32 s4, s16, 0xc0
	s_min_u32 s4, s4, 0x3c0
	s_lshl_b32 s4, s4, 1
	s_setprio 1
	v_mfma_f32_16x16x32_bf16 v[94:97], v[216:219], v[224:227], v[94:97]
	s_add_u32 m0, s17, 0x8000
	v_lshl_add_u64 v[204:205], v[188:189], 0, s[4:5]
	global_load_lds_dwordx4 v[204:205], off
	v_mfma_f32_16x16x32_bf16 v[90:93], v[220:223], v[224:227], v[90:93]
	v_mfma_f32_16x16x32_bf16 v[86:89], v[232:235], v[224:227], v[86:89]
	s_add_u32 m0, s17, 0x9000
	v_lshl_add_u64 v[206:207], v[190:191], 0, s[4:5]
	global_load_lds_dwordx4 v[206:207], off
	v_mfma_f32_16x16x32_bf16 v[82:85], v[236:239], v[224:227], v[82:85]
	v_mfma_f32_16x16x32_bf16 v[54:57], v[216:219], v[228:231], v[54:57]
	s_add_u32 m0, s17, 0xa000
	v_lshl_add_u64 v[204:205], v[192:193], 0, s[4:5]
	global_load_lds_dwordx4 v[204:205], off
	v_mfma_f32_16x16x32_bf16 v[42:45], v[220:223], v[228:231], v[42:45]
	v_mfma_f32_16x16x32_bf16 v[38:41], v[232:235], v[228:231], v[38:41]
	s_add_u32 m0, s17, 0xb000
	v_lshl_add_u64 v[206:207], v[194:195], 0, s[4:5]
	global_load_lds_dwordx4 v[206:207], off
	v_mfma_f32_16x16x32_bf16 v[34:37], v[236:239], v[228:231], v[34:37]
	v_mfma_f32_16x16x32_bf16 v[78:81], v[216:219], v[240:243], v[78:81]
	s_add_u32 m0, s17, 0xc000
	v_lshl_add_u64 v[204:205], v[196:197], 0, s[4:5]
	global_load_lds_dwordx4 v[204:205], off
	v_mfma_f32_16x16x32_bf16 v[74:77], v[220:223], v[240:243], v[74:77]
	v_mfma_f32_16x16x32_bf16 v[70:73], v[232:235], v[240:243], v[70:73]
	s_add_u32 m0, s17, 0xd000
	v_lshl_add_u64 v[206:207], v[198:199], 0, s[4:5]
	global_load_lds_dwordx4 v[206:207], off
	v_mfma_f32_16x16x32_bf16 v[66:69], v[236:239], v[240:243], v[66:69]
	v_mfma_f32_16x16x32_bf16 v[62:65], v[216:219], v[244:247], v[62:65]
	s_add_u32 m0, s17, 0xe000
	v_lshl_add_u64 v[204:205], v[200:201], 0, s[4:5]
	global_load_lds_dwordx4 v[204:205], off
	v_mfma_f32_16x16x32_bf16 v[58:61], v[220:223], v[244:247], v[58:61]
	v_mfma_f32_16x16x32_bf16 v[50:53], v[232:235], v[244:247], v[50:53]
	s_add_u32 m0, s17, 0xf000
	v_lshl_add_u64 v[206:207], v[202:203], 0, s[4:5]
	global_load_lds_dwordx4 v[206:207], off
	v_mfma_f32_16x16x32_bf16 v[46:49], v[236:239], v[244:247], v[46:49]
	s_setprio 0
	s_add_i32 s16, s16, 0x80
	s_add_i32 s15, s15, 2
	s_cmp_lt_u32 s15, 14
	s_cbranch_scc1 .Lglds2_22142
	ds_read_b128 v[152:155], v112 offset:16384
	ds_read_b128 v[156:159], v112 offset:18432
	ds_read_b128 v[160:163], v110
	ds_read_b128 v[164:167], v110 offset:2048
	ds_read_b128 v[168:171], v112 offset:20480
	ds_read_b128 v[172:175], v113 offset:16384
	ds_read_b128 v[208:211], v110 offset:4096
	ds_read_b128 v[212:215], v111
	ds_read_b128 v[216:219], v116 offset:16384
	ds_read_b128 v[220:223], v116 offset:18432
	ds_read_b128 v[224:227], v114
	ds_read_b128 v[228:231], v114 offset:2048
	ds_read_b128 v[232:235], v116 offset:20480
	ds_read_b128 v[236:239], v117 offset:16384
	ds_read_b128 v[240:243], v114 offset:4096
	ds_read_b128 v[244:247], v115
	s_setprio 1
	s_waitcnt lgkmcnt(13)
	v_mfma_f32_16x16x32_bf16 v[94:97], v[152:155], v[160:163], v[94:97]
	v_mfma_f32_16x16x32_bf16 v[90:93], v[156:159], v[160:163], v[90:93]
	s_waitcnt lgkmcnt(11)
	v_mfma_f32_16x16x32_bf16 v[86:89], v[168:171], v[160:163], v[86:89]
	s_waitcnt lgkmcnt(10)
	v_mfma_f32_16x16x32_bf16 v[82:85], v[172:175], v[160:163], v[82:85]
	v_mfma_f32_16x16x32_bf16 v[54:57], v[152:155], v[164:167], v[54:57]
	v_mfma_f32_16x16x32_bf16 v[42:45], v[156:159], v[164:167], v[42:45]
	v_mfma_f32_16x16x32_bf16 v[38:41], v[168:171], v[164:167], v[38:41]
	v_mfma_f32_16x16x32_bf16 v[34:37], v[172:175], v[164:167], v[34:37]
	s_waitcnt lgkmcnt(9)
	v_mfma_f32_16x16x32_bf16 v[78:81], v[152:155], v[208:211], v[78:81]
	v_mfma_f32_16x16x32_bf16 v[74:77], v[156:159], v[208:211], v[74:77]
	v_mfma_f32_16x16x32_bf16 v[70:73], v[168:171], v[208:211], v[70:73]
	v_mfma_f32_16x16x32_bf16 v[66:69], v[172:175], v[208:211], v[66:69]
	s_waitcnt lgkmcnt(8)
	v_mfma_f32_16x16x32_bf16 v[62:65], v[152:155], v[212:215], v[62:65]
	v_mfma_f32_16x16x32_bf16 v[58:61], v[156:159], v[212:215], v[58:61]
	v_mfma_f32_16x16x32_bf16 v[50:53], v[168:171], v[212:215], v[50:53]
	v_mfma_f32_16x16x32_bf16 v[46:49], v[172:175], v[212:215], v[46:49]
	s_setprio 0
	s_waitcnt lgkmcnt(0)
	s_waitcnt vmcnt(0)
	s_barrier
	s_setprio 1
	v_mfma_f32_16x16x32_bf16 v[94:97], v[216:219], v[224:227], v[94:97]
	v_mfma_f32_16x16x32_bf16 v[90:93], v[220:223], v[224:227], v[90:93]
	v_mfma_f32_16x16x32_bf16 v[86:89], v[232:235], v[224:227], v[86:89]
	v_mfma_f32_16x16x32_bf16 v[82:85], v[236:239], v[224:227], v[82:85]
	v_mfma_f32_16x16x32_bf16 v[54:57], v[216:219], v[228:231], v[54:57]
	v_mfma_f32_16x16x32_bf16 v[42:45], v[220:223], v[228:231], v[42:45]
	v_mfma_f32_16x16x32_bf16 v[38:41], v[232:235], v[228:231], v[38:41]
	v_mfma_f32_16x16x32_bf16 v[34:37], v[236:239], v[228:231], v[34:37]
	v_mfma_f32_16x16x32_bf16 v[78:81], v[216:219], v[240:243], v[78:81]
	v_mfma_f32_16x16x32_bf16 v[74:77], v[220:223], v[240:243], v[74:77]
	v_mfma_f32_16x16x32_bf16 v[70:73], v[232:235], v[240:243], v[70:73]
	v_mfma_f32_16x16x32_bf16 v[66:69], v[236:239], v[240:243], v[66:69]
	v_mfma_f32_16x16x32_bf16 v[62:65], v[216:219], v[244:247], v[62:65]
	v_mfma_f32_16x16x32_bf16 v[58:61], v[220:223], v[244:247], v[58:61]
	v_mfma_f32_16x16x32_bf16 v[50:53], v[232:235], v[244:247], v[50:53]
	v_mfma_f32_16x16x32_bf16 v[46:49], v[236:239], v[244:247], v[46:49]
	s_setprio 0
	ds_read_b128 v[152:155], v112 offset:49152
	ds_read_b128 v[156:159], v112 offset:51200
	ds_read_b128 v[160:163], v110 offset:32768
	ds_read_b128 v[164:167], v110 offset:34816
	ds_read_b128 v[168:171], v112 offset:53248
	ds_read_b128 v[172:175], v113 offset:49152
	ds_read_b128 v[208:211], v110 offset:36864
	ds_read_b128 v[212:215], v111 offset:32768
	ds_read_b128 v[216:219], v116 offset:49152
	ds_read_b128 v[220:223], v116 offset:51200
	ds_read_b128 v[224:227], v114 offset:32768
	ds_read_b128 v[228:231], v114 offset:34816
	ds_read_b128 v[232:235], v116 offset:53248
	ds_read_b128 v[236:239], v117 offset:49152
	ds_read_b128 v[240:243], v114 offset:36864
	ds_read_b128 v[244:247], v115 offset:32768
	s_setprio 1
	s_waitcnt lgkmcnt(13)
	v_mfma_f32_16x16x32_bf16 v[94:97], v[152:155], v[160:163], v[94:97]
	v_mfma_f32_16x16x32_bf16 v[90:93], v[156:159], v[160:163], v[90:93]
	s_waitcnt lgkmcnt(11)
	v_mfma_f32_16x16x32_bf16 v[86:89], v[168:171], v[160:163], v[86:89]
	s_waitcnt lgkmcnt(10)
	v_mfma_f32_16x16x32_bf16 v[82:85], v[172:175], v[160:163], v[82:85]
	v_mfma_f32_16x16x32_bf16 v[54:57], v[152:155], v[164:167], v[54:57]
	v_mfma_f32_16x16x32_bf16 v[42:45], v[156:159], v[164:167], v[42:45]
	v_mfma_f32_16x16x32_bf16 v[38:41], v[168:171], v[164:167], v[38:41]
	v_mfma_f32_16x16x32_bf16 v[34:37], v[172:175], v[164:167], v[34:37]
	s_waitcnt lgkmcnt(9)
	v_mfma_f32_16x16x32_bf16 v[78:81], v[152:155], v[208:211], v[78:81]
	v_mfma_f32_16x16x32_bf16 v[74:77], v[156:159], v[208:211], v[74:77]
	v_mfma_f32_16x16x32_bf16 v[70:73], v[168:171], v[208:211], v[70:73]
	v_mfma_f32_16x16x32_bf16 v[66:69], v[172:175], v[208:211], v[66:69]
	s_waitcnt lgkmcnt(8)
	v_mfma_f32_16x16x32_bf16 v[62:65], v[152:155], v[212:215], v[62:65]
	v_mfma_f32_16x16x32_bf16 v[58:61], v[156:159], v[212:215], v[58:61]
	v_mfma_f32_16x16x32_bf16 v[50:53], v[168:171], v[212:215], v[50:53]
	v_mfma_f32_16x16x32_bf16 v[46:49], v[172:175], v[212:215], v[46:49]
	s_setprio 0
	s_waitcnt lgkmcnt(0)
	s_barrier
	s_setprio 1
	v_mfma_f32_16x16x32_bf16 v[94:97], v[216:219], v[224:227], v[94:97]
	v_mfma_f32_16x16x32_bf16 v[90:93], v[220:223], v[224:227], v[90:93]
	v_mfma_f32_16x16x32_bf16 v[86:89], v[232:235], v[224:227], v[86:89]
	v_mfma_f32_16x16x32_bf16 v[82:85], v[236:239], v[224:227], v[82:85]
	v_mfma_f32_16x16x32_bf16 v[54:57], v[216:219], v[228:231], v[54:57]
	v_mfma_f32_16x16x32_bf16 v[42:45], v[220:223], v[228:231], v[42:45]
	v_mfma_f32_16x16x32_bf16 v[38:41], v[232:235], v[228:231], v[38:41]
	v_mfma_f32_16x16x32_bf16 v[34:37], v[236:239], v[228:231], v[34:37]
	v_mfma_f32_16x16x32_bf16 v[78:81], v[216:219], v[240:243], v[78:81]
	v_mfma_f32_16x16x32_bf16 v[74:77], v[220:223], v[240:243], v[74:77]
	v_mfma_f32_16x16x32_bf16 v[70:73], v[232:235], v[240:243], v[70:73]
	v_mfma_f32_16x16x32_bf16 v[66:69], v[236:239], v[240:243], v[66:69]
	v_mfma_f32_16x16x32_bf16 v[62:65], v[216:219], v[244:247], v[62:65]
	v_mfma_f32_16x16x32_bf16 v[58:61], v[220:223], v[244:247], v[58:61]
	v_mfma_f32_16x16x32_bf16 v[50:53], v[232:235], v[244:247], v[50:53]
	v_mfma_f32_16x16x32_bf16 v[46:49], v[236:239], v[244:247], v[46:49]
	s_setprio 0
	s_waitcnt vmcnt(0)
	s_waitcnt vmcnt(7)
	v_or_b32_e32 v2, s14, v119
	s_waitcnt vmcnt(5)
	v_add_u32_e32 v10, s13, v118
	v_mov_b64_e32 v[4:5], s[64:65]
	v_ashrrev_i32_e32 v3, 31, v2
	v_mad_i64_i32 v[6:7], s[14:15], v10, s12, v[4:5]
	v_lshlrev_b64 v[2:3], 1, v[2:3]
	v_lshl_add_u64 v[6:7], v[6:7], 0, v[2:3]
	v_cvt_pk_bf16_f32 v8, v94, v95
	v_cvt_pk_bf16_f32 v9, v96, v97
	global_store_dwordx2 v[6:7], v[8:9], off
	v_cvt_pk_bf16_f32 v8, v90, v91
	v_cvt_pk_bf16_f32 v9, v92, v93
	global_store_dwordx2 v[6:7], v[8:9], off offset:32
	v_cvt_pk_bf16_f32 v8, v86, v87
	v_cvt_pk_bf16_f32 v9, v88, v89
	global_store_dwordx2 v[6:7], v[8:9], off offset:64
	v_cvt_pk_bf16_f32 v8, v82, v83
	v_cvt_pk_bf16_f32 v9, v84, v85
	global_store_dwordx2 v[6:7], v[8:9], off offset:96
	v_or_b32_e32 v6, 16, v10
	v_mad_i64_i32 v[6:7], s[14:15], v6, s12, v[4:5]
	v_lshl_add_u64 v[6:7], v[6:7], 0, v[2:3]
	v_cvt_pk_bf16_f32 v8, v54, v55
	v_cvt_pk_bf16_f32 v9, v56, v57
	global_store_dwordx2 v[6:7], v[8:9], off
	v_cvt_pk_bf16_f32 v8, v42, v43
	v_cvt_pk_bf16_f32 v9, v44, v45
	global_store_dwordx2 v[6:7], v[8:9], off offset:32
	v_cvt_pk_bf16_f32 v8, v38, v39
	v_cvt_pk_bf16_f32 v9, v40, v41
	global_store_dwordx2 v[6:7], v[8:9], off offset:64
	v_cvt_pk_bf16_f32 v8, v34, v35
	v_cvt_pk_bf16_f32 v9, v36, v37
	global_store_dwordx2 v[6:7], v[8:9], off offset:96
	v_or_b32_e32 v6, 32, v10
	v_mad_i64_i32 v[6:7], s[14:15], v6, s12, v[4:5]
	v_lshl_add_u64 v[6:7], v[6:7], 0, v[2:3]
	v_cvt_pk_bf16_f32 v8, v78, v79
	v_cvt_pk_bf16_f32 v9, v80, v81
	global_store_dwordx2 v[6:7], v[8:9], off
	v_cvt_pk_bf16_f32 v8, v74, v75
	v_cvt_pk_bf16_f32 v9, v76, v77
	global_store_dwordx2 v[6:7], v[8:9], off offset:32
	v_cvt_pk_bf16_f32 v8, v70, v71
	v_cvt_pk_bf16_f32 v9, v72, v73
	global_store_dwordx2 v[6:7], v[8:9], off offset:64
	v_cvt_pk_bf16_f32 v8, v66, v67
	v_cvt_pk_bf16_f32 v9, v68, v69
	global_store_dwordx2 v[6:7], v[8:9], off offset:96
	v_or_b32_e32 v6, 48, v10
	v_mad_i64_i32 v[4:5], s[14:15], v6, s12, v[4:5]
	v_lshl_add_u64 v[2:3], v[4:5], 0, v[2:3]
	v_cvt_pk_bf16_f32 v4, v62, v63
	v_cvt_pk_bf16_f32 v5, v64, v65
	global_store_dwordx2 v[2:3], v[4:5], off
	v_cvt_pk_bf16_f32 v4, v58, v59
	v_cvt_pk_bf16_f32 v5, v60, v61
	global_store_dwordx2 v[2:3], v[4:5], off offset:32
	v_cvt_pk_bf16_f32 v4, v50, v51
	v_cvt_pk_bf16_f32 v5, v52, v53
	s_add_i32 s3, s3, s2
	global_store_dwordx2 v[2:3], v[4:5], off offset:64
	v_cvt_pk_bf16_f32 v4, v46, v47
	v_cvt_pk_bf16_f32 v5, v48, v49
	s_cmpk_lt_u32 s3, 0x280
	global_store_dwordx2 v[2:3], v[4:5], off offset:96
	s_cbranch_scc1 .LBB0_664

.Lglds2_26323:
	ds_read_b128 v[152:155], v111 offset:16384
	ds_read_b128 v[156:159], v111 offset:18432
	ds_read_b128 v[160:163], v109
	ds_read_b128 v[164:167], v109 offset:2048
	ds_read_b128 v[168:171], v111 offset:20480
	ds_read_b128 v[172:175], v112 offset:16384
	ds_read_b128 v[208:211], v109 offset:4096
	ds_read_b128 v[212:215], v110
	ds_read_b128 v[216:219], v115 offset:16384
	ds_read_b128 v[220:223], v115 offset:18432
	ds_read_b128 v[224:227], v113
	ds_read_b128 v[228:231], v113 offset:2048
	ds_read_b128 v[232:235], v115 offset:20480
	ds_read_b128 v[236:239], v116 offset:16384
	ds_read_b128 v[240:243], v113 offset:4096
	ds_read_b128 v[244:247], v114
	s_setprio 1
	s_waitcnt lgkmcnt(13)
	v_mfma_f32_16x16x32_bf16 v[92:95], v[152:155], v[160:163], v[92:95]
	v_mfma_f32_16x16x32_bf16 v[88:91], v[156:159], v[160:163], v[88:91]
	s_waitcnt lgkmcnt(11)
	v_mfma_f32_16x16x32_bf16 v[84:87], v[168:171], v[160:163], v[84:87]
	s_waitcnt lgkmcnt(10)
	v_mfma_f32_16x16x32_bf16 v[80:83], v[172:175], v[160:163], v[80:83]
	v_mfma_f32_16x16x32_bf16 v[76:79], v[152:155], v[164:167], v[76:79]
	v_mfma_f32_16x16x32_bf16 v[72:75], v[156:159], v[164:167], v[72:75]
	v_mfma_f32_16x16x32_bf16 v[60:63], v[168:171], v[164:167], v[60:63]
	v_mfma_f32_16x16x32_bf16 v[28:31], v[172:175], v[164:167], v[28:31]
	s_waitcnt lgkmcnt(9)
	v_mfma_f32_16x16x32_bf16 v[64:67], v[152:155], v[208:211], v[64:67]
	v_mfma_f32_16x16x32_bf16 v[36:39], v[156:159], v[208:211], v[36:39]
	v_mfma_f32_16x16x32_bf16 v[32:35], v[168:171], v[208:211], v[32:35]
	v_mfma_f32_16x16x32_bf16 v[16:19], v[172:175], v[208:211], v[16:19]
	s_waitcnt lgkmcnt(8)
	v_mfma_f32_16x16x32_bf16 v[12:15], v[152:155], v[212:215], v[12:15]
	v_mfma_f32_16x16x32_bf16 v[8:11], v[156:159], v[212:215], v[8:11]
	v_mfma_f32_16x16x32_bf16 v[4:7], v[168:171], v[212:215], v[4:7]
	v_mfma_f32_16x16x32_bf16 v[0:3], v[172:175], v[212:215], v[0:3]
	s_setprio 0
	s_waitcnt lgkmcnt(0)
	s_waitcnt vmcnt(0)
	s_barrier
	s_add_i32 s4, s14, 0x80
	s_min_u32 s4, s4, 0x3c0
	s_lshl_b32 s4, s4, 1
	s_setprio 1
	v_mfma_f32_16x16x32_bf16 v[92:95], v[216:219], v[224:227], v[92:95]
	s_add_u32 m0, s15, 0x0
	v_lshl_add_u64 v[204:205], v[188:189], 0, s[4:5]
	global_load_lds_dwordx4 v[204:205], off
	v_mfma_f32_16x16x32_bf16 v[88:91], v[220:223], v[224:227], v[88:91]
	v_mfma_f32_16x16x32_bf16 v[84:87], v[232:235], v[224:227], v[84:87]
	s_add_u32 m0, s15, 0x1000
	v_lshl_add_u64 v[206:207], v[190:191], 0, s[4:5]
	global_load_lds_dwordx4 v[206:207], off
	v_mfma_f32_16x16x32_bf16 v[80:83], v[236:239], v[224:227], v[80:83]
	v_mfma_f32_16x16x32_bf16 v[76:79], v[216:219], v[228:231], v[76:79]
	s_add_u32 m0, s15, 0x2000
	v_lshl_add_u64 v[204:205], v[192:193], 0, s[4:5]
	global_load_lds_dwordx4 v[204:205], off
	v_mfma_f32_16x16x32_bf16 v[72:75], v[220:223], v[228:231], v[72:75]
	v_mfma_f32_16x16x32_bf16 v[60:63], v[232:235], v[228:231], v[60:63]
	s_add_u32 m0, s15, 0x3000
	v_lshl_add_u64 v[206:207], v[194:195], 0, s[4:5]
	global_load_lds_dwordx4 v[206:207], off
	v_mfma_f32_16x16x32_bf16 v[28:31], v[236:239], v[228:231], v[28:31]
	v_mfma_f32_16x16x32_bf16 v[64:67], v[216:219], v[240:243], v[64:67]
	s_add_u32 m0, s15, 0x4000
	v_lshl_add_u64 v[204:205], v[196:197], 0, s[4:5]
	global_load_lds_dwordx4 v[204:205], off
	v_mfma_f32_16x16x32_bf16 v[36:39], v[220:223], v[240:243], v[36:39]
	v_mfma_f32_16x16x32_bf16 v[32:35], v[232:235], v[240:243], v[32:35]
	s_add_u32 m0, s15, 0x5000
	v_lshl_add_u64 v[206:207], v[198:199], 0, s[4:5]
	global_load_lds_dwordx4 v[206:207], off
	v_mfma_f32_16x16x32_bf16 v[16:19], v[236:239], v[240:243], v[16:19]
	v_mfma_f32_16x16x32_bf16 v[12:15], v[216:219], v[244:247], v[12:15]
	s_add_u32 m0, s15, 0x6000
	v_lshl_add_u64 v[204:205], v[200:201], 0, s[4:5]
	global_load_lds_dwordx4 v[204:205], off
	v_mfma_f32_16x16x32_bf16 v[8:11], v[220:223], v[244:247], v[8:11]
	v_mfma_f32_16x16x32_bf16 v[4:7], v[232:235], v[244:247], v[4:7]
	s_add_u32 m0, s15, 0x7000
	v_lshl_add_u64 v[206:207], v[202:203], 0, s[4:5]
	global_load_lds_dwordx4 v[206:207], off
	v_mfma_f32_16x16x32_bf16 v[0:3], v[236:239], v[244:247], v[0:3]
	s_setprio 0
	ds_read_b128 v[152:155], v111 offset:49152
	ds_read_b128 v[156:159], v111 offset:51200
	ds_read_b128 v[160:163], v109 offset:32768
	ds_read_b128 v[164:167], v109 offset:34816
	ds_read_b128 v[168:171], v111 offset:53248
	ds_read_b128 v[172:175], v112 offset:49152
	ds_read_b128 v[208:211], v109 offset:36864
	ds_read_b128 v[212:215], v110 offset:32768
	ds_read_b128 v[216:219], v115 offset:49152
	ds_read_b128 v[220:223], v115 offset:51200
	ds_read_b128 v[224:227], v113 offset:32768
	ds_read_b128 v[228:231], v113 offset:34816
	ds_read_b128 v[232:235], v115 offset:53248
	ds_read_b128 v[236:239], v116 offset:49152
	ds_read_b128 v[240:243], v113 offset:36864
	ds_read_b128 v[244:247], v114 offset:32768
	s_setprio 1
	s_waitcnt lgkmcnt(13)
	v_mfma_f32_16x16x32_bf16 v[92:95], v[152:155], v[160:163], v[92:95]
	v_mfma_f32_16x16x32_bf16 v[88:91], v[156:159], v[160:163], v[88:91]
	s_waitcnt lgkmcnt(11)
	v_mfma_f32_16x16x32_bf16 v[84:87], v[168:171], v[160:163], v[84:87]
	s_waitcnt lgkmcnt(10)
	v_mfma_f32_16x16x32_bf16 v[80:83], v[172:175], v[160:163], v[80:83]
	v_mfma_f32_16x16x32_bf16 v[76:79], v[152:155], v[164:167], v[76:79]
	v_mfma_f32_16x16x32_bf16 v[72:75], v[156:159], v[164:167], v[72:75]
	v_mfma_f32_16x16x32_bf16 v[60:63], v[168:171], v[164:167], v[60:63]
	v_mfma_f32_16x16x32_bf16 v[28:31], v[172:175], v[164:167], v[28:31]
	s_waitcnt lgkmcnt(9)
	v_mfma_f32_16x16x32_bf16 v[64:67], v[152:155], v[208:211], v[64:67]
	v_mfma_f32_16x16x32_bf16 v[36:39], v[156:159], v[208:211], v[36:39]
	v_mfma_f32_16x16x32_bf16 v[32:35], v[168:171], v[208:211], v[32:35]
	v_mfma_f32_16x16x32_bf16 v[16:19], v[172:175], v[208:211], v[16:19]
	s_waitcnt lgkmcnt(8)
	v_mfma_f32_16x16x32_bf16 v[12:15], v[152:155], v[212:215], v[12:15]
	v_mfma_f32_16x16x32_bf16 v[8:11], v[156:159], v[212:215], v[8:11]
	v_mfma_f32_16x16x32_bf16 v[4:7], v[168:171], v[212:215], v[4:7]
	v_mfma_f32_16x16x32_bf16 v[0:3], v[172:175], v[212:215], v[0:3]
	s_setprio 0
	s_waitcnt lgkmcnt(0)
	s_waitcnt vmcnt(0)
	s_barrier
	s_add_i32 s4, s14, 0xc0
	s_min_u32 s4, s4, 0x3c0
	s_lshl_b32 s4, s4, 1
	s_setprio 1
	v_mfma_f32_16x16x32_bf16 v[92:95], v[216:219], v[224:227], v[92:95]
	s_add_u32 m0, s15, 0x8000
	v_lshl_add_u64 v[204:205], v[188:189], 0, s[4:5]
	global_load_lds_dwordx4 v[204:205], off
	v_mfma_f32_16x16x32_bf16 v[88:91], v[220:223], v[224:227], v[88:91]
	v_mfma_f32_16x16x32_bf16 v[84:87], v[232:235], v[224:227], v[84:87]
	s_add_u32 m0, s15, 0x9000
	v_lshl_add_u64 v[206:207], v[190:191], 0, s[4:5]
	global_load_lds_dwordx4 v[206:207], off
	v_mfma_f32_16x16x32_bf16 v[80:83], v[236:239], v[224:227], v[80:83]
	v_mfma_f32_16x16x32_bf16 v[76:79], v[216:219], v[228:231], v[76:79]
	s_add_u32 m0, s15, 0xa000
	v_lshl_add_u64 v[204:205], v[192:193], 0, s[4:5]
	global_load_lds_dwordx4 v[204:205], off
	v_mfma_f32_16x16x32_bf16 v[72:75], v[220:223], v[228:231], v[72:75]
	v_mfma_f32_16x16x32_bf16 v[60:63], v[232:235], v[228:231], v[60:63]
	s_add_u32 m0, s15, 0xb000
	v_lshl_add_u64 v[206:207], v[194:195], 0, s[4:5]
	global_load_lds_dwordx4 v[206:207], off
	v_mfma_f32_16x16x32_bf16 v[28:31], v[236:239], v[228:231], v[28:31]
	v_mfma_f32_16x16x32_bf16 v[64:67], v[216:219], v[240:243], v[64:67]
	s_add_u32 m0, s15, 0xc000
	v_lshl_add_u64 v[204:205], v[196:197], 0, s[4:5]
	global_load_lds_dwordx4 v[204:205], off
	v_mfma_f32_16x16x32_bf16 v[36:39], v[220:223], v[240:243], v[36:39]
	v_mfma_f32_16x16x32_bf16 v[32:35], v[232:235], v[240:243], v[32:35]
	s_add_u32 m0, s15, 0xd000
	v_lshl_add_u64 v[206:207], v[198:199], 0, s[4:5]
	global_load_lds_dwordx4 v[206:207], off
	v_mfma_f32_16x16x32_bf16 v[16:19], v[236:239], v[240:243], v[16:19]
	v_mfma_f32_16x16x32_bf16 v[12:15], v[216:219], v[244:247], v[12:15]
	s_add_u32 m0, s15, 0xe000
	v_lshl_add_u64 v[204:205], v[200:201], 0, s[4:5]
	global_load_lds_dwordx4 v[204:205], off
	v_mfma_f32_16x16x32_bf16 v[8:11], v[220:223], v[244:247], v[8:11]
	v_mfma_f32_16x16x32_bf16 v[4:7], v[232:235], v[244:247], v[4:7]
	s_add_u32 m0, s15, 0xf000
	v_lshl_add_u64 v[206:207], v[202:203], 0, s[4:5]
	global_load_lds_dwordx4 v[206:207], off
	v_mfma_f32_16x16x32_bf16 v[0:3], v[236:239], v[244:247], v[0:3]
	s_setprio 0
	s_add_i32 s14, s14, 0x80
	s_add_i32 s13, s13, 2
	s_cmp_lt_u32 s13, 14
	s_cbranch_scc1 .Lglds2_26323
	ds_read_b128 v[152:155], v111 offset:16384
	ds_read_b128 v[156:159], v111 offset:18432
	ds_read_b128 v[160:163], v109
	ds_read_b128 v[164:167], v109 offset:2048
	ds_read_b128 v[168:171], v111 offset:20480
	ds_read_b128 v[172:175], v112 offset:16384
	ds_read_b128 v[208:211], v109 offset:4096
	ds_read_b128 v[212:215], v110
	ds_read_b128 v[216:219], v115 offset:16384
	ds_read_b128 v[220:223], v115 offset:18432
	ds_read_b128 v[224:227], v113
	ds_read_b128 v[228:231], v113 offset:2048
	ds_read_b128 v[232:235], v115 offset:20480
	ds_read_b128 v[236:239], v116 offset:16384
	ds_read_b128 v[240:243], v113 offset:4096
	ds_read_b128 v[244:247], v114
	s_setprio 1
	s_waitcnt lgkmcnt(13)
	v_mfma_f32_16x16x32_bf16 v[92:95], v[152:155], v[160:163], v[92:95]
	v_mfma_f32_16x16x32_bf16 v[88:91], v[156:159], v[160:163], v[88:91]
	s_waitcnt lgkmcnt(11)
	v_mfma_f32_16x16x32_bf16 v[84:87], v[168:171], v[160:163], v[84:87]
	s_waitcnt lgkmcnt(10)
	v_mfma_f32_16x16x32_bf16 v[80:83], v[172:175], v[160:163], v[80:83]
	v_mfma_f32_16x16x32_bf16 v[76:79], v[152:155], v[164:167], v[76:79]
	v_mfma_f32_16x16x32_bf16 v[72:75], v[156:159], v[164:167], v[72:75]
	v_mfma_f32_16x16x32_bf16 v[60:63], v[168:171], v[164:167], v[60:63]
	v_mfma_f32_16x16x32_bf16 v[28:31], v[172:175], v[164:167], v[28:31]
	s_waitcnt lgkmcnt(9)
	v_mfma_f32_16x16x32_bf16 v[64:67], v[152:155], v[208:211], v[64:67]
	v_mfma_f32_16x16x32_bf16 v[36:39], v[156:159], v[208:211], v[36:39]
	v_mfma_f32_16x16x32_bf16 v[32:35], v[168:171], v[208:211], v[32:35]
	v_mfma_f32_16x16x32_bf16 v[16:19], v[172:175], v[208:211], v[16:19]
	s_waitcnt lgkmcnt(8)
	v_mfma_f32_16x16x32_bf16 v[12:15], v[152:155], v[212:215], v[12:15]
	v_mfma_f32_16x16x32_bf16 v[8:11], v[156:159], v[212:215], v[8:11]
	v_mfma_f32_16x16x32_bf16 v[4:7], v[168:171], v[212:215], v[4:7]
	v_mfma_f32_16x16x32_bf16 v[0:3], v[172:175], v[212:215], v[0:3]
	s_setprio 0
	s_waitcnt lgkmcnt(0)
	s_waitcnt vmcnt(0)
	s_barrier
	s_setprio 1
	v_mfma_f32_16x16x32_bf16 v[92:95], v[216:219], v[224:227], v[92:95]
	v_mfma_f32_16x16x32_bf16 v[88:91], v[220:223], v[224:227], v[88:91]
	v_mfma_f32_16x16x32_bf16 v[84:87], v[232:235], v[224:227], v[84:87]
	v_mfma_f32_16x16x32_bf16 v[80:83], v[236:239], v[224:227], v[80:83]
	v_mfma_f32_16x16x32_bf16 v[76:79], v[216:219], v[228:231], v[76:79]
	v_mfma_f32_16x16x32_bf16 v[72:75], v[220:223], v[228:231], v[72:75]
	v_mfma_f32_16x16x32_bf16 v[60:63], v[232:235], v[228:231], v[60:63]
	v_mfma_f32_16x16x32_bf16 v[28:31], v[236:239], v[228:231], v[28:31]
	v_mfma_f32_16x16x32_bf16 v[64:67], v[216:219], v[240:243], v[64:67]
	v_mfma_f32_16x16x32_bf16 v[36:39], v[220:223], v[240:243], v[36:39]
	v_mfma_f32_16x16x32_bf16 v[32:35], v[232:235], v[240:243], v[32:35]
	v_mfma_f32_16x16x32_bf16 v[16:19], v[236:239], v[240:243], v[16:19]
	v_mfma_f32_16x16x32_bf16 v[12:15], v[216:219], v[244:247], v[12:15]
	v_mfma_f32_16x16x32_bf16 v[8:11], v[220:223], v[244:247], v[8:11]
	v_mfma_f32_16x16x32_bf16 v[4:7], v[232:235], v[244:247], v[4:7]
	v_mfma_f32_16x16x32_bf16 v[0:3], v[236:239], v[244:247], v[0:3]
	s_setprio 0
	ds_read_b128 v[152:155], v111 offset:49152
	ds_read_b128 v[156:159], v111 offset:51200
	ds_read_b128 v[160:163], v109 offset:32768
	ds_read_b128 v[164:167], v109 offset:34816
	ds_read_b128 v[168:171], v111 offset:53248
	ds_read_b128 v[172:175], v112 offset:49152
	ds_read_b128 v[208:211], v109 offset:36864
	ds_read_b128 v[212:215], v110 offset:32768
	ds_read_b128 v[216:219], v115 offset:49152
	ds_read_b128 v[220:223], v115 offset:51200
	ds_read_b128 v[224:227], v113 offset:32768
	ds_read_b128 v[228:231], v113 offset:34816
	ds_read_b128 v[232:235], v115 offset:53248
	ds_read_b128 v[236:239], v116 offset:49152
	ds_read_b128 v[240:243], v113 offset:36864
	ds_read_b128 v[244:247], v114 offset:32768
	s_setprio 1
	s_waitcnt lgkmcnt(13)
	v_mfma_f32_16x16x32_bf16 v[92:95], v[152:155], v[160:163], v[92:95]
	v_mfma_f32_16x16x32_bf16 v[88:91], v[156:159], v[160:163], v[88:91]
	s_waitcnt lgkmcnt(11)
	v_mfma_f32_16x16x32_bf16 v[84:87], v[168:171], v[160:163], v[84:87]
	s_waitcnt lgkmcnt(10)
	v_mfma_f32_16x16x32_bf16 v[80:83], v[172:175], v[160:163], v[80:83]
	v_mfma_f32_16x16x32_bf16 v[76:79], v[152:155], v[164:167], v[76:79]
	v_mfma_f32_16x16x32_bf16 v[72:75], v[156:159], v[164:167], v[72:75]
	v_mfma_f32_16x16x32_bf16 v[60:63], v[168:171], v[164:167], v[60:63]
	v_mfma_f32_16x16x32_bf16 v[28:31], v[172:175], v[164:167], v[28:31]
	s_waitcnt lgkmcnt(9)
	v_mfma_f32_16x16x32_bf16 v[64:67], v[152:155], v[208:211], v[64:67]
	v_mfma_f32_16x16x32_bf16 v[36:39], v[156:159], v[208:211], v[36:39]
	v_mfma_f32_16x16x32_bf16 v[32:35], v[168:171], v[208:211], v[32:35]
	v_mfma_f32_16x16x32_bf16 v[16:19], v[172:175], v[208:211], v[16:19]
	s_waitcnt lgkmcnt(8)
	v_mfma_f32_16x16x32_bf16 v[12:15], v[152:155], v[212:215], v[12:15]
	v_mfma_f32_16x16x32_bf16 v[8:11], v[156:159], v[212:215], v[8:11]
	v_mfma_f32_16x16x32_bf16 v[4:7], v[168:171], v[212:215], v[4:7]
	v_mfma_f32_16x16x32_bf16 v[0:3], v[172:175], v[212:215], v[0:3]
	s_setprio 0
	s_waitcnt lgkmcnt(0)
	s_barrier
	s_setprio 1
	v_mfma_f32_16x16x32_bf16 v[92:95], v[216:219], v[224:227], v[92:95]
	v_mfma_f32_16x16x32_bf16 v[88:91], v[220:223], v[224:227], v[88:91]
	v_mfma_f32_16x16x32_bf16 v[84:87], v[232:235], v[224:227], v[84:87]
	v_mfma_f32_16x16x32_bf16 v[80:83], v[236:239], v[224:227], v[80:83]
	v_mfma_f32_16x16x32_bf16 v[76:79], v[216:219], v[228:231], v[76:79]
	v_mfma_f32_16x16x32_bf16 v[72:75], v[220:223], v[228:231], v[72:75]
	v_mfma_f32_16x16x32_bf16 v[60:63], v[232:235], v[228:231], v[60:63]
	v_mfma_f32_16x16x32_bf16 v[28:31], v[236:239], v[228:231], v[28:31]
	v_mfma_f32_16x16x32_bf16 v[64:67], v[216:219], v[240:243], v[64:67]
	v_mfma_f32_16x16x32_bf16 v[36:39], v[220:223], v[240:243], v[36:39]
	v_mfma_f32_16x16x32_bf16 v[32:35], v[232:235], v[240:243], v[32:35]
	v_mfma_f32_16x16x32_bf16 v[16:19], v[236:239], v[240:243], v[16:19]
	v_mfma_f32_16x16x32_bf16 v[12:15], v[216:219], v[244:247], v[12:15]
	v_mfma_f32_16x16x32_bf16 v[8:11], v[220:223], v[244:247], v[8:11]
	v_mfma_f32_16x16x32_bf16 v[4:7], v[232:235], v[244:247], v[4:7]
	v_mfma_f32_16x16x32_bf16 v[0:3], v[236:239], v[244:247], v[0:3]
	s_setprio 0
	s_waitcnt vmcnt(0)
	s_waitcnt vmcnt(0)
	v_or_b32_e32 v170, s12, v118
	v_add_lshl_u32 v96, v117, s11, 10
	v_readlane_b32 s12, v254, 24
	v_readlane_b32 s16, v254, 28
	v_readlane_b32 s17, v254, 29
	v_readlane_b32 s13, v254, 25
	v_readlane_b32 s14, v254, 26
	v_readlane_b32 s15, v254, 27
	v_readlane_b32 s18, v254, 30
	v_readlane_b32 s19, v254, 31
	v_readlane_b32 s20, v254, 32
	v_readlane_b32 s21, v254, 33
	v_readlane_b32 s22, v254, 34
	v_readlane_b32 s23, v254, 35
	v_readlane_b32 s24, v254, 36
	v_readlane_b32 s25, v254, 37
	v_readlane_b32 s26, v254, 38
	v_readlane_b32 s27, v254, 39
	v_lshlrev_b32_e32 v168, 2, v170
	v_mov_b32_e32 v169, v97
	v_lshlrev_b64 v[174:175], 2, v[96:97]
	v_lshl_add_u64 v[152:153], s[16:17], 0, v[174:175]
	v_lshl_add_u64 v[160:161], s[82:83], 0, v[174:175]
	v_lshl_add_u64 v[152:153], v[152:153], 0, v[168:169]
	v_lshl_add_u64 v[160:161], v[160:161], 0, v[168:169]
	global_load_dwordx4 v[120:123], v[152:153], off
	global_load_dwordx4 v[124:127], v[152:153], off offset:64
	global_load_dwordx4 v[128:131], v[152:153], off offset:128
	global_load_dwordx4 v[132:135], v[152:153], off offset:192
	v_or_b32_e32 v172, 0x4000, v96
	v_mov_b32_e32 v173, v97
	v_lshlrev_b64 v[174:175], 2, v[172:173]
	v_lshl_add_u64 v[154:155], s[16:17], 0, v[174:175]
	v_lshl_add_u64 v[162:163], s[82:83], 0, v[174:175]
	v_lshl_add_u64 v[154:155], v[154:155], 0, v[168:169]
	v_lshl_add_u64 v[162:163], v[162:163], 0, v[168:169]
	global_load_dwordx4 v[136:139], v[154:155], off
	global_load_dwordx4 v[140:143], v[154:155], off offset:64
	global_load_dwordx4 v[144:147], v[154:155], off offset:128
	global_load_dwordx4 v[148:151], v[154:155], off offset:192
	v_or_b32_e32 v172, 0x8000, v96
	v_mov_b32_e32 v173, v97
	v_lshlrev_b64 v[174:175], 2, v[172:173]
	v_lshl_add_u64 v[156:157], s[16:17], 0, v[174:175]
	v_lshl_add_u64 v[164:165], s[82:83], 0, v[174:175]
	v_lshl_add_u64 v[156:157], v[156:157], 0, v[168:169]
	v_lshl_add_u64 v[164:165], v[164:165], 0, v[168:169]
	global_load_dwordx4 v[20:23], v[156:157], off
	global_load_dwordx4 v[24:27], v[156:157], off offset:64
	global_load_dwordx4 v[40:43], v[156:157], off offset:128
	global_load_dwordx4 v[44:47], v[156:157], off offset:192
	v_or_b32_e32 v172, 0xc000, v96
	v_mov_b32_e32 v173, v97
	v_lshlrev_b64 v[174:175], 2, v[172:173]
	v_lshl_add_u64 v[158:159], s[16:17], 0, v[174:175]
	v_lshl_add_u64 v[166:167], s[82:83], 0, v[174:175]
	v_lshl_add_u64 v[158:159], v[158:159], 0, v[168:169]
	v_lshl_add_u64 v[166:167], v[166:167], 0, v[168:169]
	global_load_dwordx4 v[48:51], v[158:159], off
	global_load_dwordx4 v[52:55], v[158:159], off offset:64
	global_load_dwordx4 v[56:59], v[158:159], off offset:128
	global_load_dwordx4 v[68:71], v[158:159], off offset:192
	s_waitcnt vmcnt(15)
	v_pk_fma_f32 v[120:121], v[120:121], s[6:7], v[92:93] op_sel_hi:[1,0,1]
	v_pk_fma_f32 v[122:123], v[122:123], s[6:7], v[94:95] op_sel_hi:[1,0,1]
	s_waitcnt vmcnt(14)
	v_pk_fma_f32 v[124:125], v[124:125], s[6:7], v[88:89] op_sel_hi:[1,0,1]
	v_pk_fma_f32 v[126:127], v[126:127], s[6:7], v[90:91] op_sel_hi:[1,0,1]
	s_waitcnt vmcnt(13)
	v_pk_fma_f32 v[128:129], v[128:129], s[6:7], v[84:85] op_sel_hi:[1,0,1]
	v_pk_fma_f32 v[130:131], v[130:131], s[6:7], v[86:87] op_sel_hi:[1,0,1]
	s_waitcnt vmcnt(12)
	v_pk_fma_f32 v[132:133], v[132:133], s[6:7], v[80:81] op_sel_hi:[1,0,1]
	v_pk_fma_f32 v[134:135], v[134:135], s[6:7], v[82:83] op_sel_hi:[1,0,1]
	s_waitcnt vmcnt(11)
	v_pk_fma_f32 v[136:137], v[136:137], s[6:7], v[76:77] op_sel_hi:[1,0,1]
	v_pk_fma_f32 v[138:139], v[138:139], s[6:7], v[78:79] op_sel_hi:[1,0,1]
	s_waitcnt vmcnt(10)
	v_pk_fma_f32 v[140:141], v[140:141], s[6:7], v[72:73] op_sel_hi:[1,0,1]
	v_pk_fma_f32 v[142:143], v[142:143], s[6:7], v[74:75] op_sel_hi:[1,0,1]
	s_waitcnt vmcnt(9)
	v_pk_fma_f32 v[144:145], v[144:145], s[6:7], v[60:61] op_sel_hi:[1,0,1]
	v_pk_fma_f32 v[146:147], v[146:147], s[6:7], v[62:63] op_sel_hi:[1,0,1]
	s_waitcnt vmcnt(8)
	v_pk_fma_f32 v[148:149], v[148:149], s[6:7], v[28:29] op_sel_hi:[1,0,1]
	v_pk_fma_f32 v[150:151], v[150:151], s[6:7], v[30:31] op_sel_hi:[1,0,1]
	s_waitcnt vmcnt(7)
	v_pk_fma_f32 v[20:21], v[20:21], s[6:7], v[64:65] op_sel_hi:[1,0,1]
	v_pk_fma_f32 v[22:23], v[22:23], s[6:7], v[66:67] op_sel_hi:[1,0,1]
	s_waitcnt vmcnt(6)
	v_pk_fma_f32 v[24:25], v[24:25], s[6:7], v[36:37] op_sel_hi:[1,0,1]
	v_pk_fma_f32 v[26:27], v[26:27], s[6:7], v[38:39] op_sel_hi:[1,0,1]
	s_waitcnt vmcnt(5)
	v_pk_fma_f32 v[40:41], v[40:41], s[6:7], v[32:33] op_sel_hi:[1,0,1]
	v_pk_fma_f32 v[42:43], v[42:43], s[6:7], v[34:35] op_sel_hi:[1,0,1]
	s_waitcnt vmcnt(4)
	v_pk_fma_f32 v[44:45], v[44:45], s[6:7], v[16:17] op_sel_hi:[1,0,1]
	v_pk_fma_f32 v[46:47], v[46:47], s[6:7], v[18:19] op_sel_hi:[1,0,1]
	s_waitcnt vmcnt(3)
	v_pk_fma_f32 v[48:49], v[48:49], s[6:7], v[12:13] op_sel_hi:[1,0,1]
	v_pk_fma_f32 v[50:51], v[50:51], s[6:7], v[14:15] op_sel_hi:[1,0,1]
	s_waitcnt vmcnt(2)
	v_pk_fma_f32 v[52:53], v[52:53], s[6:7], v[8:9] op_sel_hi:[1,0,1]
	v_pk_fma_f32 v[54:55], v[54:55], s[6:7], v[10:11] op_sel_hi:[1,0,1]
	s_waitcnt vmcnt(1)
	v_pk_fma_f32 v[56:57], v[56:57], s[6:7], v[4:5] op_sel_hi:[1,0,1]
	v_pk_fma_f32 v[58:59], v[58:59], s[6:7], v[6:7] op_sel_hi:[1,0,1]
	s_waitcnt vmcnt(0)
	v_pk_fma_f32 v[68:69], v[68:69], s[6:7], v[0:1] op_sel_hi:[1,0,1]
	v_pk_fma_f32 v[70:71], v[70:71], s[6:7], v[2:3] op_sel_hi:[1,0,1]
	global_store_dwordx4 v[160:161], v[120:123], off
	global_store_dwordx4 v[160:161], v[124:127], off offset:64
	global_store_dwordx4 v[160:161], v[128:131], off offset:128
	global_store_dwordx4 v[160:161], v[132:135], off offset:192
	global_store_dwordx4 v[162:163], v[136:139], off
	global_store_dwordx4 v[162:163], v[140:143], off offset:64
	global_store_dwordx4 v[162:163], v[144:147], off offset:128
	global_store_dwordx4 v[162:163], v[148:151], off offset:192
	global_store_dwordx4 v[164:165], v[20:23], off
	global_store_dwordx4 v[164:165], v[24:27], off offset:64
	global_store_dwordx4 v[164:165], v[40:43], off offset:128
	global_store_dwordx4 v[164:165], v[44:47], off offset:192
	global_store_dwordx4 v[166:167], v[48:51], off
	global_store_dwordx4 v[166:167], v[52:55], off offset:64
	global_store_dwordx4 v[166:167], v[56:59], off offset:128
	global_store_dwordx4 v[166:167], v[68:71], off offset:192
	s_add_i32 s7, s7, s3
	s_cmpk_lt_u32 s7, 0x100
	s_cbranch_scc1 .LBB0_798

.Lglds2_28042:
	ds_read_b128 v[152:155], v111 offset:16384
	ds_read_b128 v[156:159], v111 offset:18432
	ds_read_b128 v[160:163], v109
	ds_read_b128 v[164:167], v109 offset:2048
	ds_read_b128 v[168:171], v111 offset:20480
	ds_read_b128 v[172:175], v112 offset:16384
	ds_read_b128 v[208:211], v109 offset:4096
	ds_read_b128 v[212:215], v110
	ds_read_b128 v[216:219], v115 offset:16384
	ds_read_b128 v[220:223], v115 offset:18432
	ds_read_b128 v[224:227], v113
	ds_read_b128 v[228:231], v113 offset:2048
	ds_read_b128 v[232:235], v115 offset:20480
	ds_read_b128 v[236:239], v116 offset:16384
	ds_read_b128 v[240:243], v113 offset:4096
	ds_read_b128 v[244:247], v114
	s_setprio 1
	s_waitcnt lgkmcnt(13)
	v_mfma_i32_16x16x64_i8 v[92:95], v[152:155], v[160:163], v[92:95]
	v_mfma_i32_16x16x64_i8 v[88:91], v[156:159], v[160:163], v[88:91]
	s_waitcnt lgkmcnt(11)
	v_mfma_i32_16x16x64_i8 v[84:87], v[168:171], v[160:163], v[84:87]
	s_waitcnt lgkmcnt(10)
	v_mfma_i32_16x16x64_i8 v[80:83], v[172:175], v[160:163], v[80:83]
	v_mfma_i32_16x16x64_i8 v[60:63], v[152:155], v[164:167], v[60:63]
	v_mfma_i32_16x16x64_i8 v[40:43], v[156:159], v[164:167], v[40:43]
	v_mfma_i32_16x16x64_i8 v[36:39], v[168:171], v[164:167], v[36:39]
	v_mfma_i32_16x16x64_i8 v[28:31], v[172:175], v[164:167], v[28:31]
	s_waitcnt lgkmcnt(9)
	v_mfma_i32_16x16x64_i8 v[32:35], v[152:155], v[208:211], v[32:35]
	v_mfma_i32_16x16x64_i8 v[24:27], v[156:159], v[208:211], v[24:27]
	v_mfma_i32_16x16x64_i8 v[20:23], v[168:171], v[208:211], v[20:23]
	v_mfma_i32_16x16x64_i8 v[16:19], v[172:175], v[208:211], v[16:19]
	s_waitcnt lgkmcnt(8)
	v_mfma_i32_16x16x64_i8 v[12:15], v[152:155], v[212:215], v[12:15]
	v_mfma_i32_16x16x64_i8 v[8:11], v[156:159], v[212:215], v[8:11]
	v_mfma_i32_16x16x64_i8 v[4:7], v[168:171], v[212:215], v[4:7]
	v_mfma_i32_16x16x64_i8 v[0:3], v[172:175], v[212:215], v[0:3]
	s_setprio 0
	s_waitcnt lgkmcnt(0)
	s_waitcnt vmcnt(0)
	s_barrier
	s_add_i32 s6, s15, 0x80
	s_min_u32 s6, s6, 0x1c0
	s_lshl_b32 s6, s6, 1
	s_setprio 1
	v_mfma_i32_16x16x64_i8 v[92:95], v[216:219], v[224:227], v[92:95]
	s_add_u32 m0, s16, 0x0
	v_lshl_add_u64 v[204:205], v[188:189], 0, s[6:7]
	global_load_lds_dwordx4 v[204:205], off
	v_mfma_i32_16x16x64_i8 v[88:91], v[220:223], v[224:227], v[88:91]
	v_mfma_i32_16x16x64_i8 v[84:87], v[232:235], v[224:227], v[84:87]
	s_add_u32 m0, s16, 0x1000
	v_lshl_add_u64 v[206:207], v[190:191], 0, s[6:7]
	global_load_lds_dwordx4 v[206:207], off
	v_mfma_i32_16x16x64_i8 v[80:83], v[236:239], v[224:227], v[80:83]
	v_mfma_i32_16x16x64_i8 v[60:63], v[216:219], v[228:231], v[60:63]
	s_add_u32 m0, s16, 0x2000
	v_lshl_add_u64 v[204:205], v[192:193], 0, s[6:7]
	global_load_lds_dwordx4 v[204:205], off
	v_mfma_i32_16x16x64_i8 v[40:43], v[220:223], v[228:231], v[40:43]
	v_mfma_i32_16x16x64_i8 v[36:39], v[232:235], v[228:231], v[36:39]
	s_add_u32 m0, s16, 0x3000
	v_lshl_add_u64 v[206:207], v[194:195], 0, s[6:7]
	global_load_lds_dwordx4 v[206:207], off
	v_mfma_i32_16x16x64_i8 v[28:31], v[236:239], v[228:231], v[28:31]
	v_mfma_i32_16x16x64_i8 v[32:35], v[216:219], v[240:243], v[32:35]
	s_add_u32 m0, s16, 0x4000
	v_lshl_add_u64 v[204:205], v[196:197], 0, s[6:7]
	global_load_lds_dwordx4 v[204:205], off
	v_mfma_i32_16x16x64_i8 v[24:27], v[220:223], v[240:243], v[24:27]
	v_mfma_i32_16x16x64_i8 v[20:23], v[232:235], v[240:243], v[20:23]
	s_add_u32 m0, s16, 0x5000
	v_lshl_add_u64 v[206:207], v[198:199], 0, s[6:7]
	global_load_lds_dwordx4 v[206:207], off
	v_mfma_i32_16x16x64_i8 v[16:19], v[236:239], v[240:243], v[16:19]
	v_mfma_i32_16x16x64_i8 v[12:15], v[216:219], v[244:247], v[12:15]
	s_add_u32 m0, s16, 0x6000
	v_lshl_add_u64 v[204:205], v[200:201], 0, s[6:7]
	global_load_lds_dwordx4 v[204:205], off
	v_mfma_i32_16x16x64_i8 v[8:11], v[220:223], v[244:247], v[8:11]
	v_mfma_i32_16x16x64_i8 v[4:7], v[232:235], v[244:247], v[4:7]
	s_add_u32 m0, s16, 0x7000
	v_lshl_add_u64 v[206:207], v[202:203], 0, s[6:7]
	global_load_lds_dwordx4 v[206:207], off
	v_mfma_i32_16x16x64_i8 v[0:3], v[236:239], v[244:247], v[0:3]
	s_setprio 0
	ds_read_b128 v[152:155], v111 offset:49152
	ds_read_b128 v[156:159], v111 offset:51200
	ds_read_b128 v[160:163], v109 offset:32768
	ds_read_b128 v[164:167], v109 offset:34816
	ds_read_b128 v[168:171], v111 offset:53248
	ds_read_b128 v[172:175], v112 offset:49152
	ds_read_b128 v[208:211], v109 offset:36864
	ds_read_b128 v[212:215], v110 offset:32768
	ds_read_b128 v[216:219], v115 offset:49152
	ds_read_b128 v[220:223], v115 offset:51200
	ds_read_b128 v[224:227], v113 offset:32768
	ds_read_b128 v[228:231], v113 offset:34816
	ds_read_b128 v[232:235], v115 offset:53248
	ds_read_b128 v[236:239], v116 offset:49152
	ds_read_b128 v[240:243], v113 offset:36864
	ds_read_b128 v[244:247], v114 offset:32768
	s_setprio 1
	s_waitcnt lgkmcnt(13)
	v_mfma_i32_16x16x64_i8 v[92:95], v[152:155], v[160:163], v[92:95]
	v_mfma_i32_16x16x64_i8 v[88:91], v[156:159], v[160:163], v[88:91]
	s_waitcnt lgkmcnt(11)
	v_mfma_i32_16x16x64_i8 v[84:87], v[168:171], v[160:163], v[84:87]
	s_waitcnt lgkmcnt(10)
	v_mfma_i32_16x16x64_i8 v[80:83], v[172:175], v[160:163], v[80:83]
	v_mfma_i32_16x16x64_i8 v[60:63], v[152:155], v[164:167], v[60:63]
	v_mfma_i32_16x16x64_i8 v[40:43], v[156:159], v[164:167], v[40:43]
	v_mfma_i32_16x16x64_i8 v[36:39], v[168:171], v[164:167], v[36:39]
	v_mfma_i32_16x16x64_i8 v[28:31], v[172:175], v[164:167], v[28:31]
	s_waitcnt lgkmcnt(9)
	v_mfma_i32_16x16x64_i8 v[32:35], v[152:155], v[208:211], v[32:35]
	v_mfma_i32_16x16x64_i8 v[24:27], v[156:159], v[208:211], v[24:27]
	v_mfma_i32_16x16x64_i8 v[20:23], v[168:171], v[208:211], v[20:23]
	v_mfma_i32_16x16x64_i8 v[16:19], v[172:175], v[208:211], v[16:19]
	s_waitcnt lgkmcnt(8)
	v_mfma_i32_16x16x64_i8 v[12:15], v[152:155], v[212:215], v[12:15]
	v_mfma_i32_16x16x64_i8 v[8:11], v[156:159], v[212:215], v[8:11]
	v_mfma_i32_16x16x64_i8 v[4:7], v[168:171], v[212:215], v[4:7]
	v_mfma_i32_16x16x64_i8 v[0:3], v[172:175], v[212:215], v[0:3]
	s_setprio 0
	s_waitcnt lgkmcnt(0)
	s_waitcnt vmcnt(0)
	s_barrier
	s_add_i32 s6, s15, 0xc0
	s_min_u32 s6, s6, 0x1c0
	s_lshl_b32 s6, s6, 1
	s_setprio 1
	v_mfma_i32_16x16x64_i8 v[92:95], v[216:219], v[224:227], v[92:95]
	s_add_u32 m0, s16, 0x8000
	v_lshl_add_u64 v[204:205], v[188:189], 0, s[6:7]
	global_load_lds_dwordx4 v[204:205], off
	v_mfma_i32_16x16x64_i8 v[88:91], v[220:223], v[224:227], v[88:91]
	v_mfma_i32_16x16x64_i8 v[84:87], v[232:235], v[224:227], v[84:87]
	s_add_u32 m0, s16, 0x9000
	v_lshl_add_u64 v[206:207], v[190:191], 0, s[6:7]
	global_load_lds_dwordx4 v[206:207], off
	v_mfma_i32_16x16x64_i8 v[80:83], v[236:239], v[224:227], v[80:83]
	v_mfma_i32_16x16x64_i8 v[60:63], v[216:219], v[228:231], v[60:63]
	s_add_u32 m0, s16, 0xa000
	v_lshl_add_u64 v[204:205], v[192:193], 0, s[6:7]
	global_load_lds_dwordx4 v[204:205], off
	v_mfma_i32_16x16x64_i8 v[40:43], v[220:223], v[228:231], v[40:43]
	v_mfma_i32_16x16x64_i8 v[36:39], v[232:235], v[228:231], v[36:39]
	s_add_u32 m0, s16, 0xb000
	v_lshl_add_u64 v[206:207], v[194:195], 0, s[6:7]
	global_load_lds_dwordx4 v[206:207], off
	v_mfma_i32_16x16x64_i8 v[28:31], v[236:239], v[228:231], v[28:31]
	v_mfma_i32_16x16x64_i8 v[32:35], v[216:219], v[240:243], v[32:35]
	s_add_u32 m0, s16, 0xc000
	v_lshl_add_u64 v[204:205], v[196:197], 0, s[6:7]
	global_load_lds_dwordx4 v[204:205], off
	v_mfma_i32_16x16x64_i8 v[24:27], v[220:223], v[240:243], v[24:27]
	v_mfma_i32_16x16x64_i8 v[20:23], v[232:235], v[240:243], v[20:23]
	s_add_u32 m0, s16, 0xd000
	v_lshl_add_u64 v[206:207], v[198:199], 0, s[6:7]
	global_load_lds_dwordx4 v[206:207], off
	v_mfma_i32_16x16x64_i8 v[16:19], v[236:239], v[240:243], v[16:19]
	v_mfma_i32_16x16x64_i8 v[12:15], v[216:219], v[244:247], v[12:15]
	s_add_u32 m0, s16, 0xe000
	v_lshl_add_u64 v[204:205], v[200:201], 0, s[6:7]
	global_load_lds_dwordx4 v[204:205], off
	v_mfma_i32_16x16x64_i8 v[8:11], v[220:223], v[244:247], v[8:11]
	v_mfma_i32_16x16x64_i8 v[4:7], v[232:235], v[244:247], v[4:7]
	s_add_u32 m0, s16, 0xf000
	v_lshl_add_u64 v[206:207], v[202:203], 0, s[6:7]
	global_load_lds_dwordx4 v[206:207], off
	v_mfma_i32_16x16x64_i8 v[0:3], v[236:239], v[244:247], v[0:3]
	s_setprio 0
	s_add_i32 s15, s15, 0x80
	s_add_i32 s14, s14, 2
	s_cmp_lt_u32 s14, 6
	s_cbranch_scc1 .Lglds2_28042
	ds_read_b128 v[152:155], v111 offset:16384
	ds_read_b128 v[156:159], v111 offset:18432
	ds_read_b128 v[160:163], v109
	ds_read_b128 v[164:167], v109 offset:2048
	ds_read_b128 v[168:171], v111 offset:20480
	ds_read_b128 v[172:175], v112 offset:16384
	ds_read_b128 v[208:211], v109 offset:4096
	ds_read_b128 v[212:215], v110
	ds_read_b128 v[216:219], v115 offset:16384
	ds_read_b128 v[220:223], v115 offset:18432
	ds_read_b128 v[224:227], v113
	ds_read_b128 v[228:231], v113 offset:2048
	ds_read_b128 v[232:235], v115 offset:20480
	ds_read_b128 v[236:239], v116 offset:16384
	ds_read_b128 v[240:243], v113 offset:4096
	ds_read_b128 v[244:247], v114
	s_setprio 1
	s_waitcnt lgkmcnt(13)
	v_mfma_i32_16x16x64_i8 v[92:95], v[152:155], v[160:163], v[92:95]
	v_mfma_i32_16x16x64_i8 v[88:91], v[156:159], v[160:163], v[88:91]
	s_waitcnt lgkmcnt(11)
	v_mfma_i32_16x16x64_i8 v[84:87], v[168:171], v[160:163], v[84:87]
	s_waitcnt lgkmcnt(10)
	v_mfma_i32_16x16x64_i8 v[80:83], v[172:175], v[160:163], v[80:83]
	v_mfma_i32_16x16x64_i8 v[60:63], v[152:155], v[164:167], v[60:63]
	v_mfma_i32_16x16x64_i8 v[40:43], v[156:159], v[164:167], v[40:43]
	v_mfma_i32_16x16x64_i8 v[36:39], v[168:171], v[164:167], v[36:39]
	v_mfma_i32_16x16x64_i8 v[28:31], v[172:175], v[164:167], v[28:31]
	s_waitcnt lgkmcnt(9)
	v_mfma_i32_16x16x64_i8 v[32:35], v[152:155], v[208:211], v[32:35]
	v_mfma_i32_16x16x64_i8 v[24:27], v[156:159], v[208:211], v[24:27]
	v_mfma_i32_16x16x64_i8 v[20:23], v[168:171], v[208:211], v[20:23]
	v_mfma_i32_16x16x64_i8 v[16:19], v[172:175], v[208:211], v[16:19]
	s_waitcnt lgkmcnt(8)
	v_mfma_i32_16x16x64_i8 v[12:15], v[152:155], v[212:215], v[12:15]
	v_mfma_i32_16x16x64_i8 v[8:11], v[156:159], v[212:215], v[8:11]
	v_mfma_i32_16x16x64_i8 v[4:7], v[168:171], v[212:215], v[4:7]
	v_mfma_i32_16x16x64_i8 v[0:3], v[172:175], v[212:215], v[0:3]
	s_setprio 0
	s_waitcnt lgkmcnt(0)
	s_waitcnt vmcnt(0)
	s_barrier
	s_setprio 1
	v_mfma_i32_16x16x64_i8 v[92:95], v[216:219], v[224:227], v[92:95]
	v_mfma_i32_16x16x64_i8 v[88:91], v[220:223], v[224:227], v[88:91]
	v_mfma_i32_16x16x64_i8 v[84:87], v[232:235], v[224:227], v[84:87]
	v_mfma_i32_16x16x64_i8 v[80:83], v[236:239], v[224:227], v[80:83]
	v_mfma_i32_16x16x64_i8 v[60:63], v[216:219], v[228:231], v[60:63]
	v_mfma_i32_16x16x64_i8 v[40:43], v[220:223], v[228:231], v[40:43]
	v_mfma_i32_16x16x64_i8 v[36:39], v[232:235], v[228:231], v[36:39]
	v_mfma_i32_16x16x64_i8 v[28:31], v[236:239], v[228:231], v[28:31]
	v_mfma_i32_16x16x64_i8 v[32:35], v[216:219], v[240:243], v[32:35]
	v_mfma_i32_16x16x64_i8 v[24:27], v[220:223], v[240:243], v[24:27]
	v_mfma_i32_16x16x64_i8 v[20:23], v[232:235], v[240:243], v[20:23]
	v_mfma_i32_16x16x64_i8 v[16:19], v[236:239], v[240:243], v[16:19]
	v_mfma_i32_16x16x64_i8 v[12:15], v[216:219], v[244:247], v[12:15]
	v_mfma_i32_16x16x64_i8 v[8:11], v[220:223], v[244:247], v[8:11]
	v_mfma_i32_16x16x64_i8 v[4:7], v[232:235], v[244:247], v[4:7]
	v_mfma_i32_16x16x64_i8 v[0:3], v[236:239], v[244:247], v[0:3]
	s_setprio 0
	ds_read_b128 v[152:155], v111 offset:49152
	ds_read_b128 v[156:159], v111 offset:51200
	ds_read_b128 v[160:163], v109 offset:32768
	ds_read_b128 v[164:167], v109 offset:34816
	ds_read_b128 v[168:171], v111 offset:53248
	ds_read_b128 v[172:175], v112 offset:49152
	ds_read_b128 v[208:211], v109 offset:36864
	ds_read_b128 v[212:215], v110 offset:32768
	ds_read_b128 v[216:219], v115 offset:49152
	ds_read_b128 v[220:223], v115 offset:51200
	ds_read_b128 v[224:227], v113 offset:32768
	ds_read_b128 v[228:231], v113 offset:34816
	ds_read_b128 v[232:235], v115 offset:53248
	ds_read_b128 v[236:239], v116 offset:49152
	ds_read_b128 v[240:243], v113 offset:36864
	ds_read_b128 v[244:247], v114 offset:32768
	s_setprio 1
	s_waitcnt lgkmcnt(13)
	v_mfma_i32_16x16x64_i8 v[92:95], v[152:155], v[160:163], v[92:95]
	v_mfma_i32_16x16x64_i8 v[88:91], v[156:159], v[160:163], v[88:91]
	s_waitcnt lgkmcnt(11)
	v_mfma_i32_16x16x64_i8 v[84:87], v[168:171], v[160:163], v[84:87]
	s_waitcnt lgkmcnt(10)
	v_mfma_i32_16x16x64_i8 v[80:83], v[172:175], v[160:163], v[80:83]
	v_mfma_i32_16x16x64_i8 v[60:63], v[152:155], v[164:167], v[60:63]
	v_mfma_i32_16x16x64_i8 v[40:43], v[156:159], v[164:167], v[40:43]
	v_mfma_i32_16x16x64_i8 v[36:39], v[168:171], v[164:167], v[36:39]
	v_mfma_i32_16x16x64_i8 v[28:31], v[172:175], v[164:167], v[28:31]
	s_waitcnt lgkmcnt(9)
	v_mfma_i32_16x16x64_i8 v[32:35], v[152:155], v[208:211], v[32:35]
	v_mfma_i32_16x16x64_i8 v[24:27], v[156:159], v[208:211], v[24:27]
	v_mfma_i32_16x16x64_i8 v[20:23], v[168:171], v[208:211], v[20:23]
	v_mfma_i32_16x16x64_i8 v[16:19], v[172:175], v[208:211], v[16:19]
	s_waitcnt lgkmcnt(8)
	v_mfma_i32_16x16x64_i8 v[12:15], v[152:155], v[212:215], v[12:15]
	v_mfma_i32_16x16x64_i8 v[8:11], v[156:159], v[212:215], v[8:11]
	v_mfma_i32_16x16x64_i8 v[4:7], v[168:171], v[212:215], v[4:7]
	v_mfma_i32_16x16x64_i8 v[0:3], v[172:175], v[212:215], v[0:3]
	s_setprio 0
	s_waitcnt lgkmcnt(0)
	s_barrier
	s_setprio 1
	v_mfma_i32_16x16x64_i8 v[92:95], v[216:219], v[224:227], v[92:95]
	v_mfma_i32_16x16x64_i8 v[88:91], v[220:223], v[224:227], v[88:91]
	v_mfma_i32_16x16x64_i8 v[84:87], v[232:235], v[224:227], v[84:87]
	v_mfma_i32_16x16x64_i8 v[80:83], v[236:239], v[224:227], v[80:83]
	v_mfma_i32_16x16x64_i8 v[60:63], v[216:219], v[228:231], v[60:63]
	v_mfma_i32_16x16x64_i8 v[40:43], v[220:223], v[228:231], v[40:43]
	v_mfma_i32_16x16x64_i8 v[36:39], v[232:235], v[228:231], v[36:39]
	v_mfma_i32_16x16x64_i8 v[28:31], v[236:239], v[228:231], v[28:31]
	v_mfma_i32_16x16x64_i8 v[32:35], v[216:219], v[240:243], v[32:35]
	v_mfma_i32_16x16x64_i8 v[24:27], v[220:223], v[240:243], v[24:27]
	v_mfma_i32_16x16x64_i8 v[20:23], v[232:235], v[240:243], v[20:23]
	v_mfma_i32_16x16x64_i8 v[16:19], v[236:239], v[240:243], v[16:19]
	v_mfma_i32_16x16x64_i8 v[12:15], v[216:219], v[244:247], v[12:15]
	v_mfma_i32_16x16x64_i8 v[8:11], v[220:223], v[244:247], v[8:11]
	v_mfma_i32_16x16x64_i8 v[4:7], v[232:235], v[244:247], v[4:7]
	v_mfma_i32_16x16x64_i8 v[0:3], v[236:239], v[244:247], v[0:3]
	s_setprio 0
	s_waitcnt vmcnt(0)
	v_cvt_f32_i32_e32 v92, v92
	v_cvt_f32_i32_e32 v93, v93
	v_cvt_f32_i32_e32 v94, v94
	v_cvt_f32_i32_e32 v95, v95
	v_cvt_f32_i32_e32 v88, v88
	v_cvt_f32_i32_e32 v89, v89
	v_cvt_f32_i32_e32 v90, v90
	v_cvt_f32_i32_e32 v91, v91
	v_cvt_f32_i32_e32 v84, v84
	v_cvt_f32_i32_e32 v85, v85
	v_cvt_f32_i32_e32 v86, v86
	v_cvt_f32_i32_e32 v87, v87
	v_cvt_f32_i32_e32 v80, v80
	v_cvt_f32_i32_e32 v81, v81
	v_cvt_f32_i32_e32 v82, v82
	v_cvt_f32_i32_e32 v83, v83
	v_cvt_f32_i32_e32 v60, v60
	v_cvt_f32_i32_e32 v61, v61
	v_cvt_f32_i32_e32 v62, v62
	v_cvt_f32_i32_e32 v63, v63
	v_cvt_f32_i32_e32 v40, v40
	v_cvt_f32_i32_e32 v41, v41
	v_cvt_f32_i32_e32 v42, v42
	v_cvt_f32_i32_e32 v43, v43
	v_cvt_f32_i32_e32 v36, v36
	v_cvt_f32_i32_e32 v37, v37
	v_cvt_f32_i32_e32 v38, v38
	v_cvt_f32_i32_e32 v39, v39
	v_cvt_f32_i32_e32 v28, v28
	v_cvt_f32_i32_e32 v29, v29
	v_cvt_f32_i32_e32 v30, v30
	v_cvt_f32_i32_e32 v31, v31
	v_cvt_f32_i32_e32 v32, v32
	v_cvt_f32_i32_e32 v33, v33
	v_cvt_f32_i32_e32 v34, v34
	v_cvt_f32_i32_e32 v35, v35
	v_cvt_f32_i32_e32 v24, v24
	v_cvt_f32_i32_e32 v25, v25
	v_cvt_f32_i32_e32 v26, v26
	v_cvt_f32_i32_e32 v27, v27
	v_cvt_f32_i32_e32 v20, v20
	v_cvt_f32_i32_e32 v21, v21
	v_cvt_f32_i32_e32 v22, v22
	v_cvt_f32_i32_e32 v23, v23
	v_cvt_f32_i32_e32 v16, v16
	v_cvt_f32_i32_e32 v17, v17
	v_cvt_f32_i32_e32 v18, v18
	v_cvt_f32_i32_e32 v19, v19
	v_cvt_f32_i32_e32 v12, v12
	v_cvt_f32_i32_e32 v13, v13
	v_cvt_f32_i32_e32 v14, v14
	v_cvt_f32_i32_e32 v15, v15
	v_cvt_f32_i32_e32 v8, v8
	v_cvt_f32_i32_e32 v9, v9
	v_cvt_f32_i32_e32 v10, v10
	v_cvt_f32_i32_e32 v11, v11
	v_cvt_f32_i32_e32 v4, v4
	v_cvt_f32_i32_e32 v5, v5
	v_cvt_f32_i32_e32 v6, v6
	v_cvt_f32_i32_e32 v7, v7
	v_cvt_f32_i32_e32 v0, v0
	v_cvt_f32_i32_e32 v1, v1
	v_cvt_f32_i32_e32 v2, v2
	v_cvt_f32_i32_e32 v3, v3
	s_waitcnt vmcnt(0)
	v_add_u32_e32 v96, s12, v117
	v_or_b32_e32 v146, s13, v118
	v_lshl_add_u64 v[144:145], v[96:97], 2, s[68:69]
	v_lshlrev_b32_e32 v148, 2, v146
	global_load_dword v136, v[144:145], off
	global_load_dword v138, v[144:145], off offset:64
	global_load_dword v140, v[144:145], off offset:128
	global_load_dword v142, v[144:145], off offset:192
	global_load_dwordx4 v[120:123], v148, s[0:1]
	global_load_dwordx4 v[124:127], v148, s[0:1] offset:64
	global_load_dwordx4 v[128:131], v148, s[0:1] offset:128
	global_load_dwordx4 v[132:135], v148, s[0:1] offset:192
	v_lshlrev_b32_e32 v146, 1, v146
	v_mov_b32_e32 v147, v97
	v_lshlrev_b64 v[44:45], 12, v[96:97]
	v_lshl_add_u64 v[44:45], s[64:65], 0, v[44:45]
	v_lshl_add_u64 v[44:45], v[44:45], 0, v[146:147]
	v_or_b32_e32 v52, 16, v96
	v_mov_b32_e32 v53, v97
	v_lshlrev_b64 v[46:47], 12, v[52:53]
	v_lshl_add_u64 v[46:47], s[64:65], 0, v[46:47]
	v_lshl_add_u64 v[46:47], v[46:47], 0, v[146:147]
	v_or_b32_e32 v52, 32, v96
	v_mov_b32_e32 v53, v97
	v_lshlrev_b64 v[48:49], 12, v[52:53]
	v_lshl_add_u64 v[48:49], s[64:65], 0, v[48:49]
	v_lshl_add_u64 v[48:49], v[48:49], 0, v[146:147]
	v_or_b32_e32 v52, 48, v96
	v_mov_b32_e32 v53, v97
	v_lshlrev_b64 v[50:51], 12, v[52:53]
	v_lshl_add_u64 v[50:51], s[64:65], 0, v[50:51]
	v_lshl_add_u64 v[50:51], v[50:51], 0, v[146:147]
	s_waitcnt vmcnt(0)
	v_pk_mul_f32 v[92:93], v[136:137], v[92:93] op_sel_hi:[0,1]
	v_pk_mul_f32 v[94:95], v[136:137], v[94:95] op_sel_hi:[0,1]
	v_pk_mul_f32 v[92:93], v[120:121], v[92:93]
	v_pk_mul_f32 v[94:95], v[94:95], v[122:123]
	v_cvt_pk_bf16_f32 v92, v92, v93
	v_cvt_pk_bf16_f32 v93, v94, v95
	global_store_dwordx2 v[44:45], v[92:93], off
	v_pk_mul_f32 v[88:89], v[136:137], v[88:89] op_sel_hi:[0,1]
	v_pk_mul_f32 v[90:91], v[136:137], v[90:91] op_sel_hi:[0,1]
	v_pk_mul_f32 v[88:89], v[124:125], v[88:89]
	v_pk_mul_f32 v[90:91], v[90:91], v[126:127]
	v_cvt_pk_bf16_f32 v88, v88, v89
	v_cvt_pk_bf16_f32 v89, v90, v91
	global_store_dwordx2 v[44:45], v[88:89], off offset:32
	v_pk_mul_f32 v[84:85], v[136:137], v[84:85] op_sel_hi:[0,1]
	v_pk_mul_f32 v[86:87], v[136:137], v[86:87] op_sel_hi:[0,1]
	v_pk_mul_f32 v[84:85], v[128:129], v[84:85]
	v_pk_mul_f32 v[86:87], v[86:87], v[130:131]
	v_cvt_pk_bf16_f32 v84, v84, v85
	v_cvt_pk_bf16_f32 v85, v86, v87
	global_store_dwordx2 v[44:45], v[84:85], off offset:64
	v_pk_mul_f32 v[80:81], v[136:137], v[80:81] op_sel_hi:[0,1]
	v_pk_mul_f32 v[82:83], v[136:137], v[82:83] op_sel_hi:[0,1]
	v_pk_mul_f32 v[80:81], v[132:133], v[80:81]
	v_pk_mul_f32 v[82:83], v[82:83], v[134:135]
	v_cvt_pk_bf16_f32 v80, v80, v81
	v_cvt_pk_bf16_f32 v81, v82, v83
	global_store_dwordx2 v[44:45], v[80:81], off offset:96
	v_pk_mul_f32 v[60:61], v[138:139], v[60:61] op_sel_hi:[0,1]
	v_pk_mul_f32 v[62:63], v[138:139], v[62:63] op_sel_hi:[0,1]
	v_pk_mul_f32 v[60:61], v[120:121], v[60:61]
	v_pk_mul_f32 v[62:63], v[62:63], v[122:123]
	v_cvt_pk_bf16_f32 v60, v60, v61
	v_cvt_pk_bf16_f32 v61, v62, v63
	global_store_dwordx2 v[46:47], v[60:61], off
	v_pk_mul_f32 v[40:41], v[138:139], v[40:41] op_sel_hi:[0,1]
	v_pk_mul_f32 v[42:43], v[138:139], v[42:43] op_sel_hi:[0,1]
	v_pk_mul_f32 v[40:41], v[124:125], v[40:41]
	v_pk_mul_f32 v[42:43], v[42:43], v[126:127]
	v_cvt_pk_bf16_f32 v40, v40, v41
	v_cvt_pk_bf16_f32 v41, v42, v43
	global_store_dwordx2 v[46:47], v[40:41], off offset:32
	v_pk_mul_f32 v[36:37], v[138:139], v[36:37] op_sel_hi:[0,1]
	v_pk_mul_f32 v[38:39], v[138:139], v[38:39] op_sel_hi:[0,1]
	v_pk_mul_f32 v[36:37], v[128:129], v[36:37]
	v_pk_mul_f32 v[38:39], v[38:39], v[130:131]
	v_cvt_pk_bf16_f32 v36, v36, v37
	v_cvt_pk_bf16_f32 v37, v38, v39
	global_store_dwordx2 v[46:47], v[36:37], off offset:64
	v_pk_mul_f32 v[28:29], v[138:139], v[28:29] op_sel_hi:[0,1]
	v_pk_mul_f32 v[30:31], v[138:139], v[30:31] op_sel_hi:[0,1]
	v_pk_mul_f32 v[28:29], v[132:133], v[28:29]
	v_pk_mul_f32 v[30:31], v[30:31], v[134:135]
	v_cvt_pk_bf16_f32 v28, v28, v29
	v_cvt_pk_bf16_f32 v29, v30, v31
	global_store_dwordx2 v[46:47], v[28:29], off offset:96
	v_pk_mul_f32 v[32:33], v[140:141], v[32:33] op_sel_hi:[0,1]
	v_pk_mul_f32 v[34:35], v[140:141], v[34:35] op_sel_hi:[0,1]
	v_pk_mul_f32 v[32:33], v[120:121], v[32:33]
	v_pk_mul_f32 v[34:35], v[34:35], v[122:123]
	v_cvt_pk_bf16_f32 v32, v32, v33
	v_cvt_pk_bf16_f32 v33, v34, v35
	global_store_dwordx2 v[48:49], v[32:33], off
	v_pk_mul_f32 v[24:25], v[140:141], v[24:25] op_sel_hi:[0,1]
	v_pk_mul_f32 v[26:27], v[140:141], v[26:27] op_sel_hi:[0,1]
	v_pk_mul_f32 v[24:25], v[124:125], v[24:25]
	v_pk_mul_f32 v[26:27], v[26:27], v[126:127]
	v_cvt_pk_bf16_f32 v24, v24, v25
	v_cvt_pk_bf16_f32 v25, v26, v27
	global_store_dwordx2 v[48:49], v[24:25], off offset:32
	v_pk_mul_f32 v[20:21], v[140:141], v[20:21] op_sel_hi:[0,1]
	v_pk_mul_f32 v[22:23], v[140:141], v[22:23] op_sel_hi:[0,1]
	v_pk_mul_f32 v[20:21], v[128:129], v[20:21]
	v_pk_mul_f32 v[22:23], v[22:23], v[130:131]
	v_cvt_pk_bf16_f32 v20, v20, v21
	v_cvt_pk_bf16_f32 v21, v22, v23
	global_store_dwordx2 v[48:49], v[20:21], off offset:64
	v_pk_mul_f32 v[16:17], v[140:141], v[16:17] op_sel_hi:[0,1]
	v_pk_mul_f32 v[18:19], v[140:141], v[18:19] op_sel_hi:[0,1]
	v_pk_mul_f32 v[16:17], v[132:133], v[16:17]
	v_pk_mul_f32 v[18:19], v[18:19], v[134:135]
	v_cvt_pk_bf16_f32 v16, v16, v17
	v_cvt_pk_bf16_f32 v17, v18, v19
	global_store_dwordx2 v[48:49], v[16:17], off offset:96
	v_pk_mul_f32 v[12:13], v[142:143], v[12:13] op_sel_hi:[0,1]
	v_pk_mul_f32 v[14:15], v[142:143], v[14:15] op_sel_hi:[0,1]
	v_pk_mul_f32 v[12:13], v[120:121], v[12:13]
	v_pk_mul_f32 v[14:15], v[14:15], v[122:123]
	v_cvt_pk_bf16_f32 v12, v12, v13
	v_cvt_pk_bf16_f32 v13, v14, v15
	global_store_dwordx2 v[50:51], v[12:13], off
	v_pk_mul_f32 v[8:9], v[142:143], v[8:9] op_sel_hi:[0,1]
	v_pk_mul_f32 v[10:11], v[142:143], v[10:11] op_sel_hi:[0,1]
	v_pk_mul_f32 v[8:9], v[124:125], v[8:9]
	v_pk_mul_f32 v[10:11], v[10:11], v[126:127]
	v_cvt_pk_bf16_f32 v8, v8, v9
	v_cvt_pk_bf16_f32 v9, v10, v11
	global_store_dwordx2 v[50:51], v[8:9], off offset:32
	v_pk_mul_f32 v[4:5], v[142:143], v[4:5] op_sel_hi:[0,1]
	v_pk_mul_f32 v[6:7], v[142:143], v[6:7] op_sel_hi:[0,1]
	v_pk_mul_f32 v[4:5], v[128:129], v[4:5]
	v_pk_mul_f32 v[6:7], v[6:7], v[130:131]
	v_cvt_pk_bf16_f32 v4, v4, v5
	v_cvt_pk_bf16_f32 v5, v6, v7
	global_store_dwordx2 v[50:51], v[4:5], off offset:64
	v_pk_mul_f32 v[0:1], v[142:143], v[0:1] op_sel_hi:[0,1]
	v_pk_mul_f32 v[2:3], v[142:143], v[2:3] op_sel_hi:[0,1]
	v_pk_mul_f32 v[0:1], v[132:133], v[0:1]
	v_pk_mul_f32 v[2:3], v[2:3], v[134:135]
	v_cvt_pk_bf16_f32 v0, v0, v1
	v_cvt_pk_bf16_f32 v1, v2, v3
	global_store_dwordx2 v[50:51], v[0:1], off offset:96
	s_add_i32 s8, s8, s3
	s_cmpk_lt_u32 s8, 0x200
	s_cbranch_scc1 .LBB0_889
